# LayerNorm phases: row loads issued two rows ahead (three row buffers) instead of one
# baseline (speedup 1.0000x reference)
; __device__ __forceinline__ int otid() { int t = threadIdx.x; asm volatile("" : "+v"(t)); return t; }
; __device__ __forceinline__ void phase_ln(float* R, const float* __restrict__ g, const float* __restrict__ b, bf16_t* xbf, float samp_scale, const float* __restrict__ part, int nsplit, bool f32_all) {
;   const int tid = otid(), lane = tid & 63, gw = blockIdx.x * 8 + (tid >> 6), nw = gridDim.x * 8;
;   f32x4 gv[4], bv[4];
; #pragma unroll
;   for (int i = 0; i < 4; ++i) { gv[i] = *(const f32x4*)(g + i * 256 + lane * 4); bv[i] = *(const f32x4*)(b + i * 256 + lane * 4); }
;   for (int r = gw; r < MT; r += nw) {
;     float* row = R + (size_t)r * 1024;
;     f32x4 v[4];
; #pragma unroll
;     for (int i = 0; i < 4; ++i) v[i] = *(const f32x4*)(row + i * 256 + lane * 4);
;     if (r >= MP) {
;       for (int sp = 0; sp < nsplit; ++sp) {
;         const float* prow = part + ((size_t)sp * MS + (r - MP)) * 1024;
; #pragma unroll
;         for (int i = 0; i < 4; ++i) v[i] = v[i] + *(const f32x4*)(prow + i * 256 + lane * 4);
;       }
;     }
;     float s = 0.f;
; #pragma unroll
;     for (int i = 0; i < 4; ++i) s += v[i][0] + v[i][1] + v[i][2] + v[i][3];
; #pragma unroll
;     for (int o = 32; o >= 1; o >>= 1) s += __shfl_xor(s, o);
;     const float mean = s * (1.f / 1024.f);
;     float ss = 0.f;
; #pragma unroll
;     for (int i = 0; i < 4; ++i) { v[i] = v[i] - mean; ss += v[i][0] * v[i][0] + v[i][1] * v[i][1] + v[i][2] * v[i][2] + v[i][3] * v[i][3]; }
; #pragma unroll
;     for (int o = 32; o >= 1; o >>= 1) ss += __shfl_xor(ss, o);
;     const float rstd = rsqrtf(ss * (1.f / 1024.f) + LN_EPS);
; #pragma unroll
;     for (int i = 0; i < 4; ++i) {
;       const f32x4 y = v[i] * rstd * gv[i] + bv[i];
;       if (r >= MP) *(f32x4*)(row + i * 256 + lane * 4) = y * samp_scale;
;       else if (f32_all) *(f32x4*)(row + i * 256 + lane * 4) = y;
;       if (xbf) {
;         u32x2 wv;
;         wv[0] = cvt_pk_bf16(y[0], y[1]); wv[1] = cvt_pk_bf16(y[2], y[3]);
;         *(u32x2*)(xbf + (size_t)r * 1024 + i * 256 + lane * 4) = wv;
;       }
;     }
;   }
.LBB0_3720:
	s_or_b64 exec, exec, s[0:1]
	v_readlane_b32 s0, v254, 51
	s_nop 0
	s_cmp_lg_u32 s0, 0
	s_cbranch_scc1 .Lln1_orig
	v_readlane_b32 s6, v254, 2
	v_readlane_b32 s7, v254, 3
	v_readlane_b32 s8, v255, 22
	s_waitcnt lgkmcnt(0)
	s_barrier
	s_load_dwordx4 s[0:3], s[6:7], 0x78
	s_load_dwordx4 s[4:7], s[6:7], 0xa8
	v_readlane_b32 s9, v254, 15
	v_readfirstlane_b32 s10, v244
	v_lshlrev_b32_e32 v114, 4, v252
	v_lshlrev_b32_e32 v115, 3, v252
	s_lshr_b32 s10, s10, 6
	s_add_i32 s9, s9, s10
	s_lshl_b32 s11, s8, 12
	s_waitcnt lgkmcnt(0)
	s_add_u32 s0, s0, s11
	s_addc_u32 s1, s1, 0
	s_add_u32 s2, s2, s11
	s_addc_u32 s3, s3, 0
	global_load_dwordx4 v[34:37], v114, s[0:1] offset:0 nt
	global_load_dwordx4 v[38:41], v114, s[0:1] offset:1024 nt
	global_load_dwordx4 v[42:45], v114, s[0:1] offset:2048 nt
	global_load_dwordx4 v[46:49], v114, s[0:1] offset:3072 nt
	global_load_dwordx4 v[50:53], v114, s[2:3] offset:0
	global_load_dwordx4 v[54:57], v114, s[2:3] offset:1024
	global_load_dwordx4 v[58:61], v114, s[2:3] offset:2048
	global_load_dwordx4 v[62:65], v114, s[2:3] offset:3072
	s_lshl_b32 s11, s9, 12
	s_add_u32 s0, s4, s11
	s_addc_u32 s1, s5, 0
	s_lshl_b32 s11, s9, 11
	s_add_u32 s11, s11, 0x39c0000
	s_add_u32 s2, s6, s11
	s_addc_u32 s3, s7, 0
	global_load_dwordx4 v[0:3], v114, s[0:1] offset:0 nt
	global_load_dwordx4 v[4:7], v114, s[0:1] offset:1024 nt
	global_load_dwordx4 v[8:11], v114, s[0:1] offset:2048 nt
	global_load_dwordx4 v[12:15], v114, s[0:1] offset:3072 nt
	s_add_u32 s0, s0, 0x800000
	s_addc_u32 s1, s1, 0
	global_load_dwordx4 v[18:21], v114, s[0:1] offset:0 nt
	global_load_dwordx4 v[22:25], v114, s[0:1] offset:1024 nt
	global_load_dwordx4 v[26:29], v114, s[0:1] offset:2048 nt
	global_load_dwordx4 v[30:33], v114, s[0:1] offset:3072 nt
	s_add_u32 s0, s0, 0x800000
	s_addc_u32 s1, s1, 0
	global_load_dwordx4 v[122:125], v114, s[0:1] offset:0 nt
	global_load_dwordx4 v[126:129], v114, s[0:1] offset:1024 nt
	global_load_dwordx4 v[130:133], v114, s[0:1] offset:2048 nt
	global_load_dwordx4 v[134:137], v114, s[0:1] offset:3072 nt
	s_waitcnt vmcnt(8)
	v_pk_add_f32 v[66:67], v[0:1], v[2:3]
	v_pk_add_f32 v[68:69], v[4:5], v[6:7]
	v_pk_add_f32 v[70:71], v[8:9], v[10:11]
	v_pk_add_f32 v[72:73], v[12:13], v[14:15]
	v_pk_add_f32 v[66:67], v[66:67], v[68:69]
	v_pk_add_f32 v[70:71], v[70:71], v[72:73]
	v_pk_add_f32 v[66:67], v[66:67], v[70:71]
	v_add_f32_e32 v66, v66, v67
	s_nop 1
	v_add_f32_dpp v66, v66, v66 row_shr:1 row_mask:0xf bank_mask:0xf bound_ctrl:1
	s_nop 1
	v_add_f32_dpp v66, v66, v66 row_shr:2 row_mask:0xf bank_mask:0xf bound_ctrl:1
	s_nop 1
	v_add_f32_dpp v66, v66, v66 row_shr:4 row_mask:0xf bank_mask:0xf bound_ctrl:1
	s_nop 1
	v_add_f32_dpp v66, v66, v66 row_shr:8 row_mask:0xf bank_mask:0xf bound_ctrl:1
	s_nop 0
	v_readlane_b32 s9, v66, 15
	v_readlane_b32 s10, v66, 31
	v_readlane_b32 s11, v66, 47
	v_readlane_b32 vcc_lo, v66, 63
	s_nop 1
	v_mov_b32_e32 v66, s9
	v_add_f32_e32 v66, s10, v66
	v_add_f32_e32 v66, s11, v66
	v_add_f32_e32 v66, vcc_lo, v66
	v_mul_f32_e32 v116, 0x3a800000, v66
	v_mov_b32_e32 v117, v116
	v_pk_add_f32 v[0:1], v[0:1], v[116:117] neg_lo:[0,1] neg_hi:[0,1]
	v_pk_add_f32 v[2:3], v[2:3], v[116:117] neg_lo:[0,1] neg_hi:[0,1]
	v_pk_add_f32 v[4:5], v[4:5], v[116:117] neg_lo:[0,1] neg_hi:[0,1]
	v_pk_add_f32 v[6:7], v[6:7], v[116:117] neg_lo:[0,1] neg_hi:[0,1]
	v_pk_add_f32 v[8:9], v[8:9], v[116:117] neg_lo:[0,1] neg_hi:[0,1]
	v_pk_add_f32 v[10:11], v[10:11], v[116:117] neg_lo:[0,1] neg_hi:[0,1]
	v_pk_add_f32 v[12:13], v[12:13], v[116:117] neg_lo:[0,1] neg_hi:[0,1]
	v_pk_add_f32 v[14:15], v[14:15], v[116:117] neg_lo:[0,1] neg_hi:[0,1]
	v_pk_mul_f32 v[66:67], v[0:1], v[0:1]
	v_pk_mul_f32 v[68:69], v[2:3], v[2:3]
	v_pk_fma_f32 v[66:67], v[4:5], v[4:5], v[66:67]
	v_pk_fma_f32 v[68:69], v[6:7], v[6:7], v[68:69]
	v_pk_fma_f32 v[66:67], v[8:9], v[8:9], v[66:67]
	v_pk_fma_f32 v[68:69], v[10:11], v[10:11], v[68:69]
	v_pk_fma_f32 v[66:67], v[12:13], v[12:13], v[66:67]
	v_pk_fma_f32 v[68:69], v[14:15], v[14:15], v[68:69]
	v_pk_add_f32 v[66:67], v[66:67], v[68:69]
	v_add_f32_e32 v66, v66, v67
	s_nop 1
	v_add_f32_dpp v66, v66, v66 row_shr:1 row_mask:0xf bank_mask:0xf bound_ctrl:1
	s_nop 1
	v_add_f32_dpp v66, v66, v66 row_shr:2 row_mask:0xf bank_mask:0xf bound_ctrl:1
	s_nop 1
	v_add_f32_dpp v66, v66, v66 row_shr:4 row_mask:0xf bank_mask:0xf bound_ctrl:1
	s_nop 1
	v_add_f32_dpp v66, v66, v66 row_shr:8 row_mask:0xf bank_mask:0xf bound_ctrl:1
	s_nop 0
	v_readlane_b32 s9, v66, 15
	v_readlane_b32 s10, v66, 31
	v_readlane_b32 s11, v66, 47
	v_readlane_b32 vcc_lo, v66, 63
	s_nop 1
	v_mov_b32_e32 v66, s9
	v_add_f32_e32 v66, s10, v66
	v_add_f32_e32 v66, s11, v66
	v_add_f32_e32 v66, vcc_lo, v66
	v_mul_f32_e32 v66, 0x3a800000, v66
	v_add_f32_e32 v66, 0x3727c5ac, v66
	v_rsq_f32_e32 v118, v66
	s_nop 0
	v_mov_b32_e32 v119, v118
	v_pk_mul_f32 v[0:1], v[0:1], v[118:119]
	v_pk_mul_f32 v[2:3], v[2:3], v[118:119]
	v_pk_mul_f32 v[4:5], v[4:5], v[118:119]
	v_pk_mul_f32 v[6:7], v[6:7], v[118:119]
	v_pk_mul_f32 v[8:9], v[8:9], v[118:119]
	v_pk_mul_f32 v[10:11], v[10:11], v[118:119]
	v_pk_mul_f32 v[12:13], v[12:13], v[118:119]
	v_pk_mul_f32 v[14:15], v[14:15], v[118:119]
	v_pk_fma_f32 v[76:77], v[0:1], v[34:35], v[50:51]
	v_pk_fma_f32 v[78:79], v[2:3], v[36:37], v[52:53]
	v_pk_fma_f32 v[80:81], v[4:5], v[38:39], v[54:55]
	v_pk_fma_f32 v[82:83], v[6:7], v[40:41], v[56:57]
	v_pk_fma_f32 v[84:85], v[8:9], v[42:43], v[58:59]
	v_pk_fma_f32 v[86:87], v[10:11], v[44:45], v[60:61]
	v_pk_fma_f32 v[88:89], v[12:13], v[46:47], v[62:63]
	v_pk_fma_f32 v[90:91], v[14:15], v[48:49], v[64:65]
	v_cvt_pk_bf16_f32 v92, v76, v77
	v_cvt_pk_bf16_f32 v93, v78, v79
	v_cvt_pk_bf16_f32 v94, v80, v81
	v_cvt_pk_bf16_f32 v95, v82, v83
	v_cvt_pk_bf16_f32 v96, v84, v85
	v_cvt_pk_bf16_f32 v97, v86, v87
	v_cvt_pk_bf16_f32 v98, v88, v89
	v_cvt_pk_bf16_f32 v99, v90, v91
	global_store_dwordx2 v115, v[92:93], s[2:3] offset:0 sc1
	global_store_dwordx2 v115, v[94:95], s[2:3] offset:512 sc1
	global_store_dwordx2 v115, v[96:97], s[2:3] offset:1024 sc1
	global_store_dwordx2 v115, v[98:99], s[2:3] offset:1536 sc1
	s_add_u32 s2, s2, 0x400000
	s_addc_u32 s3, s3, 0
	s_add_u32 s0, s0, 0x800000
	s_addc_u32 s1, s1, 0
	global_load_dwordx4 v[0:3], v114, s[0:1] offset:0 nt
	global_load_dwordx4 v[4:7], v114, s[0:1] offset:1024 nt
	global_load_dwordx4 v[8:11], v114, s[0:1] offset:2048 nt
	global_load_dwordx4 v[12:15], v114, s[0:1] offset:3072 nt
	s_waitcnt vmcnt(12)
; __device__ __forceinline__ void phase_ln(float* R, const float* __restrict__ g, const float* __restrict__ b, bf16_t* xbf, float samp_scale, const float* __restrict__ part, int nsplit, bool f32_all) {
;     ...
;   for (int r = gw; r < MT; r += nw) {
;     float* row = R + (size_t)r * 1024;
;     f32x4 v[4];
; #pragma unroll
;     for (int i = 0; i < 4; ++i) v[i] = *(const f32x4*)(row + i * 256 + lane * 4);
;     if (r >= MP) {
;       for (int sp = 0; sp < nsplit; ++sp) {
;         const float* prow = part + ((size_t)sp * MS + (r - MP)) * 1024;
; #pragma unroll
;         for (int i = 0; i < 4; ++i) v[i] = v[i] + *(const f32x4*)(prow + i * 256 + lane * 4);
;       }
;     }
;     float s = 0.f;
; #pragma unroll
;     for (int i = 0; i < 4; ++i) s += v[i][0] + v[i][1] + v[i][2] + v[i][3];
; #pragma unroll
;     for (int o = 32; o >= 1; o >>= 1) s += __shfl_xor(s, o);
;     const float mean = s * (1.f / 1024.f);
;     float ss = 0.f;
; #pragma unroll
;     for (int i = 0; i < 4; ++i) { v[i] = v[i] - mean; ss += v[i][0] * v[i][0] + v[i][1] * v[i][1] + v[i][2] * v[i][2] + v[i][3] * v[i][3]; }
; #pragma unroll
;     for (int o = 32; o >= 1; o >>= 1) ss += __shfl_xor(ss, o);
;     const float rstd = rsqrtf(ss * (1.f / 1024.f) + LN_EPS);
; #pragma unroll
;     for (int i = 0; i < 4; ++i) {
;       const f32x4 y = v[i] * rstd * gv[i] + bv[i];
;       if (r >= MP) *(f32x4*)(row + i * 256 + lane * 4) = y * samp_scale;
;       else if (f32_all) *(f32x4*)(row + i * 256 + lane * 4) = y;
;       if (xbf) {
;         u32x2 wv;
;         wv[0] = cvt_pk_bf16(y[0], y[1]); wv[1] = cvt_pk_bf16(y[2], y[3]);
;         *(u32x2*)(xbf + (size_t)r * 1024 + i * 256 + lane * 4) = wv;
;       }
;     }
	v_pk_add_f32 v[66:67], v[18:19], v[20:21]
	v_pk_add_f32 v[68:69], v[22:23], v[24:25]
	v_pk_add_f32 v[70:71], v[26:27], v[28:29]
	v_pk_add_f32 v[72:73], v[30:31], v[32:33]
	v_pk_add_f32 v[66:67], v[66:67], v[68:69]
	v_pk_add_f32 v[70:71], v[70:71], v[72:73]
	v_pk_add_f32 v[66:67], v[66:67], v[70:71]
	v_add_f32_e32 v66, v66, v67
	s_nop 1
	v_add_f32_dpp v66, v66, v66 row_shr:1 row_mask:0xf bank_mask:0xf bound_ctrl:1
	s_nop 1
	v_add_f32_dpp v66, v66, v66 row_shr:2 row_mask:0xf bank_mask:0xf bound_ctrl:1
	s_nop 1
	v_add_f32_dpp v66, v66, v66 row_shr:4 row_mask:0xf bank_mask:0xf bound_ctrl:1
	s_nop 1
	v_add_f32_dpp v66, v66, v66 row_shr:8 row_mask:0xf bank_mask:0xf bound_ctrl:1
	s_nop 0
	v_readlane_b32 s9, v66, 15
	v_readlane_b32 s10, v66, 31
	v_readlane_b32 s11, v66, 47
	v_readlane_b32 vcc_lo, v66, 63
	s_nop 1
	v_mov_b32_e32 v66, s9
	v_add_f32_e32 v66, s10, v66
	v_add_f32_e32 v66, s11, v66
	v_add_f32_e32 v66, vcc_lo, v66
	v_mul_f32_e32 v116, 0x3a800000, v66
	v_mov_b32_e32 v117, v116
	v_pk_add_f32 v[18:19], v[18:19], v[116:117] neg_lo:[0,1] neg_hi:[0,1]
	v_pk_add_f32 v[20:21], v[20:21], v[116:117] neg_lo:[0,1] neg_hi:[0,1]
	v_pk_add_f32 v[22:23], v[22:23], v[116:117] neg_lo:[0,1] neg_hi:[0,1]
	v_pk_add_f32 v[24:25], v[24:25], v[116:117] neg_lo:[0,1] neg_hi:[0,1]
	v_pk_add_f32 v[26:27], v[26:27], v[116:117] neg_lo:[0,1] neg_hi:[0,1]
	v_pk_add_f32 v[28:29], v[28:29], v[116:117] neg_lo:[0,1] neg_hi:[0,1]
	v_pk_add_f32 v[30:31], v[30:31], v[116:117] neg_lo:[0,1] neg_hi:[0,1]
	v_pk_add_f32 v[32:33], v[32:33], v[116:117] neg_lo:[0,1] neg_hi:[0,1]
	v_pk_mul_f32 v[66:67], v[18:19], v[18:19]
	v_pk_mul_f32 v[68:69], v[20:21], v[20:21]
	v_pk_fma_f32 v[66:67], v[22:23], v[22:23], v[66:67]
	v_pk_fma_f32 v[68:69], v[24:25], v[24:25], v[68:69]
	v_pk_fma_f32 v[66:67], v[26:27], v[26:27], v[66:67]
	v_pk_fma_f32 v[68:69], v[28:29], v[28:29], v[68:69]
	v_pk_fma_f32 v[66:67], v[30:31], v[30:31], v[66:67]
	v_pk_fma_f32 v[68:69], v[32:33], v[32:33], v[68:69]
	v_pk_add_f32 v[66:67], v[66:67], v[68:69]
	v_add_f32_e32 v66, v66, v67
	s_nop 1
	v_add_f32_dpp v66, v66, v66 row_shr:1 row_mask:0xf bank_mask:0xf bound_ctrl:1
	s_nop 1
	v_add_f32_dpp v66, v66, v66 row_shr:2 row_mask:0xf bank_mask:0xf bound_ctrl:1
	s_nop 1
	v_add_f32_dpp v66, v66, v66 row_shr:4 row_mask:0xf bank_mask:0xf bound_ctrl:1
	s_nop 1
	v_add_f32_dpp v66, v66, v66 row_shr:8 row_mask:0xf bank_mask:0xf bound_ctrl:1
	s_nop 0
	v_readlane_b32 s9, v66, 15
	v_readlane_b32 s10, v66, 31
	v_readlane_b32 s11, v66, 47
	v_readlane_b32 vcc_lo, v66, 63
	s_nop 1
	v_mov_b32_e32 v66, s9
	v_add_f32_e32 v66, s10, v66
	v_add_f32_e32 v66, s11, v66
	v_add_f32_e32 v66, vcc_lo, v66
	v_mul_f32_e32 v66, 0x3a800000, v66
	v_add_f32_e32 v66, 0x3727c5ac, v66
	v_rsq_f32_e32 v118, v66
	s_nop 0
	v_mov_b32_e32 v119, v118
	v_pk_mul_f32 v[18:19], v[18:19], v[118:119]
	v_pk_mul_f32 v[20:21], v[20:21], v[118:119]
	v_pk_mul_f32 v[22:23], v[22:23], v[118:119]
	v_pk_mul_f32 v[24:25], v[24:25], v[118:119]
	v_pk_mul_f32 v[26:27], v[26:27], v[118:119]
	v_pk_mul_f32 v[28:29], v[28:29], v[118:119]
	v_pk_mul_f32 v[30:31], v[30:31], v[118:119]
	v_pk_mul_f32 v[32:33], v[32:33], v[118:119]
	v_pk_fma_f32 v[76:77], v[18:19], v[34:35], v[50:51]
	v_pk_fma_f32 v[78:79], v[20:21], v[36:37], v[52:53]
	v_pk_fma_f32 v[80:81], v[22:23], v[38:39], v[54:55]
	v_pk_fma_f32 v[82:83], v[24:25], v[40:41], v[56:57]
	v_pk_fma_f32 v[84:85], v[26:27], v[42:43], v[58:59]
	v_pk_fma_f32 v[86:87], v[28:29], v[44:45], v[60:61]
	v_pk_fma_f32 v[88:89], v[30:31], v[46:47], v[62:63]
	v_pk_fma_f32 v[90:91], v[32:33], v[48:49], v[64:65]
	v_cvt_pk_bf16_f32 v92, v76, v77
	v_cvt_pk_bf16_f32 v93, v78, v79
	v_cvt_pk_bf16_f32 v94, v80, v81
	v_cvt_pk_bf16_f32 v95, v82, v83
	v_cvt_pk_bf16_f32 v96, v84, v85
	v_cvt_pk_bf16_f32 v97, v86, v87
	v_cvt_pk_bf16_f32 v98, v88, v89
	v_cvt_pk_bf16_f32 v99, v90, v91
	global_store_dwordx2 v115, v[92:93], s[2:3] offset:0 sc1
	global_store_dwordx2 v115, v[94:95], s[2:3] offset:512 sc1
	global_store_dwordx2 v115, v[96:97], s[2:3] offset:1024 sc1
	global_store_dwordx2 v115, v[98:99], s[2:3] offset:1536 sc1
	s_add_u32 s2, s2, 0x400000
	s_addc_u32 s3, s3, 0
	s_add_u32 s0, s0, 0x800000
	s_addc_u32 s1, s1, 0
	global_load_dwordx4 v[18:21], v114, s[0:1] offset:0 nt
	global_load_dwordx4 v[22:25], v114, s[0:1] offset:1024 nt
	global_load_dwordx4 v[26:29], v114, s[0:1] offset:2048 nt
	global_load_dwordx4 v[30:33], v114, s[0:1] offset:3072 nt
	s_waitcnt vmcnt(16)
; __device__ __forceinline__ void phase_ln(float* R, const float* __restrict__ g, const float* __restrict__ b, bf16_t* xbf, float samp_scale, const float* __restrict__ part, int nsplit, bool f32_all) {
;     ...
;   for (int r = gw; r < MT; r += nw) {
;     float* row = R + (size_t)r * 1024;
;     f32x4 v[4];
; #pragma unroll
;     for (int i = 0; i < 4; ++i) v[i] = *(const f32x4*)(row + i * 256 + lane * 4);
;     if (r >= MP) {
;       for (int sp = 0; sp < nsplit; ++sp) {
;         const float* prow = part + ((size_t)sp * MS + (r - MP)) * 1024;
; #pragma unroll
;         for (int i = 0; i < 4; ++i) v[i] = v[i] + *(const f32x4*)(prow + i * 256 + lane * 4);
;       }
;     }
;     float s = 0.f;
; #pragma unroll
;     for (int i = 0; i < 4; ++i) s += v[i][0] + v[i][1] + v[i][2] + v[i][3];
; #pragma unroll
;     for (int o = 32; o >= 1; o >>= 1) s += __shfl_xor(s, o);
;     const float mean = s * (1.f / 1024.f);
;     float ss = 0.f;
; #pragma unroll
;     for (int i = 0; i < 4; ++i) { v[i] = v[i] - mean; ss += v[i][0] * v[i][0] + v[i][1] * v[i][1] + v[i][2] * v[i][2] + v[i][3] * v[i][3]; }
; #pragma unroll
;     for (int o = 32; o >= 1; o >>= 1) ss += __shfl_xor(ss, o);
;     const float rstd = rsqrtf(ss * (1.f / 1024.f) + LN_EPS);
; #pragma unroll
;     for (int i = 0; i < 4; ++i) {
;       const f32x4 y = v[i] * rstd * gv[i] + bv[i];
;       if (r >= MP) *(f32x4*)(row + i * 256 + lane * 4) = y * samp_scale;
;       else if (f32_all) *(f32x4*)(row + i * 256 + lane * 4) = y;
;       if (xbf) {
;         u32x2 wv;
;         wv[0] = cvt_pk_bf16(y[0], y[1]); wv[1] = cvt_pk_bf16(y[2], y[3]);
;         *(u32x2*)(xbf + (size_t)r * 1024 + i * 256 + lane * 4) = wv;
;       }
;     }
	v_pk_add_f32 v[66:67], v[122:123], v[124:125]
	v_pk_add_f32 v[68:69], v[126:127], v[128:129]
	v_pk_add_f32 v[70:71], v[130:131], v[132:133]
	v_pk_add_f32 v[72:73], v[134:135], v[136:137]
	v_pk_add_f32 v[66:67], v[66:67], v[68:69]
	v_pk_add_f32 v[70:71], v[70:71], v[72:73]
	v_pk_add_f32 v[66:67], v[66:67], v[70:71]
	v_add_f32_e32 v66, v66, v67
	s_nop 1
	v_add_f32_dpp v66, v66, v66 row_shr:1 row_mask:0xf bank_mask:0xf bound_ctrl:1
	s_nop 1
	v_add_f32_dpp v66, v66, v66 row_shr:2 row_mask:0xf bank_mask:0xf bound_ctrl:1
	s_nop 1
	v_add_f32_dpp v66, v66, v66 row_shr:4 row_mask:0xf bank_mask:0xf bound_ctrl:1
	s_nop 1
	v_add_f32_dpp v66, v66, v66 row_shr:8 row_mask:0xf bank_mask:0xf bound_ctrl:1
	s_nop 0
	v_readlane_b32 s9, v66, 15
	v_readlane_b32 s10, v66, 31
	v_readlane_b32 s11, v66, 47
	v_readlane_b32 vcc_lo, v66, 63
	s_nop 1
	v_mov_b32_e32 v66, s9
	v_add_f32_e32 v66, s10, v66
	v_add_f32_e32 v66, s11, v66
	v_add_f32_e32 v66, vcc_lo, v66
	v_mul_f32_e32 v116, 0x3a800000, v66
	v_mov_b32_e32 v117, v116
	v_pk_add_f32 v[122:123], v[122:123], v[116:117] neg_lo:[0,1] neg_hi:[0,1]
	v_pk_add_f32 v[124:125], v[124:125], v[116:117] neg_lo:[0,1] neg_hi:[0,1]
	v_pk_add_f32 v[126:127], v[126:127], v[116:117] neg_lo:[0,1] neg_hi:[0,1]
	v_pk_add_f32 v[128:129], v[128:129], v[116:117] neg_lo:[0,1] neg_hi:[0,1]
	v_pk_add_f32 v[130:131], v[130:131], v[116:117] neg_lo:[0,1] neg_hi:[0,1]
	v_pk_add_f32 v[132:133], v[132:133], v[116:117] neg_lo:[0,1] neg_hi:[0,1]
	v_pk_add_f32 v[134:135], v[134:135], v[116:117] neg_lo:[0,1] neg_hi:[0,1]
	v_pk_add_f32 v[136:137], v[136:137], v[116:117] neg_lo:[0,1] neg_hi:[0,1]
	v_pk_mul_f32 v[66:67], v[122:123], v[122:123]
	v_pk_mul_f32 v[68:69], v[124:125], v[124:125]
	v_pk_fma_f32 v[66:67], v[126:127], v[126:127], v[66:67]
	v_pk_fma_f32 v[68:69], v[128:129], v[128:129], v[68:69]
	v_pk_fma_f32 v[66:67], v[130:131], v[130:131], v[66:67]
	v_pk_fma_f32 v[68:69], v[132:133], v[132:133], v[68:69]
	v_pk_fma_f32 v[66:67], v[134:135], v[134:135], v[66:67]
	v_pk_fma_f32 v[68:69], v[136:137], v[136:137], v[68:69]
	v_pk_add_f32 v[66:67], v[66:67], v[68:69]
	v_add_f32_e32 v66, v66, v67
	s_nop 1
	v_add_f32_dpp v66, v66, v66 row_shr:1 row_mask:0xf bank_mask:0xf bound_ctrl:1
	s_nop 1
	v_add_f32_dpp v66, v66, v66 row_shr:2 row_mask:0xf bank_mask:0xf bound_ctrl:1
	s_nop 1
	v_add_f32_dpp v66, v66, v66 row_shr:4 row_mask:0xf bank_mask:0xf bound_ctrl:1
	s_nop 1
	v_add_f32_dpp v66, v66, v66 row_shr:8 row_mask:0xf bank_mask:0xf bound_ctrl:1
	s_nop 0
	v_readlane_b32 s9, v66, 15
	v_readlane_b32 s10, v66, 31
	v_readlane_b32 s11, v66, 47
	v_readlane_b32 vcc_lo, v66, 63
	s_nop 1
	v_mov_b32_e32 v66, s9
	v_add_f32_e32 v66, s10, v66
	v_add_f32_e32 v66, s11, v66
	v_add_f32_e32 v66, vcc_lo, v66
	v_mul_f32_e32 v66, 0x3a800000, v66
	v_add_f32_e32 v66, 0x3727c5ac, v66
	v_rsq_f32_e32 v118, v66
	s_nop 0
	v_mov_b32_e32 v119, v118
	v_pk_mul_f32 v[122:123], v[122:123], v[118:119]
	v_pk_mul_f32 v[124:125], v[124:125], v[118:119]
	v_pk_mul_f32 v[126:127], v[126:127], v[118:119]
	v_pk_mul_f32 v[128:129], v[128:129], v[118:119]
	v_pk_mul_f32 v[130:131], v[130:131], v[118:119]
	v_pk_mul_f32 v[132:133], v[132:133], v[118:119]
	v_pk_mul_f32 v[134:135], v[134:135], v[118:119]
	v_pk_mul_f32 v[136:137], v[136:137], v[118:119]
	v_pk_fma_f32 v[76:77], v[122:123], v[34:35], v[50:51]
	v_pk_fma_f32 v[78:79], v[124:125], v[36:37], v[52:53]
	v_pk_fma_f32 v[80:81], v[126:127], v[38:39], v[54:55]
	v_pk_fma_f32 v[82:83], v[128:129], v[40:41], v[56:57]
	v_pk_fma_f32 v[84:85], v[130:131], v[42:43], v[58:59]
	v_pk_fma_f32 v[86:87], v[132:133], v[44:45], v[60:61]
	v_pk_fma_f32 v[88:89], v[134:135], v[46:47], v[62:63]
	v_pk_fma_f32 v[90:91], v[136:137], v[48:49], v[64:65]
	v_cvt_pk_bf16_f32 v92, v76, v77
	v_cvt_pk_bf16_f32 v93, v78, v79
	v_cvt_pk_bf16_f32 v94, v80, v81
	v_cvt_pk_bf16_f32 v95, v82, v83
	v_cvt_pk_bf16_f32 v96, v84, v85
	v_cvt_pk_bf16_f32 v97, v86, v87
	v_cvt_pk_bf16_f32 v98, v88, v89
	v_cvt_pk_bf16_f32 v99, v90, v91
	global_store_dwordx2 v115, v[92:93], s[2:3] offset:0 sc1
	global_store_dwordx2 v115, v[94:95], s[2:3] offset:512 sc1
	global_store_dwordx2 v115, v[96:97], s[2:3] offset:1024 sc1
	global_store_dwordx2 v115, v[98:99], s[2:3] offset:1536 sc1
	s_add_u32 s2, s2, 0x400000
	s_addc_u32 s3, s3, 0
	s_add_u32 s0, s0, 0x800000
	s_addc_u32 s1, s1, 0
	global_load_dwordx4 v[122:125], v114, s[0:1] offset:0 nt
	global_load_dwordx4 v[126:129], v114, s[0:1] offset:1024 nt
	global_load_dwordx4 v[130:133], v114, s[0:1] offset:2048 nt
	global_load_dwordx4 v[134:137], v114, s[0:1] offset:3072 nt
	s_waitcnt vmcnt(16)
; __device__ __forceinline__ void phase_ln(float* R, const float* __restrict__ g, const float* __restrict__ b, bf16_t* xbf, float samp_scale, const float* __restrict__ part, int nsplit, bool f32_all) {
;     ...
;   for (int r = gw; r < MT; r += nw) {
;     float* row = R + (size_t)r * 1024;
;     f32x4 v[4];
; #pragma unroll
;     for (int i = 0; i < 4; ++i) v[i] = *(const f32x4*)(row + i * 256 + lane * 4);
;     if (r >= MP) {
;       for (int sp = 0; sp < nsplit; ++sp) {
;         const float* prow = part + ((size_t)sp * MS + (r - MP)) * 1024;
; #pragma unroll
;         for (int i = 0; i < 4; ++i) v[i] = v[i] + *(const f32x4*)(prow + i * 256 + lane * 4);
;       }
;     }
;     float s = 0.f;
; #pragma unroll
;     for (int i = 0; i < 4; ++i) s += v[i][0] + v[i][1] + v[i][2] + v[i][3];
; #pragma unroll
;     for (int o = 32; o >= 1; o >>= 1) s += __shfl_xor(s, o);
;     const float mean = s * (1.f / 1024.f);
;     float ss = 0.f;
; #pragma unroll
;     for (int i = 0; i < 4; ++i) { v[i] = v[i] - mean; ss += v[i][0] * v[i][0] + v[i][1] * v[i][1] + v[i][2] * v[i][2] + v[i][3] * v[i][3]; }
; #pragma unroll
;     for (int o = 32; o >= 1; o >>= 1) ss += __shfl_xor(ss, o);
;     const float rstd = rsqrtf(ss * (1.f / 1024.f) + LN_EPS);
; #pragma unroll
;     for (int i = 0; i < 4; ++i) {
;       const f32x4 y = v[i] * rstd * gv[i] + bv[i];
;       if (r >= MP) *(f32x4*)(row + i * 256 + lane * 4) = y * samp_scale;
;       else if (f32_all) *(f32x4*)(row + i * 256 + lane * 4) = y;
;       if (xbf) {
;         u32x2 wv;
;         wv[0] = cvt_pk_bf16(y[0], y[1]); wv[1] = cvt_pk_bf16(y[2], y[3]);
;         *(u32x2*)(xbf + (size_t)r * 1024 + i * 256 + lane * 4) = wv;
;       }
;     }
	v_pk_add_f32 v[66:67], v[0:1], v[2:3]
	v_pk_add_f32 v[68:69], v[4:5], v[6:7]
	v_pk_add_f32 v[70:71], v[8:9], v[10:11]
	v_pk_add_f32 v[72:73], v[12:13], v[14:15]
	v_pk_add_f32 v[66:67], v[66:67], v[68:69]
	v_pk_add_f32 v[70:71], v[70:71], v[72:73]
	v_pk_add_f32 v[66:67], v[66:67], v[70:71]
	v_add_f32_e32 v66, v66, v67
	s_nop 1
	v_add_f32_dpp v66, v66, v66 row_shr:1 row_mask:0xf bank_mask:0xf bound_ctrl:1
	s_nop 1
	v_add_f32_dpp v66, v66, v66 row_shr:2 row_mask:0xf bank_mask:0xf bound_ctrl:1
	s_nop 1
	v_add_f32_dpp v66, v66, v66 row_shr:4 row_mask:0xf bank_mask:0xf bound_ctrl:1
	s_nop 1
	v_add_f32_dpp v66, v66, v66 row_shr:8 row_mask:0xf bank_mask:0xf bound_ctrl:1
	s_nop 0
	v_readlane_b32 s9, v66, 15
	v_readlane_b32 s10, v66, 31
	v_readlane_b32 s11, v66, 47
	v_readlane_b32 vcc_lo, v66, 63
	s_nop 1
	v_mov_b32_e32 v66, s9
	v_add_f32_e32 v66, s10, v66
	v_add_f32_e32 v66, s11, v66
	v_add_f32_e32 v66, vcc_lo, v66
	v_mul_f32_e32 v116, 0x3a800000, v66
	v_mov_b32_e32 v117, v116
	v_pk_add_f32 v[0:1], v[0:1], v[116:117] neg_lo:[0,1] neg_hi:[0,1]
	v_pk_add_f32 v[2:3], v[2:3], v[116:117] neg_lo:[0,1] neg_hi:[0,1]
	v_pk_add_f32 v[4:5], v[4:5], v[116:117] neg_lo:[0,1] neg_hi:[0,1]
	v_pk_add_f32 v[6:7], v[6:7], v[116:117] neg_lo:[0,1] neg_hi:[0,1]
	v_pk_add_f32 v[8:9], v[8:9], v[116:117] neg_lo:[0,1] neg_hi:[0,1]
	v_pk_add_f32 v[10:11], v[10:11], v[116:117] neg_lo:[0,1] neg_hi:[0,1]
	v_pk_add_f32 v[12:13], v[12:13], v[116:117] neg_lo:[0,1] neg_hi:[0,1]
	v_pk_add_f32 v[14:15], v[14:15], v[116:117] neg_lo:[0,1] neg_hi:[0,1]
	v_pk_mul_f32 v[66:67], v[0:1], v[0:1]
	v_pk_mul_f32 v[68:69], v[2:3], v[2:3]
	v_pk_fma_f32 v[66:67], v[4:5], v[4:5], v[66:67]
	v_pk_fma_f32 v[68:69], v[6:7], v[6:7], v[68:69]
	v_pk_fma_f32 v[66:67], v[8:9], v[8:9], v[66:67]
	v_pk_fma_f32 v[68:69], v[10:11], v[10:11], v[68:69]
	v_pk_fma_f32 v[66:67], v[12:13], v[12:13], v[66:67]
	v_pk_fma_f32 v[68:69], v[14:15], v[14:15], v[68:69]
	v_pk_add_f32 v[66:67], v[66:67], v[68:69]
	v_add_f32_e32 v66, v66, v67
	s_nop 1
	v_add_f32_dpp v66, v66, v66 row_shr:1 row_mask:0xf bank_mask:0xf bound_ctrl:1
	s_nop 1
	v_add_f32_dpp v66, v66, v66 row_shr:2 row_mask:0xf bank_mask:0xf bound_ctrl:1
	s_nop 1
	v_add_f32_dpp v66, v66, v66 row_shr:4 row_mask:0xf bank_mask:0xf bound_ctrl:1
	s_nop 1
	v_add_f32_dpp v66, v66, v66 row_shr:8 row_mask:0xf bank_mask:0xf bound_ctrl:1
	s_nop 0
	v_readlane_b32 s9, v66, 15
	v_readlane_b32 s10, v66, 31
	v_readlane_b32 s11, v66, 47
	v_readlane_b32 vcc_lo, v66, 63
	s_nop 1
	v_mov_b32_e32 v66, s9
	v_add_f32_e32 v66, s10, v66
	v_add_f32_e32 v66, s11, v66
	v_add_f32_e32 v66, vcc_lo, v66
	v_mul_f32_e32 v66, 0x3a800000, v66
	v_add_f32_e32 v66, 0x3727c5ac, v66
	v_rsq_f32_e32 v118, v66
	s_nop 0
	v_mov_b32_e32 v119, v118
	v_pk_mul_f32 v[0:1], v[0:1], v[118:119]
	v_pk_mul_f32 v[2:3], v[2:3], v[118:119]
	v_pk_mul_f32 v[4:5], v[4:5], v[118:119]
	v_pk_mul_f32 v[6:7], v[6:7], v[118:119]
	v_pk_mul_f32 v[8:9], v[8:9], v[118:119]
	v_pk_mul_f32 v[10:11], v[10:11], v[118:119]
	v_pk_mul_f32 v[12:13], v[12:13], v[118:119]
	v_pk_mul_f32 v[14:15], v[14:15], v[118:119]
	v_pk_fma_f32 v[76:77], v[0:1], v[34:35], v[50:51]
	v_pk_fma_f32 v[78:79], v[2:3], v[36:37], v[52:53]
	v_pk_fma_f32 v[80:81], v[4:5], v[38:39], v[54:55]
	v_pk_fma_f32 v[82:83], v[6:7], v[40:41], v[56:57]
	v_pk_fma_f32 v[84:85], v[8:9], v[42:43], v[58:59]
	v_pk_fma_f32 v[86:87], v[10:11], v[44:45], v[60:61]
	v_pk_fma_f32 v[88:89], v[12:13], v[46:47], v[62:63]
	v_pk_fma_f32 v[90:91], v[14:15], v[48:49], v[64:65]
	v_cvt_pk_bf16_f32 v92, v76, v77
	v_cvt_pk_bf16_f32 v93, v78, v79
	v_cvt_pk_bf16_f32 v94, v80, v81
	v_cvt_pk_bf16_f32 v95, v82, v83
	v_cvt_pk_bf16_f32 v96, v84, v85
	v_cvt_pk_bf16_f32 v97, v86, v87
	v_cvt_pk_bf16_f32 v98, v88, v89
	v_cvt_pk_bf16_f32 v99, v90, v91
	global_store_dwordx2 v115, v[92:93], s[2:3] offset:0 sc1
	global_store_dwordx2 v115, v[94:95], s[2:3] offset:512 sc1
	global_store_dwordx2 v115, v[96:97], s[2:3] offset:1024 sc1
	global_store_dwordx2 v115, v[98:99], s[2:3] offset:1536 sc1
	s_add_u32 s2, s2, 0x400000
	s_addc_u32 s3, s3, 0
	s_add_u32 s0, s0, 0x800000
	s_addc_u32 s1, s1, 0
	global_load_dwordx4 v[0:3], v114, s[0:1] offset:0 nt
	global_load_dwordx4 v[4:7], v114, s[0:1] offset:1024 nt
	global_load_dwordx4 v[8:11], v114, s[0:1] offset:2048 nt
	global_load_dwordx4 v[12:15], v114, s[0:1] offset:3072 nt
	s_waitcnt vmcnt(16)
; __device__ __forceinline__ void phase_ln(float* R, const float* __restrict__ g, const float* __restrict__ b, bf16_t* xbf, float samp_scale, const float* __restrict__ part, int nsplit, bool f32_all) {
;     ...
;   for (int r = gw; r < MT; r += nw) {
;     float* row = R + (size_t)r * 1024;
;     f32x4 v[4];
; #pragma unroll
;     for (int i = 0; i < 4; ++i) v[i] = *(const f32x4*)(row + i * 256 + lane * 4);
;     if (r >= MP) {
;       for (int sp = 0; sp < nsplit; ++sp) {
;         const float* prow = part + ((size_t)sp * MS + (r - MP)) * 1024;
; #pragma unroll
;         for (int i = 0; i < 4; ++i) v[i] = v[i] + *(const f32x4*)(prow + i * 256 + lane * 4);
;       }
;     }
;     float s = 0.f;
; #pragma unroll
;     for (int i = 0; i < 4; ++i) s += v[i][0] + v[i][1] + v[i][2] + v[i][3];
; #pragma unroll
;     for (int o = 32; o >= 1; o >>= 1) s += __shfl_xor(s, o);
;     const float mean = s * (1.f / 1024.f);
;     float ss = 0.f;
; #pragma unroll
;     for (int i = 0; i < 4; ++i) { v[i] = v[i] - mean; ss += v[i][0] * v[i][0] + v[i][1] * v[i][1] + v[i][2] * v[i][2] + v[i][3] * v[i][3]; }
; #pragma unroll
;     for (int o = 32; o >= 1; o >>= 1) ss += __shfl_xor(ss, o);
;     const float rstd = rsqrtf(ss * (1.f / 1024.f) + LN_EPS);
; #pragma unroll
;     for (int i = 0; i < 4; ++i) {
;       const f32x4 y = v[i] * rstd * gv[i] + bv[i];
;       if (r >= MP) *(f32x4*)(row + i * 256 + lane * 4) = y * samp_scale;
;       else if (f32_all) *(f32x4*)(row + i * 256 + lane * 4) = y;
;       if (xbf) {
;         u32x2 wv;
;         wv[0] = cvt_pk_bf16(y[0], y[1]); wv[1] = cvt_pk_bf16(y[2], y[3]);
;         *(u32x2*)(xbf + (size_t)r * 1024 + i * 256 + lane * 4) = wv;
;       }
;     }
	v_pk_add_f32 v[66:67], v[18:19], v[20:21]
	v_pk_add_f32 v[68:69], v[22:23], v[24:25]
	v_pk_add_f32 v[70:71], v[26:27], v[28:29]
	v_pk_add_f32 v[72:73], v[30:31], v[32:33]
	v_pk_add_f32 v[66:67], v[66:67], v[68:69]
	v_pk_add_f32 v[70:71], v[70:71], v[72:73]
	v_pk_add_f32 v[66:67], v[66:67], v[70:71]
	v_add_f32_e32 v66, v66, v67
	s_nop 1
	v_add_f32_dpp v66, v66, v66 row_shr:1 row_mask:0xf bank_mask:0xf bound_ctrl:1
	s_nop 1
	v_add_f32_dpp v66, v66, v66 row_shr:2 row_mask:0xf bank_mask:0xf bound_ctrl:1
	s_nop 1
	v_add_f32_dpp v66, v66, v66 row_shr:4 row_mask:0xf bank_mask:0xf bound_ctrl:1
	s_nop 1
	v_add_f32_dpp v66, v66, v66 row_shr:8 row_mask:0xf bank_mask:0xf bound_ctrl:1
	s_nop 0
	v_readlane_b32 s9, v66, 15
	v_readlane_b32 s10, v66, 31
	v_readlane_b32 s11, v66, 47
	v_readlane_b32 vcc_lo, v66, 63
	s_nop 1
	v_mov_b32_e32 v66, s9
	v_add_f32_e32 v66, s10, v66
	v_add_f32_e32 v66, s11, v66
	v_add_f32_e32 v66, vcc_lo, v66
	v_mul_f32_e32 v116, 0x3a800000, v66
	v_mov_b32_e32 v117, v116
	v_pk_add_f32 v[18:19], v[18:19], v[116:117] neg_lo:[0,1] neg_hi:[0,1]
	v_pk_add_f32 v[20:21], v[20:21], v[116:117] neg_lo:[0,1] neg_hi:[0,1]
	v_pk_add_f32 v[22:23], v[22:23], v[116:117] neg_lo:[0,1] neg_hi:[0,1]
	v_pk_add_f32 v[24:25], v[24:25], v[116:117] neg_lo:[0,1] neg_hi:[0,1]
	v_pk_add_f32 v[26:27], v[26:27], v[116:117] neg_lo:[0,1] neg_hi:[0,1]
	v_pk_add_f32 v[28:29], v[28:29], v[116:117] neg_lo:[0,1] neg_hi:[0,1]
	v_pk_add_f32 v[30:31], v[30:31], v[116:117] neg_lo:[0,1] neg_hi:[0,1]
	v_pk_add_f32 v[32:33], v[32:33], v[116:117] neg_lo:[0,1] neg_hi:[0,1]
	v_pk_mul_f32 v[66:67], v[18:19], v[18:19]
	v_pk_mul_f32 v[68:69], v[20:21], v[20:21]
	v_pk_fma_f32 v[66:67], v[22:23], v[22:23], v[66:67]
	v_pk_fma_f32 v[68:69], v[24:25], v[24:25], v[68:69]
	v_pk_fma_f32 v[66:67], v[26:27], v[26:27], v[66:67]
	v_pk_fma_f32 v[68:69], v[28:29], v[28:29], v[68:69]
	v_pk_fma_f32 v[66:67], v[30:31], v[30:31], v[66:67]
	v_pk_fma_f32 v[68:69], v[32:33], v[32:33], v[68:69]
	v_pk_add_f32 v[66:67], v[66:67], v[68:69]
	v_add_f32_e32 v66, v66, v67
	s_nop 1
	v_add_f32_dpp v66, v66, v66 row_shr:1 row_mask:0xf bank_mask:0xf bound_ctrl:1
	s_nop 1
	v_add_f32_dpp v66, v66, v66 row_shr:2 row_mask:0xf bank_mask:0xf bound_ctrl:1
	s_nop 1
	v_add_f32_dpp v66, v66, v66 row_shr:4 row_mask:0xf bank_mask:0xf bound_ctrl:1
	s_nop 1
	v_add_f32_dpp v66, v66, v66 row_shr:8 row_mask:0xf bank_mask:0xf bound_ctrl:1
	s_nop 0
	v_readlane_b32 s9, v66, 15
	v_readlane_b32 s10, v66, 31
	v_readlane_b32 s11, v66, 47
	v_readlane_b32 vcc_lo, v66, 63
	s_nop 1
	v_mov_b32_e32 v66, s9
	v_add_f32_e32 v66, s10, v66
	v_add_f32_e32 v66, s11, v66
	v_add_f32_e32 v66, vcc_lo, v66
	v_mul_f32_e32 v66, 0x3a800000, v66
	v_add_f32_e32 v66, 0x3727c5ac, v66
	v_rsq_f32_e32 v118, v66
	s_nop 0
	v_mov_b32_e32 v119, v118
	v_pk_mul_f32 v[18:19], v[18:19], v[118:119]
	v_pk_mul_f32 v[20:21], v[20:21], v[118:119]
	v_pk_mul_f32 v[22:23], v[22:23], v[118:119]
	v_pk_mul_f32 v[24:25], v[24:25], v[118:119]
	v_pk_mul_f32 v[26:27], v[26:27], v[118:119]
	v_pk_mul_f32 v[28:29], v[28:29], v[118:119]
	v_pk_mul_f32 v[30:31], v[30:31], v[118:119]
	v_pk_mul_f32 v[32:33], v[32:33], v[118:119]
	v_pk_fma_f32 v[76:77], v[18:19], v[34:35], v[50:51]
	v_pk_fma_f32 v[78:79], v[20:21], v[36:37], v[52:53]
	v_pk_fma_f32 v[80:81], v[22:23], v[38:39], v[54:55]
	v_pk_fma_f32 v[82:83], v[24:25], v[40:41], v[56:57]
	v_pk_fma_f32 v[84:85], v[26:27], v[42:43], v[58:59]
	v_pk_fma_f32 v[86:87], v[28:29], v[44:45], v[60:61]
	v_pk_fma_f32 v[88:89], v[30:31], v[46:47], v[62:63]
	v_pk_fma_f32 v[90:91], v[32:33], v[48:49], v[64:65]
	v_cvt_pk_bf16_f32 v92, v76, v77
	v_cvt_pk_bf16_f32 v93, v78, v79
	v_cvt_pk_bf16_f32 v94, v80, v81
	v_cvt_pk_bf16_f32 v95, v82, v83
	v_cvt_pk_bf16_f32 v96, v84, v85
	v_cvt_pk_bf16_f32 v97, v86, v87
	v_cvt_pk_bf16_f32 v98, v88, v89
	v_cvt_pk_bf16_f32 v99, v90, v91
	global_store_dwordx2 v115, v[92:93], s[2:3] offset:0 sc1
	global_store_dwordx2 v115, v[94:95], s[2:3] offset:512 sc1
	global_store_dwordx2 v115, v[96:97], s[2:3] offset:1024 sc1
	global_store_dwordx2 v115, v[98:99], s[2:3] offset:1536 sc1
	s_add_u32 s2, s2, 0x400000
	s_addc_u32 s3, s3, 0
	s_add_u32 s0, s0, 0x800000
	s_addc_u32 s1, s1, 0
	global_load_dwordx4 v[18:21], v114, s[0:1] offset:0 nt
	global_load_dwordx4 v[22:25], v114, s[0:1] offset:1024 nt
	global_load_dwordx4 v[26:29], v114, s[0:1] offset:2048 nt
	global_load_dwordx4 v[30:33], v114, s[0:1] offset:3072 nt
	s_waitcnt vmcnt(16)
; __device__ __forceinline__ void phase_ln(float* R, const float* __restrict__ g, const float* __restrict__ b, bf16_t* xbf, float samp_scale, const float* __restrict__ part, int nsplit, bool f32_all) {
;     ...
;   for (int r = gw; r < MT; r += nw) {
;     float* row = R + (size_t)r * 1024;
;     f32x4 v[4];
; #pragma unroll
;     for (int i = 0; i < 4; ++i) v[i] = *(const f32x4*)(row + i * 256 + lane * 4);
;     if (r >= MP) {
;       for (int sp = 0; sp < nsplit; ++sp) {
;         const float* prow = part + ((size_t)sp * MS + (r - MP)) * 1024;
; #pragma unroll
;         for (int i = 0; i < 4; ++i) v[i] = v[i] + *(const f32x4*)(prow + i * 256 + lane * 4);
;       }
;     }
;     float s = 0.f;
; #pragma unroll
;     for (int i = 0; i < 4; ++i) s += v[i][0] + v[i][1] + v[i][2] + v[i][3];
; #pragma unroll
;     for (int o = 32; o >= 1; o >>= 1) s += __shfl_xor(s, o);
;     const float mean = s * (1.f / 1024.f);
;     float ss = 0.f;
; #pragma unroll
;     for (int i = 0; i < 4; ++i) { v[i] = v[i] - mean; ss += v[i][0] * v[i][0] + v[i][1] * v[i][1] + v[i][2] * v[i][2] + v[i][3] * v[i][3]; }
; #pragma unroll
;     for (int o = 32; o >= 1; o >>= 1) ss += __shfl_xor(ss, o);
;     const float rstd = rsqrtf(ss * (1.f / 1024.f) + LN_EPS);
; #pragma unroll
;     for (int i = 0; i < 4; ++i) {
;       const f32x4 y = v[i] * rstd * gv[i] + bv[i];
;       if (r >= MP) *(f32x4*)(row + i * 256 + lane * 4) = y * samp_scale;
;       else if (f32_all) *(f32x4*)(row + i * 256 + lane * 4) = y;
;       if (xbf) {
;         u32x2 wv;
;         wv[0] = cvt_pk_bf16(y[0], y[1]); wv[1] = cvt_pk_bf16(y[2], y[3]);
;         *(u32x2*)(xbf + (size_t)r * 1024 + i * 256 + lane * 4) = wv;
;       }
;     }
	v_pk_add_f32 v[66:67], v[122:123], v[124:125]
	v_pk_add_f32 v[68:69], v[126:127], v[128:129]
	v_pk_add_f32 v[70:71], v[130:131], v[132:133]
	v_pk_add_f32 v[72:73], v[134:135], v[136:137]
	v_pk_add_f32 v[66:67], v[66:67], v[68:69]
	v_pk_add_f32 v[70:71], v[70:71], v[72:73]
	v_pk_add_f32 v[66:67], v[66:67], v[70:71]
	v_add_f32_e32 v66, v66, v67
	s_nop 1
	v_add_f32_dpp v66, v66, v66 row_shr:1 row_mask:0xf bank_mask:0xf bound_ctrl:1
	s_nop 1
	v_add_f32_dpp v66, v66, v66 row_shr:2 row_mask:0xf bank_mask:0xf bound_ctrl:1
	s_nop 1
	v_add_f32_dpp v66, v66, v66 row_shr:4 row_mask:0xf bank_mask:0xf bound_ctrl:1
	s_nop 1
	v_add_f32_dpp v66, v66, v66 row_shr:8 row_mask:0xf bank_mask:0xf bound_ctrl:1
	s_nop 0
	v_readlane_b32 s9, v66, 15
	v_readlane_b32 s10, v66, 31
	v_readlane_b32 s11, v66, 47
	v_readlane_b32 vcc_lo, v66, 63
	s_nop 1
	v_mov_b32_e32 v66, s9
	v_add_f32_e32 v66, s10, v66
	v_add_f32_e32 v66, s11, v66
	v_add_f32_e32 v66, vcc_lo, v66
	v_mul_f32_e32 v116, 0x3a800000, v66
	v_mov_b32_e32 v117, v116
	v_pk_add_f32 v[122:123], v[122:123], v[116:117] neg_lo:[0,1] neg_hi:[0,1]
	v_pk_add_f32 v[124:125], v[124:125], v[116:117] neg_lo:[0,1] neg_hi:[0,1]
	v_pk_add_f32 v[126:127], v[126:127], v[116:117] neg_lo:[0,1] neg_hi:[0,1]
	v_pk_add_f32 v[128:129], v[128:129], v[116:117] neg_lo:[0,1] neg_hi:[0,1]
	v_pk_add_f32 v[130:131], v[130:131], v[116:117] neg_lo:[0,1] neg_hi:[0,1]
	v_pk_add_f32 v[132:133], v[132:133], v[116:117] neg_lo:[0,1] neg_hi:[0,1]
	v_pk_add_f32 v[134:135], v[134:135], v[116:117] neg_lo:[0,1] neg_hi:[0,1]
	v_pk_add_f32 v[136:137], v[136:137], v[116:117] neg_lo:[0,1] neg_hi:[0,1]
	v_pk_mul_f32 v[66:67], v[122:123], v[122:123]
	v_pk_mul_f32 v[68:69], v[124:125], v[124:125]
	v_pk_fma_f32 v[66:67], v[126:127], v[126:127], v[66:67]
	v_pk_fma_f32 v[68:69], v[128:129], v[128:129], v[68:69]
	v_pk_fma_f32 v[66:67], v[130:131], v[130:131], v[66:67]
	v_pk_fma_f32 v[68:69], v[132:133], v[132:133], v[68:69]
	v_pk_fma_f32 v[66:67], v[134:135], v[134:135], v[66:67]
	v_pk_fma_f32 v[68:69], v[136:137], v[136:137], v[68:69]
	v_pk_add_f32 v[66:67], v[66:67], v[68:69]
	v_add_f32_e32 v66, v66, v67
	s_nop 1
	v_add_f32_dpp v66, v66, v66 row_shr:1 row_mask:0xf bank_mask:0xf bound_ctrl:1
	s_nop 1
	v_add_f32_dpp v66, v66, v66 row_shr:2 row_mask:0xf bank_mask:0xf bound_ctrl:1
	s_nop 1
	v_add_f32_dpp v66, v66, v66 row_shr:4 row_mask:0xf bank_mask:0xf bound_ctrl:1
	s_nop 1
	v_add_f32_dpp v66, v66, v66 row_shr:8 row_mask:0xf bank_mask:0xf bound_ctrl:1
	s_nop 0
	v_readlane_b32 s9, v66, 15
	v_readlane_b32 s10, v66, 31
	v_readlane_b32 s11, v66, 47
	v_readlane_b32 vcc_lo, v66, 63
	s_nop 1
	v_mov_b32_e32 v66, s9
	v_add_f32_e32 v66, s10, v66
	v_add_f32_e32 v66, s11, v66
	v_add_f32_e32 v66, vcc_lo, v66
	v_mul_f32_e32 v66, 0x3a800000, v66
	v_add_f32_e32 v66, 0x3727c5ac, v66
	v_rsq_f32_e32 v118, v66
	s_nop 0
	v_mov_b32_e32 v119, v118
	v_pk_mul_f32 v[122:123], v[122:123], v[118:119]
	v_pk_mul_f32 v[124:125], v[124:125], v[118:119]
	v_pk_mul_f32 v[126:127], v[126:127], v[118:119]
	v_pk_mul_f32 v[128:129], v[128:129], v[118:119]
	v_pk_mul_f32 v[130:131], v[130:131], v[118:119]
	v_pk_mul_f32 v[132:133], v[132:133], v[118:119]
	v_pk_mul_f32 v[134:135], v[134:135], v[118:119]
	v_pk_mul_f32 v[136:137], v[136:137], v[118:119]
	v_pk_fma_f32 v[76:77], v[122:123], v[34:35], v[50:51]
	v_pk_fma_f32 v[78:79], v[124:125], v[36:37], v[52:53]
	v_pk_fma_f32 v[80:81], v[126:127], v[38:39], v[54:55]
	v_pk_fma_f32 v[82:83], v[128:129], v[40:41], v[56:57]
	v_pk_fma_f32 v[84:85], v[130:131], v[42:43], v[58:59]
	v_pk_fma_f32 v[86:87], v[132:133], v[44:45], v[60:61]
	v_pk_fma_f32 v[88:89], v[134:135], v[46:47], v[62:63]
	v_pk_fma_f32 v[90:91], v[136:137], v[48:49], v[64:65]
	v_cvt_pk_bf16_f32 v92, v76, v77
	v_cvt_pk_bf16_f32 v93, v78, v79
	v_cvt_pk_bf16_f32 v94, v80, v81
	v_cvt_pk_bf16_f32 v95, v82, v83
	v_cvt_pk_bf16_f32 v96, v84, v85
	v_cvt_pk_bf16_f32 v97, v86, v87
	v_cvt_pk_bf16_f32 v98, v88, v89
	v_cvt_pk_bf16_f32 v99, v90, v91
	global_store_dwordx2 v115, v[92:93], s[2:3] offset:0 sc1
	global_store_dwordx2 v115, v[94:95], s[2:3] offset:512 sc1
	global_store_dwordx2 v115, v[96:97], s[2:3] offset:1024 sc1
	global_store_dwordx2 v115, v[98:99], s[2:3] offset:1536 sc1
	s_add_u32 s2, s2, 0x400000
	s_addc_u32 s3, s3, 0
	s_add_u32 s0, s0, 0x800000
	s_addc_u32 s1, s1, 0
	global_load_dwordx4 v[122:125], v114, s[0:1] offset:0 nt
	global_load_dwordx4 v[126:129], v114, s[0:1] offset:1024 nt
	global_load_dwordx4 v[130:133], v114, s[0:1] offset:2048 nt
	global_load_dwordx4 v[134:137], v114, s[0:1] offset:3072 nt
	s_waitcnt vmcnt(16)
; __device__ __forceinline__ void phase_ln(float* R, const float* __restrict__ g, const float* __restrict__ b, bf16_t* xbf, float samp_scale, const float* __restrict__ part, int nsplit, bool f32_all) {
;     ...
;   for (int r = gw; r < MT; r += nw) {
;     float* row = R + (size_t)r * 1024;
;     f32x4 v[4];
; #pragma unroll
;     for (int i = 0; i < 4; ++i) v[i] = *(const f32x4*)(row + i * 256 + lane * 4);
;     if (r >= MP) {
;       for (int sp = 0; sp < nsplit; ++sp) {
;         const float* prow = part + ((size_t)sp * MS + (r - MP)) * 1024;
; #pragma unroll
;         for (int i = 0; i < 4; ++i) v[i] = v[i] + *(const f32x4*)(prow + i * 256 + lane * 4);
;       }
;     }
;     float s = 0.f;
; #pragma unroll
;     for (int i = 0; i < 4; ++i) s += v[i][0] + v[i][1] + v[i][2] + v[i][3];
; #pragma unroll
;     for (int o = 32; o >= 1; o >>= 1) s += __shfl_xor(s, o);
;     const float mean = s * (1.f / 1024.f);
;     float ss = 0.f;
; #pragma unroll
;     for (int i = 0; i < 4; ++i) { v[i] = v[i] - mean; ss += v[i][0] * v[i][0] + v[i][1] * v[i][1] + v[i][2] * v[i][2] + v[i][3] * v[i][3]; }
; #pragma unroll
;     for (int o = 32; o >= 1; o >>= 1) ss += __shfl_xor(ss, o);
;     const float rstd = rsqrtf(ss * (1.f / 1024.f) + LN_EPS);
; #pragma unroll
;     for (int i = 0; i < 4; ++i) {
;       const f32x4 y = v[i] * rstd * gv[i] + bv[i];
;       if (r >= MP) *(f32x4*)(row + i * 256 + lane * 4) = y * samp_scale;
;       else if (f32_all) *(f32x4*)(row + i * 256 + lane * 4) = y;
;       if (xbf) {
;         u32x2 wv;
;         wv[0] = cvt_pk_bf16(y[0], y[1]); wv[1] = cvt_pk_bf16(y[2], y[3]);
;         *(u32x2*)(xbf + (size_t)r * 1024 + i * 256 + lane * 4) = wv;
;       }
;     }
	v_pk_add_f32 v[66:67], v[0:1], v[2:3]
	v_pk_add_f32 v[68:69], v[4:5], v[6:7]
	v_pk_add_f32 v[70:71], v[8:9], v[10:11]
	v_pk_add_f32 v[72:73], v[12:13], v[14:15]
	v_pk_add_f32 v[66:67], v[66:67], v[68:69]
	v_pk_add_f32 v[70:71], v[70:71], v[72:73]
	v_pk_add_f32 v[66:67], v[66:67], v[70:71]
	v_add_f32_e32 v66, v66, v67
	s_nop 1
	v_add_f32_dpp v66, v66, v66 row_shr:1 row_mask:0xf bank_mask:0xf bound_ctrl:1
	s_nop 1
	v_add_f32_dpp v66, v66, v66 row_shr:2 row_mask:0xf bank_mask:0xf bound_ctrl:1
	s_nop 1
	v_add_f32_dpp v66, v66, v66 row_shr:4 row_mask:0xf bank_mask:0xf bound_ctrl:1
	s_nop 1
	v_add_f32_dpp v66, v66, v66 row_shr:8 row_mask:0xf bank_mask:0xf bound_ctrl:1
	s_nop 0
	v_readlane_b32 s9, v66, 15
	v_readlane_b32 s10, v66, 31
	v_readlane_b32 s11, v66, 47
	v_readlane_b32 vcc_lo, v66, 63
	s_nop 1
	v_mov_b32_e32 v66, s9
	v_add_f32_e32 v66, s10, v66
	v_add_f32_e32 v66, s11, v66
	v_add_f32_e32 v66, vcc_lo, v66
	v_mul_f32_e32 v116, 0x3a800000, v66
	v_mov_b32_e32 v117, v116
	v_pk_add_f32 v[0:1], v[0:1], v[116:117] neg_lo:[0,1] neg_hi:[0,1]
	v_pk_add_f32 v[2:3], v[2:3], v[116:117] neg_lo:[0,1] neg_hi:[0,1]
	v_pk_add_f32 v[4:5], v[4:5], v[116:117] neg_lo:[0,1] neg_hi:[0,1]
	v_pk_add_f32 v[6:7], v[6:7], v[116:117] neg_lo:[0,1] neg_hi:[0,1]
	v_pk_add_f32 v[8:9], v[8:9], v[116:117] neg_lo:[0,1] neg_hi:[0,1]
	v_pk_add_f32 v[10:11], v[10:11], v[116:117] neg_lo:[0,1] neg_hi:[0,1]
	v_pk_add_f32 v[12:13], v[12:13], v[116:117] neg_lo:[0,1] neg_hi:[0,1]
	v_pk_add_f32 v[14:15], v[14:15], v[116:117] neg_lo:[0,1] neg_hi:[0,1]
	v_pk_mul_f32 v[66:67], v[0:1], v[0:1]
	v_pk_mul_f32 v[68:69], v[2:3], v[2:3]
	v_pk_fma_f32 v[66:67], v[4:5], v[4:5], v[66:67]
	v_pk_fma_f32 v[68:69], v[6:7], v[6:7], v[68:69]
	v_pk_fma_f32 v[66:67], v[8:9], v[8:9], v[66:67]
	v_pk_fma_f32 v[68:69], v[10:11], v[10:11], v[68:69]
	v_pk_fma_f32 v[66:67], v[12:13], v[12:13], v[66:67]
	v_pk_fma_f32 v[68:69], v[14:15], v[14:15], v[68:69]
	v_pk_add_f32 v[66:67], v[66:67], v[68:69]
	v_add_f32_e32 v66, v66, v67
	s_nop 1
	v_add_f32_dpp v66, v66, v66 row_shr:1 row_mask:0xf bank_mask:0xf bound_ctrl:1
	s_nop 1
	v_add_f32_dpp v66, v66, v66 row_shr:2 row_mask:0xf bank_mask:0xf bound_ctrl:1
	s_nop 1
	v_add_f32_dpp v66, v66, v66 row_shr:4 row_mask:0xf bank_mask:0xf bound_ctrl:1
	s_nop 1
	v_add_f32_dpp v66, v66, v66 row_shr:8 row_mask:0xf bank_mask:0xf bound_ctrl:1
	s_nop 0
	v_readlane_b32 s9, v66, 15
	v_readlane_b32 s10, v66, 31
	v_readlane_b32 s11, v66, 47
	v_readlane_b32 vcc_lo, v66, 63
	s_nop 1
	v_mov_b32_e32 v66, s9
	v_add_f32_e32 v66, s10, v66
	v_add_f32_e32 v66, s11, v66
	v_add_f32_e32 v66, vcc_lo, v66
	v_mul_f32_e32 v66, 0x3a800000, v66
	v_add_f32_e32 v66, 0x3727c5ac, v66
	v_rsq_f32_e32 v118, v66
	s_nop 0
	v_mov_b32_e32 v119, v118
	v_pk_mul_f32 v[0:1], v[0:1], v[118:119]
	v_pk_mul_f32 v[2:3], v[2:3], v[118:119]
	v_pk_mul_f32 v[4:5], v[4:5], v[118:119]
	v_pk_mul_f32 v[6:7], v[6:7], v[118:119]
	v_pk_mul_f32 v[8:9], v[8:9], v[118:119]
	v_pk_mul_f32 v[10:11], v[10:11], v[118:119]
	v_pk_mul_f32 v[12:13], v[12:13], v[118:119]
	v_pk_mul_f32 v[14:15], v[14:15], v[118:119]
	v_pk_fma_f32 v[76:77], v[0:1], v[34:35], v[50:51]
	v_pk_fma_f32 v[78:79], v[2:3], v[36:37], v[52:53]
	v_pk_fma_f32 v[80:81], v[4:5], v[38:39], v[54:55]
	v_pk_fma_f32 v[82:83], v[6:7], v[40:41], v[56:57]
	v_pk_fma_f32 v[84:85], v[8:9], v[42:43], v[58:59]
	v_pk_fma_f32 v[86:87], v[10:11], v[44:45], v[60:61]
	v_pk_fma_f32 v[88:89], v[12:13], v[46:47], v[62:63]
	v_pk_fma_f32 v[90:91], v[14:15], v[48:49], v[64:65]
	v_cvt_pk_bf16_f32 v92, v76, v77
	v_cvt_pk_bf16_f32 v93, v78, v79
	v_cvt_pk_bf16_f32 v94, v80, v81
	v_cvt_pk_bf16_f32 v95, v82, v83
	v_cvt_pk_bf16_f32 v96, v84, v85
	v_cvt_pk_bf16_f32 v97, v86, v87
	v_cvt_pk_bf16_f32 v98, v88, v89
	v_cvt_pk_bf16_f32 v99, v90, v91
	global_store_dwordx2 v115, v[92:93], s[2:3] offset:0 sc1
	global_store_dwordx2 v115, v[94:95], s[2:3] offset:512 sc1
	global_store_dwordx2 v115, v[96:97], s[2:3] offset:1024 sc1
	global_store_dwordx2 v115, v[98:99], s[2:3] offset:1536 sc1
	s_add_u32 s2, s2, 0x400000
	s_addc_u32 s3, s3, 0
	s_add_u32 s0, s0, 0x800000
	s_addc_u32 s1, s1, 0
	global_load_dwordx4 v[0:3], v114, s[0:1] offset:0 nt
	global_load_dwordx4 v[4:7], v114, s[0:1] offset:1024 nt
	global_load_dwordx4 v[8:11], v114, s[0:1] offset:2048 nt
	global_load_dwordx4 v[12:15], v114, s[0:1] offset:3072 nt
	s_waitcnt vmcnt(16)
; __device__ __forceinline__ void phase_ln(float* R, const float* __restrict__ g, const float* __restrict__ b, bf16_t* xbf, float samp_scale, const float* __restrict__ part, int nsplit, bool f32_all) {
;     ...
;   for (int r = gw; r < MT; r += nw) {
;     float* row = R + (size_t)r * 1024;
;     f32x4 v[4];
; #pragma unroll
;     for (int i = 0; i < 4; ++i) v[i] = *(const f32x4*)(row + i * 256 + lane * 4);
;     if (r >= MP) {
;       for (int sp = 0; sp < nsplit; ++sp) {
;         const float* prow = part + ((size_t)sp * MS + (r - MP)) * 1024;
; #pragma unroll
;         for (int i = 0; i < 4; ++i) v[i] = v[i] + *(const f32x4*)(prow + i * 256 + lane * 4);
;       }
;     }
;     float s = 0.f;
; #pragma unroll
;     for (int i = 0; i < 4; ++i) s += v[i][0] + v[i][1] + v[i][2] + v[i][3];
; #pragma unroll
;     for (int o = 32; o >= 1; o >>= 1) s += __shfl_xor(s, o);
;     const float mean = s * (1.f / 1024.f);
;     float ss = 0.f;
; #pragma unroll
;     for (int i = 0; i < 4; ++i) { v[i] = v[i] - mean; ss += v[i][0] * v[i][0] + v[i][1] * v[i][1] + v[i][2] * v[i][2] + v[i][3] * v[i][3]; }
; #pragma unroll
;     for (int o = 32; o >= 1; o >>= 1) ss += __shfl_xor(ss, o);
;     const float rstd = rsqrtf(ss * (1.f / 1024.f) + LN_EPS);
; #pragma unroll
;     for (int i = 0; i < 4; ++i) {
;       const f32x4 y = v[i] * rstd * gv[i] + bv[i];
;       if (r >= MP) *(f32x4*)(row + i * 256 + lane * 4) = y * samp_scale;
;       else if (f32_all) *(f32x4*)(row + i * 256 + lane * 4) = y;
;       if (xbf) {
;         u32x2 wv;
;         wv[0] = cvt_pk_bf16(y[0], y[1]); wv[1] = cvt_pk_bf16(y[2], y[3]);
;         *(u32x2*)(xbf + (size_t)r * 1024 + i * 256 + lane * 4) = wv;
;       }
;     }
	v_pk_add_f32 v[66:67], v[18:19], v[20:21]
	v_pk_add_f32 v[68:69], v[22:23], v[24:25]
	v_pk_add_f32 v[70:71], v[26:27], v[28:29]
	v_pk_add_f32 v[72:73], v[30:31], v[32:33]
	v_pk_add_f32 v[66:67], v[66:67], v[68:69]
	v_pk_add_f32 v[70:71], v[70:71], v[72:73]
	v_pk_add_f32 v[66:67], v[66:67], v[70:71]
	v_add_f32_e32 v66, v66, v67
	s_nop 1
	v_add_f32_dpp v66, v66, v66 row_shr:1 row_mask:0xf bank_mask:0xf bound_ctrl:1
	s_nop 1
	v_add_f32_dpp v66, v66, v66 row_shr:2 row_mask:0xf bank_mask:0xf bound_ctrl:1
	s_nop 1
	v_add_f32_dpp v66, v66, v66 row_shr:4 row_mask:0xf bank_mask:0xf bound_ctrl:1
	s_nop 1
	v_add_f32_dpp v66, v66, v66 row_shr:8 row_mask:0xf bank_mask:0xf bound_ctrl:1
	s_nop 0
	v_readlane_b32 s9, v66, 15
	v_readlane_b32 s10, v66, 31
	v_readlane_b32 s11, v66, 47
	v_readlane_b32 vcc_lo, v66, 63
	s_nop 1
	v_mov_b32_e32 v66, s9
	v_add_f32_e32 v66, s10, v66
	v_add_f32_e32 v66, s11, v66
	v_add_f32_e32 v66, vcc_lo, v66
	v_mul_f32_e32 v116, 0x3a800000, v66
	v_mov_b32_e32 v117, v116
	v_pk_add_f32 v[18:19], v[18:19], v[116:117] neg_lo:[0,1] neg_hi:[0,1]
	v_pk_add_f32 v[20:21], v[20:21], v[116:117] neg_lo:[0,1] neg_hi:[0,1]
	v_pk_add_f32 v[22:23], v[22:23], v[116:117] neg_lo:[0,1] neg_hi:[0,1]
	v_pk_add_f32 v[24:25], v[24:25], v[116:117] neg_lo:[0,1] neg_hi:[0,1]
	v_pk_add_f32 v[26:27], v[26:27], v[116:117] neg_lo:[0,1] neg_hi:[0,1]
	v_pk_add_f32 v[28:29], v[28:29], v[116:117] neg_lo:[0,1] neg_hi:[0,1]
	v_pk_add_f32 v[30:31], v[30:31], v[116:117] neg_lo:[0,1] neg_hi:[0,1]
	v_pk_add_f32 v[32:33], v[32:33], v[116:117] neg_lo:[0,1] neg_hi:[0,1]
	v_pk_mul_f32 v[66:67], v[18:19], v[18:19]
	v_pk_mul_f32 v[68:69], v[20:21], v[20:21]
	v_pk_fma_f32 v[66:67], v[22:23], v[22:23], v[66:67]
	v_pk_fma_f32 v[68:69], v[24:25], v[24:25], v[68:69]
	v_pk_fma_f32 v[66:67], v[26:27], v[26:27], v[66:67]
	v_pk_fma_f32 v[68:69], v[28:29], v[28:29], v[68:69]
	v_pk_fma_f32 v[66:67], v[30:31], v[30:31], v[66:67]
	v_pk_fma_f32 v[68:69], v[32:33], v[32:33], v[68:69]
	v_pk_add_f32 v[66:67], v[66:67], v[68:69]
	v_add_f32_e32 v66, v66, v67
	s_nop 1
	v_add_f32_dpp v66, v66, v66 row_shr:1 row_mask:0xf bank_mask:0xf bound_ctrl:1
	s_nop 1
	v_add_f32_dpp v66, v66, v66 row_shr:2 row_mask:0xf bank_mask:0xf bound_ctrl:1
	s_nop 1
	v_add_f32_dpp v66, v66, v66 row_shr:4 row_mask:0xf bank_mask:0xf bound_ctrl:1
	s_nop 1
	v_add_f32_dpp v66, v66, v66 row_shr:8 row_mask:0xf bank_mask:0xf bound_ctrl:1
	s_nop 0
	v_readlane_b32 s9, v66, 15
	v_readlane_b32 s10, v66, 31
	v_readlane_b32 s11, v66, 47
	v_readlane_b32 vcc_lo, v66, 63
	s_nop 1
	v_mov_b32_e32 v66, s9
	v_add_f32_e32 v66, s10, v66
	v_add_f32_e32 v66, s11, v66
	v_add_f32_e32 v66, vcc_lo, v66
	v_mul_f32_e32 v66, 0x3a800000, v66
	v_add_f32_e32 v66, 0x3727c5ac, v66
	v_rsq_f32_e32 v118, v66
	s_nop 0
	v_mov_b32_e32 v119, v118
	v_pk_mul_f32 v[18:19], v[18:19], v[118:119]
	v_pk_mul_f32 v[20:21], v[20:21], v[118:119]
	v_pk_mul_f32 v[22:23], v[22:23], v[118:119]
	v_pk_mul_f32 v[24:25], v[24:25], v[118:119]
	v_pk_mul_f32 v[26:27], v[26:27], v[118:119]
	v_pk_mul_f32 v[28:29], v[28:29], v[118:119]
	v_pk_mul_f32 v[30:31], v[30:31], v[118:119]
	v_pk_mul_f32 v[32:33], v[32:33], v[118:119]
	v_pk_fma_f32 v[76:77], v[18:19], v[34:35], v[50:51]
	v_pk_fma_f32 v[78:79], v[20:21], v[36:37], v[52:53]
	v_pk_fma_f32 v[80:81], v[22:23], v[38:39], v[54:55]
	v_pk_fma_f32 v[82:83], v[24:25], v[40:41], v[56:57]
	v_pk_fma_f32 v[84:85], v[26:27], v[42:43], v[58:59]
	v_pk_fma_f32 v[86:87], v[28:29], v[44:45], v[60:61]
	v_pk_fma_f32 v[88:89], v[30:31], v[46:47], v[62:63]
	v_pk_fma_f32 v[90:91], v[32:33], v[48:49], v[64:65]
	v_cvt_pk_bf16_f32 v92, v76, v77
	v_cvt_pk_bf16_f32 v93, v78, v79
	v_cvt_pk_bf16_f32 v94, v80, v81
	v_cvt_pk_bf16_f32 v95, v82, v83
	v_cvt_pk_bf16_f32 v96, v84, v85
	v_cvt_pk_bf16_f32 v97, v86, v87
	v_cvt_pk_bf16_f32 v98, v88, v89
	v_cvt_pk_bf16_f32 v99, v90, v91
	global_store_dwordx2 v115, v[92:93], s[2:3] offset:0 sc1
	global_store_dwordx2 v115, v[94:95], s[2:3] offset:512 sc1
	global_store_dwordx2 v115, v[96:97], s[2:3] offset:1024 sc1
	global_store_dwordx2 v115, v[98:99], s[2:3] offset:1536 sc1
	s_add_u32 s2, s2, 0x400000
	s_addc_u32 s3, s3, 0
	s_add_u32 s0, s0, 0x800000
	s_addc_u32 s1, s1, 0
	global_load_dwordx4 v[18:21], v114, s[0:1] offset:0 nt
	global_load_dwordx4 v[22:25], v114, s[0:1] offset:1024 nt
	global_load_dwordx4 v[26:29], v114, s[0:1] offset:2048 nt
	global_load_dwordx4 v[30:33], v114, s[0:1] offset:3072 nt
	s_waitcnt vmcnt(16)
; __device__ __forceinline__ void phase_ln(float* R, const float* __restrict__ g, const float* __restrict__ b, bf16_t* xbf, float samp_scale, const float* __restrict__ part, int nsplit, bool f32_all) {
;     ...
;   for (int r = gw; r < MT; r += nw) {
;     float* row = R + (size_t)r * 1024;
;     f32x4 v[4];
; #pragma unroll
;     for (int i = 0; i < 4; ++i) v[i] = *(const f32x4*)(row + i * 256 + lane * 4);
;     if (r >= MP) {
;       for (int sp = 0; sp < nsplit; ++sp) {
;         const float* prow = part + ((size_t)sp * MS + (r - MP)) * 1024;
; #pragma unroll
;         for (int i = 0; i < 4; ++i) v[i] = v[i] + *(const f32x4*)(prow + i * 256 + lane * 4);
;       }
;     }
;     float s = 0.f;
; #pragma unroll
;     for (int i = 0; i < 4; ++i) s += v[i][0] + v[i][1] + v[i][2] + v[i][3];
; #pragma unroll
;     for (int o = 32; o >= 1; o >>= 1) s += __shfl_xor(s, o);
;     const float mean = s * (1.f / 1024.f);
;     float ss = 0.f;
; #pragma unroll
;     for (int i = 0; i < 4; ++i) { v[i] = v[i] - mean; ss += v[i][0] * v[i][0] + v[i][1] * v[i][1] + v[i][2] * v[i][2] + v[i][3] * v[i][3]; }
; #pragma unroll
;     for (int o = 32; o >= 1; o >>= 1) ss += __shfl_xor(ss, o);
;     const float rstd = rsqrtf(ss * (1.f / 1024.f) + LN_EPS);
; #pragma unroll
;     for (int i = 0; i < 4; ++i) {
;       const f32x4 y = v[i] * rstd * gv[i] + bv[i];
;       if (r >= MP) *(f32x4*)(row + i * 256 + lane * 4) = y * samp_scale;
;       else if (f32_all) *(f32x4*)(row + i * 256 + lane * 4) = y;
;       if (xbf) {
;         u32x2 wv;
;         wv[0] = cvt_pk_bf16(y[0], y[1]); wv[1] = cvt_pk_bf16(y[2], y[3]);
;         *(u32x2*)(xbf + (size_t)r * 1024 + i * 256 + lane * 4) = wv;
;       }
;     }
	v_pk_add_f32 v[66:67], v[122:123], v[124:125]
	v_pk_add_f32 v[68:69], v[126:127], v[128:129]
	v_pk_add_f32 v[70:71], v[130:131], v[132:133]
	v_pk_add_f32 v[72:73], v[134:135], v[136:137]
	v_pk_add_f32 v[66:67], v[66:67], v[68:69]
	v_pk_add_f32 v[70:71], v[70:71], v[72:73]
	v_pk_add_f32 v[66:67], v[66:67], v[70:71]
	v_add_f32_e32 v66, v66, v67
	s_nop 1
	v_add_f32_dpp v66, v66, v66 row_shr:1 row_mask:0xf bank_mask:0xf bound_ctrl:1
	s_nop 1
	v_add_f32_dpp v66, v66, v66 row_shr:2 row_mask:0xf bank_mask:0xf bound_ctrl:1
	s_nop 1
	v_add_f32_dpp v66, v66, v66 row_shr:4 row_mask:0xf bank_mask:0xf bound_ctrl:1
	s_nop 1
	v_add_f32_dpp v66, v66, v66 row_shr:8 row_mask:0xf bank_mask:0xf bound_ctrl:1
	s_nop 0
	v_readlane_b32 s9, v66, 15
	v_readlane_b32 s10, v66, 31
	v_readlane_b32 s11, v66, 47
	v_readlane_b32 vcc_lo, v66, 63
	s_nop 1
	v_mov_b32_e32 v66, s9
	v_add_f32_e32 v66, s10, v66
	v_add_f32_e32 v66, s11, v66
	v_add_f32_e32 v66, vcc_lo, v66
	v_mul_f32_e32 v116, 0x3a800000, v66
	v_mov_b32_e32 v117, v116
	v_pk_add_f32 v[122:123], v[122:123], v[116:117] neg_lo:[0,1] neg_hi:[0,1]
	v_pk_add_f32 v[124:125], v[124:125], v[116:117] neg_lo:[0,1] neg_hi:[0,1]
	v_pk_add_f32 v[126:127], v[126:127], v[116:117] neg_lo:[0,1] neg_hi:[0,1]
	v_pk_add_f32 v[128:129], v[128:129], v[116:117] neg_lo:[0,1] neg_hi:[0,1]
	v_pk_add_f32 v[130:131], v[130:131], v[116:117] neg_lo:[0,1] neg_hi:[0,1]
	v_pk_add_f32 v[132:133], v[132:133], v[116:117] neg_lo:[0,1] neg_hi:[0,1]
	v_pk_add_f32 v[134:135], v[134:135], v[116:117] neg_lo:[0,1] neg_hi:[0,1]
	v_pk_add_f32 v[136:137], v[136:137], v[116:117] neg_lo:[0,1] neg_hi:[0,1]
	v_pk_mul_f32 v[66:67], v[122:123], v[122:123]
	v_pk_mul_f32 v[68:69], v[124:125], v[124:125]
	v_pk_fma_f32 v[66:67], v[126:127], v[126:127], v[66:67]
	v_pk_fma_f32 v[68:69], v[128:129], v[128:129], v[68:69]
	v_pk_fma_f32 v[66:67], v[130:131], v[130:131], v[66:67]
	v_pk_fma_f32 v[68:69], v[132:133], v[132:133], v[68:69]
	v_pk_fma_f32 v[66:67], v[134:135], v[134:135], v[66:67]
	v_pk_fma_f32 v[68:69], v[136:137], v[136:137], v[68:69]
	v_pk_add_f32 v[66:67], v[66:67], v[68:69]
	v_add_f32_e32 v66, v66, v67
	s_nop 1
	v_add_f32_dpp v66, v66, v66 row_shr:1 row_mask:0xf bank_mask:0xf bound_ctrl:1
	s_nop 1
	v_add_f32_dpp v66, v66, v66 row_shr:2 row_mask:0xf bank_mask:0xf bound_ctrl:1
	s_nop 1
	v_add_f32_dpp v66, v66, v66 row_shr:4 row_mask:0xf bank_mask:0xf bound_ctrl:1
	s_nop 1
	v_add_f32_dpp v66, v66, v66 row_shr:8 row_mask:0xf bank_mask:0xf bound_ctrl:1
	s_nop 0
	v_readlane_b32 s9, v66, 15
	v_readlane_b32 s10, v66, 31
	v_readlane_b32 s11, v66, 47
	v_readlane_b32 vcc_lo, v66, 63
	s_nop 1
	v_mov_b32_e32 v66, s9
	v_add_f32_e32 v66, s10, v66
	v_add_f32_e32 v66, s11, v66
	v_add_f32_e32 v66, vcc_lo, v66
	v_mul_f32_e32 v66, 0x3a800000, v66
	v_add_f32_e32 v66, 0x3727c5ac, v66
	v_rsq_f32_e32 v118, v66
	s_nop 0
	v_mov_b32_e32 v119, v118
	v_pk_mul_f32 v[122:123], v[122:123], v[118:119]
	v_pk_mul_f32 v[124:125], v[124:125], v[118:119]
	v_pk_mul_f32 v[126:127], v[126:127], v[118:119]
	v_pk_mul_f32 v[128:129], v[128:129], v[118:119]
	v_pk_mul_f32 v[130:131], v[130:131], v[118:119]
	v_pk_mul_f32 v[132:133], v[132:133], v[118:119]
	v_pk_mul_f32 v[134:135], v[134:135], v[118:119]
	v_pk_mul_f32 v[136:137], v[136:137], v[118:119]
	v_pk_fma_f32 v[76:77], v[122:123], v[34:35], v[50:51]
	v_pk_fma_f32 v[78:79], v[124:125], v[36:37], v[52:53]
	v_pk_fma_f32 v[80:81], v[126:127], v[38:39], v[54:55]
	v_pk_fma_f32 v[82:83], v[128:129], v[40:41], v[56:57]
	v_pk_fma_f32 v[84:85], v[130:131], v[42:43], v[58:59]
	v_pk_fma_f32 v[86:87], v[132:133], v[44:45], v[60:61]
	v_pk_fma_f32 v[88:89], v[134:135], v[46:47], v[62:63]
	v_pk_fma_f32 v[90:91], v[136:137], v[48:49], v[64:65]
	v_cvt_pk_bf16_f32 v92, v76, v77
	v_cvt_pk_bf16_f32 v93, v78, v79
	v_cvt_pk_bf16_f32 v94, v80, v81
	v_cvt_pk_bf16_f32 v95, v82, v83
	v_cvt_pk_bf16_f32 v96, v84, v85
	v_cvt_pk_bf16_f32 v97, v86, v87
	v_cvt_pk_bf16_f32 v98, v88, v89
	v_cvt_pk_bf16_f32 v99, v90, v91
	global_store_dwordx2 v115, v[92:93], s[2:3] offset:0 sc1
	global_store_dwordx2 v115, v[94:95], s[2:3] offset:512 sc1
	global_store_dwordx2 v115, v[96:97], s[2:3] offset:1024 sc1
	global_store_dwordx2 v115, v[98:99], s[2:3] offset:1536 sc1
	s_add_u32 s2, s2, 0x400000
	s_addc_u32 s3, s3, 0
	s_add_u32 s0, s0, 0x800000
	s_addc_u32 s1, s1, 0
	global_load_dwordx4 v[122:125], v114, s[0:1] offset:0 nt
	global_load_dwordx4 v[126:129], v114, s[0:1] offset:1024 nt
	global_load_dwordx4 v[130:133], v114, s[0:1] offset:2048 nt
	global_load_dwordx4 v[134:137], v114, s[0:1] offset:3072 nt
	s_waitcnt vmcnt(16)
; __device__ __forceinline__ void phase_ln(float* R, const float* __restrict__ g, const float* __restrict__ b, bf16_t* xbf, float samp_scale, const float* __restrict__ part, int nsplit, bool f32_all) {
;     ...
;   for (int r = gw; r < MT; r += nw) {
;     float* row = R + (size_t)r * 1024;
;     f32x4 v[4];
; #pragma unroll
;     for (int i = 0; i < 4; ++i) v[i] = *(const f32x4*)(row + i * 256 + lane * 4);
;     if (r >= MP) {
;       for (int sp = 0; sp < nsplit; ++sp) {
;         const float* prow = part + ((size_t)sp * MS + (r - MP)) * 1024;
; #pragma unroll
;         for (int i = 0; i < 4; ++i) v[i] = v[i] + *(const f32x4*)(prow + i * 256 + lane * 4);
;       }
;     }
;     float s = 0.f;
; #pragma unroll
;     for (int i = 0; i < 4; ++i) s += v[i][0] + v[i][1] + v[i][2] + v[i][3];
; #pragma unroll
;     for (int o = 32; o >= 1; o >>= 1) s += __shfl_xor(s, o);
;     const float mean = s * (1.f / 1024.f);
;     float ss = 0.f;
; #pragma unroll
;     for (int i = 0; i < 4; ++i) { v[i] = v[i] - mean; ss += v[i][0] * v[i][0] + v[i][1] * v[i][1] + v[i][2] * v[i][2] + v[i][3] * v[i][3]; }
; #pragma unroll
;     for (int o = 32; o >= 1; o >>= 1) ss += __shfl_xor(ss, o);
;     const float rstd = rsqrtf(ss * (1.f / 1024.f) + LN_EPS);
; #pragma unroll
;     for (int i = 0; i < 4; ++i) {
;       const f32x4 y = v[i] * rstd * gv[i] + bv[i];
;       if (r >= MP) *(f32x4*)(row + i * 256 + lane * 4) = y * samp_scale;
;       else if (f32_all) *(f32x4*)(row + i * 256 + lane * 4) = y;
;       if (xbf) {
;         u32x2 wv;
;         wv[0] = cvt_pk_bf16(y[0], y[1]); wv[1] = cvt_pk_bf16(y[2], y[3]);
;         *(u32x2*)(xbf + (size_t)r * 1024 + i * 256 + lane * 4) = wv;
;       }
;     }
	v_pk_add_f32 v[66:67], v[0:1], v[2:3]
	v_pk_add_f32 v[68:69], v[4:5], v[6:7]
	v_pk_add_f32 v[70:71], v[8:9], v[10:11]
	v_pk_add_f32 v[72:73], v[12:13], v[14:15]
	v_pk_add_f32 v[66:67], v[66:67], v[68:69]
	v_pk_add_f32 v[70:71], v[70:71], v[72:73]
	v_pk_add_f32 v[66:67], v[66:67], v[70:71]
	v_add_f32_e32 v66, v66, v67
	s_nop 1
	v_add_f32_dpp v66, v66, v66 row_shr:1 row_mask:0xf bank_mask:0xf bound_ctrl:1
	s_nop 1
	v_add_f32_dpp v66, v66, v66 row_shr:2 row_mask:0xf bank_mask:0xf bound_ctrl:1
	s_nop 1
	v_add_f32_dpp v66, v66, v66 row_shr:4 row_mask:0xf bank_mask:0xf bound_ctrl:1
	s_nop 1
	v_add_f32_dpp v66, v66, v66 row_shr:8 row_mask:0xf bank_mask:0xf bound_ctrl:1
	s_nop 0
	v_readlane_b32 s9, v66, 15
	v_readlane_b32 s10, v66, 31
	v_readlane_b32 s11, v66, 47
	v_readlane_b32 vcc_lo, v66, 63
	s_nop 1
	v_mov_b32_e32 v66, s9
	v_add_f32_e32 v66, s10, v66
	v_add_f32_e32 v66, s11, v66
	v_add_f32_e32 v66, vcc_lo, v66
	v_mul_f32_e32 v116, 0x3a800000, v66
	v_mov_b32_e32 v117, v116
	v_pk_add_f32 v[0:1], v[0:1], v[116:117] neg_lo:[0,1] neg_hi:[0,1]
	v_pk_add_f32 v[2:3], v[2:3], v[116:117] neg_lo:[0,1] neg_hi:[0,1]
	v_pk_add_f32 v[4:5], v[4:5], v[116:117] neg_lo:[0,1] neg_hi:[0,1]
	v_pk_add_f32 v[6:7], v[6:7], v[116:117] neg_lo:[0,1] neg_hi:[0,1]
	v_pk_add_f32 v[8:9], v[8:9], v[116:117] neg_lo:[0,1] neg_hi:[0,1]
	v_pk_add_f32 v[10:11], v[10:11], v[116:117] neg_lo:[0,1] neg_hi:[0,1]
	v_pk_add_f32 v[12:13], v[12:13], v[116:117] neg_lo:[0,1] neg_hi:[0,1]
	v_pk_add_f32 v[14:15], v[14:15], v[116:117] neg_lo:[0,1] neg_hi:[0,1]
	v_pk_mul_f32 v[66:67], v[0:1], v[0:1]
	v_pk_mul_f32 v[68:69], v[2:3], v[2:3]
	v_pk_fma_f32 v[66:67], v[4:5], v[4:5], v[66:67]
	v_pk_fma_f32 v[68:69], v[6:7], v[6:7], v[68:69]
	v_pk_fma_f32 v[66:67], v[8:9], v[8:9], v[66:67]
	v_pk_fma_f32 v[68:69], v[10:11], v[10:11], v[68:69]
	v_pk_fma_f32 v[66:67], v[12:13], v[12:13], v[66:67]
	v_pk_fma_f32 v[68:69], v[14:15], v[14:15], v[68:69]
	v_pk_add_f32 v[66:67], v[66:67], v[68:69]
	v_add_f32_e32 v66, v66, v67
	s_nop 1
	v_add_f32_dpp v66, v66, v66 row_shr:1 row_mask:0xf bank_mask:0xf bound_ctrl:1
	s_nop 1
	v_add_f32_dpp v66, v66, v66 row_shr:2 row_mask:0xf bank_mask:0xf bound_ctrl:1
	s_nop 1
	v_add_f32_dpp v66, v66, v66 row_shr:4 row_mask:0xf bank_mask:0xf bound_ctrl:1
	s_nop 1
	v_add_f32_dpp v66, v66, v66 row_shr:8 row_mask:0xf bank_mask:0xf bound_ctrl:1
	s_nop 0
	v_readlane_b32 s9, v66, 15
	v_readlane_b32 s10, v66, 31
	v_readlane_b32 s11, v66, 47
	v_readlane_b32 vcc_lo, v66, 63
	s_nop 1
	v_mov_b32_e32 v66, s9
	v_add_f32_e32 v66, s10, v66
	v_add_f32_e32 v66, s11, v66
	v_add_f32_e32 v66, vcc_lo, v66
	v_mul_f32_e32 v66, 0x3a800000, v66
	v_add_f32_e32 v66, 0x3727c5ac, v66
	v_rsq_f32_e32 v118, v66
	s_nop 0
	v_mov_b32_e32 v119, v118
	v_pk_mul_f32 v[0:1], v[0:1], v[118:119]
	v_pk_mul_f32 v[2:3], v[2:3], v[118:119]
	v_pk_mul_f32 v[4:5], v[4:5], v[118:119]
	v_pk_mul_f32 v[6:7], v[6:7], v[118:119]
	v_pk_mul_f32 v[8:9], v[8:9], v[118:119]
	v_pk_mul_f32 v[10:11], v[10:11], v[118:119]
	v_pk_mul_f32 v[12:13], v[12:13], v[118:119]
	v_pk_mul_f32 v[14:15], v[14:15], v[118:119]
	v_pk_fma_f32 v[76:77], v[0:1], v[34:35], v[50:51]
	v_pk_fma_f32 v[78:79], v[2:3], v[36:37], v[52:53]
	v_pk_fma_f32 v[80:81], v[4:5], v[38:39], v[54:55]
	v_pk_fma_f32 v[82:83], v[6:7], v[40:41], v[56:57]
	v_pk_fma_f32 v[84:85], v[8:9], v[42:43], v[58:59]
	v_pk_fma_f32 v[86:87], v[10:11], v[44:45], v[60:61]
	v_pk_fma_f32 v[88:89], v[12:13], v[46:47], v[62:63]
	v_pk_fma_f32 v[90:91], v[14:15], v[48:49], v[64:65]
	v_cvt_pk_bf16_f32 v92, v76, v77
	v_cvt_pk_bf16_f32 v93, v78, v79
	v_cvt_pk_bf16_f32 v94, v80, v81
	v_cvt_pk_bf16_f32 v95, v82, v83
	v_cvt_pk_bf16_f32 v96, v84, v85
	v_cvt_pk_bf16_f32 v97, v86, v87
	v_cvt_pk_bf16_f32 v98, v88, v89
	v_cvt_pk_bf16_f32 v99, v90, v91
	global_store_dwordx2 v115, v[92:93], s[2:3] offset:0 sc1
	global_store_dwordx2 v115, v[94:95], s[2:3] offset:512 sc1
	global_store_dwordx2 v115, v[96:97], s[2:3] offset:1024 sc1
	global_store_dwordx2 v115, v[98:99], s[2:3] offset:1536 sc1
	s_add_u32 s2, s2, 0x400000
	s_addc_u32 s3, s3, 0
	s_add_u32 s0, s0, 0x800000
	s_addc_u32 s1, s1, 0
	global_load_dwordx4 v[0:3], v114, s[0:1] offset:0 nt
	global_load_dwordx4 v[4:7], v114, s[0:1] offset:1024 nt
	global_load_dwordx4 v[8:11], v114, s[0:1] offset:2048 nt
	global_load_dwordx4 v[12:15], v114, s[0:1] offset:3072 nt
	s_waitcnt vmcnt(16)
; __device__ __forceinline__ void phase_ln(float* R, const float* __restrict__ g, const float* __restrict__ b, bf16_t* xbf, float samp_scale, const float* __restrict__ part, int nsplit, bool f32_all) {
;     ...
;   for (int r = gw; r < MT; r += nw) {
;     float* row = R + (size_t)r * 1024;
;     f32x4 v[4];
; #pragma unroll
;     for (int i = 0; i < 4; ++i) v[i] = *(const f32x4*)(row + i * 256 + lane * 4);
;     if (r >= MP) {
;       for (int sp = 0; sp < nsplit; ++sp) {
;         const float* prow = part + ((size_t)sp * MS + (r - MP)) * 1024;
; #pragma unroll
;         for (int i = 0; i < 4; ++i) v[i] = v[i] + *(const f32x4*)(prow + i * 256 + lane * 4);
;       }
;     }
;     float s = 0.f;
; #pragma unroll
;     for (int i = 0; i < 4; ++i) s += v[i][0] + v[i][1] + v[i][2] + v[i][3];
; #pragma unroll
;     for (int o = 32; o >= 1; o >>= 1) s += __shfl_xor(s, o);
;     const float mean = s * (1.f / 1024.f);
;     float ss = 0.f;
; #pragma unroll
;     for (int i = 0; i < 4; ++i) { v[i] = v[i] - mean; ss += v[i][0] * v[i][0] + v[i][1] * v[i][1] + v[i][2] * v[i][2] + v[i][3] * v[i][3]; }
; #pragma unroll
;     for (int o = 32; o >= 1; o >>= 1) ss += __shfl_xor(ss, o);
;     const float rstd = rsqrtf(ss * (1.f / 1024.f) + LN_EPS);
; #pragma unroll
;     for (int i = 0; i < 4; ++i) {
;       const f32x4 y = v[i] * rstd * gv[i] + bv[i];
;       if (r >= MP) *(f32x4*)(row + i * 256 + lane * 4) = y * samp_scale;
;       else if (f32_all) *(f32x4*)(row + i * 256 + lane * 4) = y;
;       if (xbf) {
;         u32x2 wv;
;         wv[0] = cvt_pk_bf16(y[0], y[1]); wv[1] = cvt_pk_bf16(y[2], y[3]);
;         *(u32x2*)(xbf + (size_t)r * 1024 + i * 256 + lane * 4) = wv;
;       }
;     }
	v_pk_add_f32 v[66:67], v[18:19], v[20:21]
	v_pk_add_f32 v[68:69], v[22:23], v[24:25]
	v_pk_add_f32 v[70:71], v[26:27], v[28:29]
	v_pk_add_f32 v[72:73], v[30:31], v[32:33]
	v_pk_add_f32 v[66:67], v[66:67], v[68:69]
	v_pk_add_f32 v[70:71], v[70:71], v[72:73]
	v_pk_add_f32 v[66:67], v[66:67], v[70:71]
	v_add_f32_e32 v66, v66, v67
	s_nop 1
	v_add_f32_dpp v66, v66, v66 row_shr:1 row_mask:0xf bank_mask:0xf bound_ctrl:1
	s_nop 1
	v_add_f32_dpp v66, v66, v66 row_shr:2 row_mask:0xf bank_mask:0xf bound_ctrl:1
	s_nop 1
	v_add_f32_dpp v66, v66, v66 row_shr:4 row_mask:0xf bank_mask:0xf bound_ctrl:1
	s_nop 1
	v_add_f32_dpp v66, v66, v66 row_shr:8 row_mask:0xf bank_mask:0xf bound_ctrl:1
	s_nop 0
	v_readlane_b32 s9, v66, 15
	v_readlane_b32 s10, v66, 31
	v_readlane_b32 s11, v66, 47
	v_readlane_b32 vcc_lo, v66, 63
	s_nop 1
	v_mov_b32_e32 v66, s9
	v_add_f32_e32 v66, s10, v66
	v_add_f32_e32 v66, s11, v66
	v_add_f32_e32 v66, vcc_lo, v66
	v_mul_f32_e32 v116, 0x3a800000, v66
	v_mov_b32_e32 v117, v116
	v_pk_add_f32 v[18:19], v[18:19], v[116:117] neg_lo:[0,1] neg_hi:[0,1]
	v_pk_add_f32 v[20:21], v[20:21], v[116:117] neg_lo:[0,1] neg_hi:[0,1]
	v_pk_add_f32 v[22:23], v[22:23], v[116:117] neg_lo:[0,1] neg_hi:[0,1]
	v_pk_add_f32 v[24:25], v[24:25], v[116:117] neg_lo:[0,1] neg_hi:[0,1]
	v_pk_add_f32 v[26:27], v[26:27], v[116:117] neg_lo:[0,1] neg_hi:[0,1]
	v_pk_add_f32 v[28:29], v[28:29], v[116:117] neg_lo:[0,1] neg_hi:[0,1]
	v_pk_add_f32 v[30:31], v[30:31], v[116:117] neg_lo:[0,1] neg_hi:[0,1]
	v_pk_add_f32 v[32:33], v[32:33], v[116:117] neg_lo:[0,1] neg_hi:[0,1]
	v_pk_mul_f32 v[66:67], v[18:19], v[18:19]
	v_pk_mul_f32 v[68:69], v[20:21], v[20:21]
	v_pk_fma_f32 v[66:67], v[22:23], v[22:23], v[66:67]
	v_pk_fma_f32 v[68:69], v[24:25], v[24:25], v[68:69]
	v_pk_fma_f32 v[66:67], v[26:27], v[26:27], v[66:67]
	v_pk_fma_f32 v[68:69], v[28:29], v[28:29], v[68:69]
	v_pk_fma_f32 v[66:67], v[30:31], v[30:31], v[66:67]
	v_pk_fma_f32 v[68:69], v[32:33], v[32:33], v[68:69]
	v_pk_add_f32 v[66:67], v[66:67], v[68:69]
	v_add_f32_e32 v66, v66, v67
	s_nop 1
	v_add_f32_dpp v66, v66, v66 row_shr:1 row_mask:0xf bank_mask:0xf bound_ctrl:1
	s_nop 1
	v_add_f32_dpp v66, v66, v66 row_shr:2 row_mask:0xf bank_mask:0xf bound_ctrl:1
	s_nop 1
	v_add_f32_dpp v66, v66, v66 row_shr:4 row_mask:0xf bank_mask:0xf bound_ctrl:1
	s_nop 1
	v_add_f32_dpp v66, v66, v66 row_shr:8 row_mask:0xf bank_mask:0xf bound_ctrl:1
	s_nop 0
	v_readlane_b32 s9, v66, 15
	v_readlane_b32 s10, v66, 31
	v_readlane_b32 s11, v66, 47
	v_readlane_b32 vcc_lo, v66, 63
	s_nop 1
	v_mov_b32_e32 v66, s9
	v_add_f32_e32 v66, s10, v66
	v_add_f32_e32 v66, s11, v66
	v_add_f32_e32 v66, vcc_lo, v66
	v_mul_f32_e32 v66, 0x3a800000, v66
	v_add_f32_e32 v66, 0x3727c5ac, v66
	v_rsq_f32_e32 v118, v66
	s_nop 0
	v_mov_b32_e32 v119, v118
	v_pk_mul_f32 v[18:19], v[18:19], v[118:119]
	v_pk_mul_f32 v[20:21], v[20:21], v[118:119]
	v_pk_mul_f32 v[22:23], v[22:23], v[118:119]
	v_pk_mul_f32 v[24:25], v[24:25], v[118:119]
	v_pk_mul_f32 v[26:27], v[26:27], v[118:119]
	v_pk_mul_f32 v[28:29], v[28:29], v[118:119]
	v_pk_mul_f32 v[30:31], v[30:31], v[118:119]
	v_pk_mul_f32 v[32:33], v[32:33], v[118:119]
	v_pk_fma_f32 v[76:77], v[18:19], v[34:35], v[50:51]
	v_pk_fma_f32 v[78:79], v[20:21], v[36:37], v[52:53]
	v_pk_fma_f32 v[80:81], v[22:23], v[38:39], v[54:55]
	v_pk_fma_f32 v[82:83], v[24:25], v[40:41], v[56:57]
	v_pk_fma_f32 v[84:85], v[26:27], v[42:43], v[58:59]
	v_pk_fma_f32 v[86:87], v[28:29], v[44:45], v[60:61]
	v_pk_fma_f32 v[88:89], v[30:31], v[46:47], v[62:63]
	v_pk_fma_f32 v[90:91], v[32:33], v[48:49], v[64:65]
	v_cvt_pk_bf16_f32 v92, v76, v77
	v_cvt_pk_bf16_f32 v93, v78, v79
	v_cvt_pk_bf16_f32 v94, v80, v81
	v_cvt_pk_bf16_f32 v95, v82, v83
	v_cvt_pk_bf16_f32 v96, v84, v85
	v_cvt_pk_bf16_f32 v97, v86, v87
	v_cvt_pk_bf16_f32 v98, v88, v89
	v_cvt_pk_bf16_f32 v99, v90, v91
	global_store_dwordx2 v115, v[92:93], s[2:3] offset:0 sc1
	global_store_dwordx2 v115, v[94:95], s[2:3] offset:512 sc1
	global_store_dwordx2 v115, v[96:97], s[2:3] offset:1024 sc1
	global_store_dwordx2 v115, v[98:99], s[2:3] offset:1536 sc1
	s_add_u32 s2, s2, 0x400000
	s_addc_u32 s3, s3, 0
	s_add_u32 s0, s0, 0x800000
	s_addc_u32 s1, s1, 0
	global_load_dwordx4 v[18:21], v114, s[0:1] offset:0 nt
	global_load_dwordx4 v[22:25], v114, s[0:1] offset:1024 nt
	global_load_dwordx4 v[26:29], v114, s[0:1] offset:2048 nt
	global_load_dwordx4 v[30:33], v114, s[0:1] offset:3072 nt
	s_waitcnt vmcnt(16)
; __device__ __forceinline__ void phase_ln(float* R, const float* __restrict__ g, const float* __restrict__ b, bf16_t* xbf, float samp_scale, const float* __restrict__ part, int nsplit, bool f32_all) {
;     ...
;   for (int r = gw; r < MT; r += nw) {
;     float* row = R + (size_t)r * 1024;
;     f32x4 v[4];
; #pragma unroll
;     for (int i = 0; i < 4; ++i) v[i] = *(const f32x4*)(row + i * 256 + lane * 4);
;     if (r >= MP) {
;       for (int sp = 0; sp < nsplit; ++sp) {
;         const float* prow = part + ((size_t)sp * MS + (r - MP)) * 1024;
; #pragma unroll
;         for (int i = 0; i < 4; ++i) v[i] = v[i] + *(const f32x4*)(prow + i * 256 + lane * 4);
;       }
;     }
;     float s = 0.f;
; #pragma unroll
;     for (int i = 0; i < 4; ++i) s += v[i][0] + v[i][1] + v[i][2] + v[i][3];
; #pragma unroll
;     for (int o = 32; o >= 1; o >>= 1) s += __shfl_xor(s, o);
;     const float mean = s * (1.f / 1024.f);
;     float ss = 0.f;
; #pragma unroll
;     for (int i = 0; i < 4; ++i) { v[i] = v[i] - mean; ss += v[i][0] * v[i][0] + v[i][1] * v[i][1] + v[i][2] * v[i][2] + v[i][3] * v[i][3]; }
; #pragma unroll
;     for (int o = 32; o >= 1; o >>= 1) ss += __shfl_xor(ss, o);
;     const float rstd = rsqrtf(ss * (1.f / 1024.f) + LN_EPS);
; #pragma unroll
;     for (int i = 0; i < 4; ++i) {
;       const f32x4 y = v[i] * rstd * gv[i] + bv[i];
;       if (r >= MP) *(f32x4*)(row + i * 256 + lane * 4) = y * samp_scale;
;       else if (f32_all) *(f32x4*)(row + i * 256 + lane * 4) = y;
;       if (xbf) {
;         u32x2 wv;
;         wv[0] = cvt_pk_bf16(y[0], y[1]); wv[1] = cvt_pk_bf16(y[2], y[3]);
;         *(u32x2*)(xbf + (size_t)r * 1024 + i * 256 + lane * 4) = wv;
;       }
;     }
	v_pk_add_f32 v[66:67], v[122:123], v[124:125]
	v_pk_add_f32 v[68:69], v[126:127], v[128:129]
	v_pk_add_f32 v[70:71], v[130:131], v[132:133]
	v_pk_add_f32 v[72:73], v[134:135], v[136:137]
	v_pk_add_f32 v[66:67], v[66:67], v[68:69]
	v_pk_add_f32 v[70:71], v[70:71], v[72:73]
	v_pk_add_f32 v[66:67], v[66:67], v[70:71]
	v_add_f32_e32 v66, v66, v67
	s_nop 1
	v_add_f32_dpp v66, v66, v66 row_shr:1 row_mask:0xf bank_mask:0xf bound_ctrl:1
	s_nop 1
	v_add_f32_dpp v66, v66, v66 row_shr:2 row_mask:0xf bank_mask:0xf bound_ctrl:1
	s_nop 1
	v_add_f32_dpp v66, v66, v66 row_shr:4 row_mask:0xf bank_mask:0xf bound_ctrl:1
	s_nop 1
	v_add_f32_dpp v66, v66, v66 row_shr:8 row_mask:0xf bank_mask:0xf bound_ctrl:1
	s_nop 0
	v_readlane_b32 s9, v66, 15
	v_readlane_b32 s10, v66, 31
	v_readlane_b32 s11, v66, 47
	v_readlane_b32 vcc_lo, v66, 63
	s_nop 1
	v_mov_b32_e32 v66, s9
	v_add_f32_e32 v66, s10, v66
	v_add_f32_e32 v66, s11, v66
	v_add_f32_e32 v66, vcc_lo, v66
	v_mul_f32_e32 v116, 0x3a800000, v66
	v_mov_b32_e32 v117, v116
	v_pk_add_f32 v[122:123], v[122:123], v[116:117] neg_lo:[0,1] neg_hi:[0,1]
	v_pk_add_f32 v[124:125], v[124:125], v[116:117] neg_lo:[0,1] neg_hi:[0,1]
	v_pk_add_f32 v[126:127], v[126:127], v[116:117] neg_lo:[0,1] neg_hi:[0,1]
	v_pk_add_f32 v[128:129], v[128:129], v[116:117] neg_lo:[0,1] neg_hi:[0,1]
	v_pk_add_f32 v[130:131], v[130:131], v[116:117] neg_lo:[0,1] neg_hi:[0,1]
	v_pk_add_f32 v[132:133], v[132:133], v[116:117] neg_lo:[0,1] neg_hi:[0,1]
	v_pk_add_f32 v[134:135], v[134:135], v[116:117] neg_lo:[0,1] neg_hi:[0,1]
	v_pk_add_f32 v[136:137], v[136:137], v[116:117] neg_lo:[0,1] neg_hi:[0,1]
	v_pk_mul_f32 v[66:67], v[122:123], v[122:123]
	v_pk_mul_f32 v[68:69], v[124:125], v[124:125]
	v_pk_fma_f32 v[66:67], v[126:127], v[126:127], v[66:67]
	v_pk_fma_f32 v[68:69], v[128:129], v[128:129], v[68:69]
	v_pk_fma_f32 v[66:67], v[130:131], v[130:131], v[66:67]
	v_pk_fma_f32 v[68:69], v[132:133], v[132:133], v[68:69]
	v_pk_fma_f32 v[66:67], v[134:135], v[134:135], v[66:67]
	v_pk_fma_f32 v[68:69], v[136:137], v[136:137], v[68:69]
	v_pk_add_f32 v[66:67], v[66:67], v[68:69]
	v_add_f32_e32 v66, v66, v67
	s_nop 1
	v_add_f32_dpp v66, v66, v66 row_shr:1 row_mask:0xf bank_mask:0xf bound_ctrl:1
	s_nop 1
	v_add_f32_dpp v66, v66, v66 row_shr:2 row_mask:0xf bank_mask:0xf bound_ctrl:1
	s_nop 1
	v_add_f32_dpp v66, v66, v66 row_shr:4 row_mask:0xf bank_mask:0xf bound_ctrl:1
	s_nop 1
	v_add_f32_dpp v66, v66, v66 row_shr:8 row_mask:0xf bank_mask:0xf bound_ctrl:1
	s_nop 0
	v_readlane_b32 s9, v66, 15
	v_readlane_b32 s10, v66, 31
	v_readlane_b32 s11, v66, 47
	v_readlane_b32 vcc_lo, v66, 63
	s_nop 1
	v_mov_b32_e32 v66, s9
	v_add_f32_e32 v66, s10, v66
	v_add_f32_e32 v66, s11, v66
	v_add_f32_e32 v66, vcc_lo, v66
	v_mul_f32_e32 v66, 0x3a800000, v66
	v_add_f32_e32 v66, 0x3727c5ac, v66
	v_rsq_f32_e32 v118, v66
	s_nop 0
	v_mov_b32_e32 v119, v118
	v_pk_mul_f32 v[122:123], v[122:123], v[118:119]
	v_pk_mul_f32 v[124:125], v[124:125], v[118:119]
	v_pk_mul_f32 v[126:127], v[126:127], v[118:119]
	v_pk_mul_f32 v[128:129], v[128:129], v[118:119]
	v_pk_mul_f32 v[130:131], v[130:131], v[118:119]
	v_pk_mul_f32 v[132:133], v[132:133], v[118:119]
	v_pk_mul_f32 v[134:135], v[134:135], v[118:119]
	v_pk_mul_f32 v[136:137], v[136:137], v[118:119]
	v_pk_fma_f32 v[76:77], v[122:123], v[34:35], v[50:51]
	v_pk_fma_f32 v[78:79], v[124:125], v[36:37], v[52:53]
	v_pk_fma_f32 v[80:81], v[126:127], v[38:39], v[54:55]
	v_pk_fma_f32 v[82:83], v[128:129], v[40:41], v[56:57]
	v_pk_fma_f32 v[84:85], v[130:131], v[42:43], v[58:59]
	v_pk_fma_f32 v[86:87], v[132:133], v[44:45], v[60:61]
	v_pk_fma_f32 v[88:89], v[134:135], v[46:47], v[62:63]
	v_pk_fma_f32 v[90:91], v[136:137], v[48:49], v[64:65]
	v_cvt_pk_bf16_f32 v92, v76, v77
	v_cvt_pk_bf16_f32 v93, v78, v79
	v_cvt_pk_bf16_f32 v94, v80, v81
	v_cvt_pk_bf16_f32 v95, v82, v83
	v_cvt_pk_bf16_f32 v96, v84, v85
	v_cvt_pk_bf16_f32 v97, v86, v87
	v_cvt_pk_bf16_f32 v98, v88, v89
	v_cvt_pk_bf16_f32 v99, v90, v91
	global_store_dwordx2 v115, v[92:93], s[2:3] offset:0 sc1
	global_store_dwordx2 v115, v[94:95], s[2:3] offset:512 sc1
	global_store_dwordx2 v115, v[96:97], s[2:3] offset:1024 sc1
	global_store_dwordx2 v115, v[98:99], s[2:3] offset:1536 sc1
	s_add_u32 s2, s2, 0x400000
	s_addc_u32 s3, s3, 0
	s_add_u32 s0, s0, 0x800000
	s_addc_u32 s1, s1, 0
	global_load_dwordx4 v[122:125], v114, s[0:1] offset:0 nt
	global_load_dwordx4 v[126:129], v114, s[0:1] offset:1024 nt
	global_load_dwordx4 v[130:133], v114, s[0:1] offset:2048 nt
	global_load_dwordx4 v[134:137], v114, s[0:1] offset:3072 nt
	s_waitcnt vmcnt(16)
; __device__ __forceinline__ void phase_ln(float* R, const float* __restrict__ g, const float* __restrict__ b, bf16_t* xbf, float samp_scale, const float* __restrict__ part, int nsplit, bool f32_all) {
;     ...
;   for (int r = gw; r < MT; r += nw) {
;     float* row = R + (size_t)r * 1024;
;     f32x4 v[4];
; #pragma unroll
;     for (int i = 0; i < 4; ++i) v[i] = *(const f32x4*)(row + i * 256 + lane * 4);
;     if (r >= MP) {
;       for (int sp = 0; sp < nsplit; ++sp) {
;         const float* prow = part + ((size_t)sp * MS + (r - MP)) * 1024;
; #pragma unroll
;         for (int i = 0; i < 4; ++i) v[i] = v[i] + *(const f32x4*)(prow + i * 256 + lane * 4);
;       }
;     }
;     float s = 0.f;
; #pragma unroll
;     for (int i = 0; i < 4; ++i) s += v[i][0] + v[i][1] + v[i][2] + v[i][3];
; #pragma unroll
;     for (int o = 32; o >= 1; o >>= 1) s += __shfl_xor(s, o);
;     const float mean = s * (1.f / 1024.f);
;     float ss = 0.f;
; #pragma unroll
;     for (int i = 0; i < 4; ++i) { v[i] = v[i] - mean; ss += v[i][0] * v[i][0] + v[i][1] * v[i][1] + v[i][2] * v[i][2] + v[i][3] * v[i][3]; }
; #pragma unroll
;     for (int o = 32; o >= 1; o >>= 1) ss += __shfl_xor(ss, o);
;     const float rstd = rsqrtf(ss * (1.f / 1024.f) + LN_EPS);
; #pragma unroll
;     for (int i = 0; i < 4; ++i) {
;       const f32x4 y = v[i] * rstd * gv[i] + bv[i];
;       if (r >= MP) *(f32x4*)(row + i * 256 + lane * 4) = y * samp_scale;
;       else if (f32_all) *(f32x4*)(row + i * 256 + lane * 4) = y;
;       if (xbf) {
;         u32x2 wv;
;         wv[0] = cvt_pk_bf16(y[0], y[1]); wv[1] = cvt_pk_bf16(y[2], y[3]);
;         *(u32x2*)(xbf + (size_t)r * 1024 + i * 256 + lane * 4) = wv;
;       }
;     }
	v_pk_add_f32 v[66:67], v[0:1], v[2:3]
	v_pk_add_f32 v[68:69], v[4:5], v[6:7]
	v_pk_add_f32 v[70:71], v[8:9], v[10:11]
	v_pk_add_f32 v[72:73], v[12:13], v[14:15]
	v_pk_add_f32 v[66:67], v[66:67], v[68:69]
	v_pk_add_f32 v[70:71], v[70:71], v[72:73]
	v_pk_add_f32 v[66:67], v[66:67], v[70:71]
	v_add_f32_e32 v66, v66, v67
	s_nop 1
	v_add_f32_dpp v66, v66, v66 row_shr:1 row_mask:0xf bank_mask:0xf bound_ctrl:1
	s_nop 1
	v_add_f32_dpp v66, v66, v66 row_shr:2 row_mask:0xf bank_mask:0xf bound_ctrl:1
	s_nop 1
	v_add_f32_dpp v66, v66, v66 row_shr:4 row_mask:0xf bank_mask:0xf bound_ctrl:1
	s_nop 1
	v_add_f32_dpp v66, v66, v66 row_shr:8 row_mask:0xf bank_mask:0xf bound_ctrl:1
	s_nop 0
	v_readlane_b32 s9, v66, 15
	v_readlane_b32 s10, v66, 31
	v_readlane_b32 s11, v66, 47
	v_readlane_b32 vcc_lo, v66, 63
	s_nop 1
	v_mov_b32_e32 v66, s9
	v_add_f32_e32 v66, s10, v66
	v_add_f32_e32 v66, s11, v66
	v_add_f32_e32 v66, vcc_lo, v66
	v_mul_f32_e32 v116, 0x3a800000, v66
	v_mov_b32_e32 v117, v116
	v_pk_add_f32 v[0:1], v[0:1], v[116:117] neg_lo:[0,1] neg_hi:[0,1]
	v_pk_add_f32 v[2:3], v[2:3], v[116:117] neg_lo:[0,1] neg_hi:[0,1]
	v_pk_add_f32 v[4:5], v[4:5], v[116:117] neg_lo:[0,1] neg_hi:[0,1]
	v_pk_add_f32 v[6:7], v[6:7], v[116:117] neg_lo:[0,1] neg_hi:[0,1]
	v_pk_add_f32 v[8:9], v[8:9], v[116:117] neg_lo:[0,1] neg_hi:[0,1]
	v_pk_add_f32 v[10:11], v[10:11], v[116:117] neg_lo:[0,1] neg_hi:[0,1]
	v_pk_add_f32 v[12:13], v[12:13], v[116:117] neg_lo:[0,1] neg_hi:[0,1]
	v_pk_add_f32 v[14:15], v[14:15], v[116:117] neg_lo:[0,1] neg_hi:[0,1]
	v_pk_mul_f32 v[66:67], v[0:1], v[0:1]
	v_pk_mul_f32 v[68:69], v[2:3], v[2:3]
	v_pk_fma_f32 v[66:67], v[4:5], v[4:5], v[66:67]
	v_pk_fma_f32 v[68:69], v[6:7], v[6:7], v[68:69]
	v_pk_fma_f32 v[66:67], v[8:9], v[8:9], v[66:67]
	v_pk_fma_f32 v[68:69], v[10:11], v[10:11], v[68:69]
	v_pk_fma_f32 v[66:67], v[12:13], v[12:13], v[66:67]
	v_pk_fma_f32 v[68:69], v[14:15], v[14:15], v[68:69]
	v_pk_add_f32 v[66:67], v[66:67], v[68:69]
	v_add_f32_e32 v66, v66, v67
	s_nop 1
	v_add_f32_dpp v66, v66, v66 row_shr:1 row_mask:0xf bank_mask:0xf bound_ctrl:1
	s_nop 1
	v_add_f32_dpp v66, v66, v66 row_shr:2 row_mask:0xf bank_mask:0xf bound_ctrl:1
	s_nop 1
	v_add_f32_dpp v66, v66, v66 row_shr:4 row_mask:0xf bank_mask:0xf bound_ctrl:1
	s_nop 1
	v_add_f32_dpp v66, v66, v66 row_shr:8 row_mask:0xf bank_mask:0xf bound_ctrl:1
	s_nop 0
	v_readlane_b32 s9, v66, 15
	v_readlane_b32 s10, v66, 31
	v_readlane_b32 s11, v66, 47
	v_readlane_b32 vcc_lo, v66, 63
	s_nop 1
	v_mov_b32_e32 v66, s9
	v_add_f32_e32 v66, s10, v66
	v_add_f32_e32 v66, s11, v66
	v_add_f32_e32 v66, vcc_lo, v66
	v_mul_f32_e32 v66, 0x3a800000, v66
	v_add_f32_e32 v66, 0x3727c5ac, v66
	v_rsq_f32_e32 v118, v66
	s_nop 0
	v_mov_b32_e32 v119, v118
	v_pk_mul_f32 v[0:1], v[0:1], v[118:119]
	v_pk_mul_f32 v[2:3], v[2:3], v[118:119]
	v_pk_mul_f32 v[4:5], v[4:5], v[118:119]
	v_pk_mul_f32 v[6:7], v[6:7], v[118:119]
	v_pk_mul_f32 v[8:9], v[8:9], v[118:119]
	v_pk_mul_f32 v[10:11], v[10:11], v[118:119]
	v_pk_mul_f32 v[12:13], v[12:13], v[118:119]
	v_pk_mul_f32 v[14:15], v[14:15], v[118:119]
	v_pk_fma_f32 v[76:77], v[0:1], v[34:35], v[50:51]
	v_pk_fma_f32 v[78:79], v[2:3], v[36:37], v[52:53]
	v_pk_fma_f32 v[80:81], v[4:5], v[38:39], v[54:55]
	v_pk_fma_f32 v[82:83], v[6:7], v[40:41], v[56:57]
	v_pk_fma_f32 v[84:85], v[8:9], v[42:43], v[58:59]
	v_pk_fma_f32 v[86:87], v[10:11], v[44:45], v[60:61]
	v_pk_fma_f32 v[88:89], v[12:13], v[46:47], v[62:63]
	v_pk_fma_f32 v[90:91], v[14:15], v[48:49], v[64:65]
	v_cvt_pk_bf16_f32 v92, v76, v77
	v_cvt_pk_bf16_f32 v93, v78, v79
	v_cvt_pk_bf16_f32 v94, v80, v81
	v_cvt_pk_bf16_f32 v95, v82, v83
	v_cvt_pk_bf16_f32 v96, v84, v85
	v_cvt_pk_bf16_f32 v97, v86, v87
	v_cvt_pk_bf16_f32 v98, v88, v89
	v_cvt_pk_bf16_f32 v99, v90, v91
	global_store_dwordx2 v115, v[92:93], s[2:3] offset:0 sc1
	global_store_dwordx2 v115, v[94:95], s[2:3] offset:512 sc1
	global_store_dwordx2 v115, v[96:97], s[2:3] offset:1024 sc1
	global_store_dwordx2 v115, v[98:99], s[2:3] offset:1536 sc1
	s_add_u32 s2, s2, 0x400000
	s_addc_u32 s3, s3, 0
	s_add_u32 s0, s0, 0x800000
	s_addc_u32 s1, s1, 0
	global_load_dwordx4 v[0:3], v114, s[0:1] offset:0 nt
	global_load_dwordx4 v[4:7], v114, s[0:1] offset:1024 nt
	global_load_dwordx4 v[8:11], v114, s[0:1] offset:2048 nt
	global_load_dwordx4 v[12:15], v114, s[0:1] offset:3072 nt
	s_waitcnt vmcnt(16)
; __device__ __forceinline__ void phase_ln(float* R, const float* __restrict__ g, const float* __restrict__ b, bf16_t* xbf, float samp_scale, const float* __restrict__ part, int nsplit, bool f32_all) {
;     ...
;   for (int r = gw; r < MT; r += nw) {
;     float* row = R + (size_t)r * 1024;
;     f32x4 v[4];
; #pragma unroll
;     for (int i = 0; i < 4; ++i) v[i] = *(const f32x4*)(row + i * 256 + lane * 4);
;     if (r >= MP) {
;       for (int sp = 0; sp < nsplit; ++sp) {
;         const float* prow = part + ((size_t)sp * MS + (r - MP)) * 1024;
; #pragma unroll
;         for (int i = 0; i < 4; ++i) v[i] = v[i] + *(const f32x4*)(prow + i * 256 + lane * 4);
;       }
;     }
;     float s = 0.f;
; #pragma unroll
;     for (int i = 0; i < 4; ++i) s += v[i][0] + v[i][1] + v[i][2] + v[i][3];
; #pragma unroll
;     for (int o = 32; o >= 1; o >>= 1) s += __shfl_xor(s, o);
;     const float mean = s * (1.f / 1024.f);
;     float ss = 0.f;
; #pragma unroll
;     for (int i = 0; i < 4; ++i) { v[i] = v[i] - mean; ss += v[i][0] * v[i][0] + v[i][1] * v[i][1] + v[i][2] * v[i][2] + v[i][3] * v[i][3]; }
; #pragma unroll
;     for (int o = 32; o >= 1; o >>= 1) ss += __shfl_xor(ss, o);
;     const float rstd = rsqrtf(ss * (1.f / 1024.f) + LN_EPS);
; #pragma unroll
;     for (int i = 0; i < 4; ++i) {
;       const f32x4 y = v[i] * rstd * gv[i] + bv[i];
;       if (r >= MP) *(f32x4*)(row + i * 256 + lane * 4) = y * samp_scale;
;       else if (f32_all) *(f32x4*)(row + i * 256 + lane * 4) = y;
;       if (xbf) {
;         u32x2 wv;
;         wv[0] = cvt_pk_bf16(y[0], y[1]); wv[1] = cvt_pk_bf16(y[2], y[3]);
;         *(u32x2*)(xbf + (size_t)r * 1024 + i * 256 + lane * 4) = wv;
;       }
;     }
	v_pk_add_f32 v[66:67], v[18:19], v[20:21]
	v_pk_add_f32 v[68:69], v[22:23], v[24:25]
	v_pk_add_f32 v[70:71], v[26:27], v[28:29]
	v_pk_add_f32 v[72:73], v[30:31], v[32:33]
	v_pk_add_f32 v[66:67], v[66:67], v[68:69]
	v_pk_add_f32 v[70:71], v[70:71], v[72:73]
	v_pk_add_f32 v[66:67], v[66:67], v[70:71]
	v_add_f32_e32 v66, v66, v67
	s_nop 1
	v_add_f32_dpp v66, v66, v66 row_shr:1 row_mask:0xf bank_mask:0xf bound_ctrl:1
	s_nop 1
	v_add_f32_dpp v66, v66, v66 row_shr:2 row_mask:0xf bank_mask:0xf bound_ctrl:1
	s_nop 1
	v_add_f32_dpp v66, v66, v66 row_shr:4 row_mask:0xf bank_mask:0xf bound_ctrl:1
	s_nop 1
	v_add_f32_dpp v66, v66, v66 row_shr:8 row_mask:0xf bank_mask:0xf bound_ctrl:1
	s_nop 0
	v_readlane_b32 s9, v66, 15
	v_readlane_b32 s10, v66, 31
	v_readlane_b32 s11, v66, 47
	v_readlane_b32 vcc_lo, v66, 63
	s_nop 1
	v_mov_b32_e32 v66, s9
	v_add_f32_e32 v66, s10, v66
	v_add_f32_e32 v66, s11, v66
	v_add_f32_e32 v66, vcc_lo, v66
	v_mul_f32_e32 v116, 0x3a800000, v66
	v_mov_b32_e32 v117, v116
	v_pk_add_f32 v[18:19], v[18:19], v[116:117] neg_lo:[0,1] neg_hi:[0,1]
	v_pk_add_f32 v[20:21], v[20:21], v[116:117] neg_lo:[0,1] neg_hi:[0,1]
	v_pk_add_f32 v[22:23], v[22:23], v[116:117] neg_lo:[0,1] neg_hi:[0,1]
	v_pk_add_f32 v[24:25], v[24:25], v[116:117] neg_lo:[0,1] neg_hi:[0,1]
	v_pk_add_f32 v[26:27], v[26:27], v[116:117] neg_lo:[0,1] neg_hi:[0,1]
	v_pk_add_f32 v[28:29], v[28:29], v[116:117] neg_lo:[0,1] neg_hi:[0,1]
	v_pk_add_f32 v[30:31], v[30:31], v[116:117] neg_lo:[0,1] neg_hi:[0,1]
	v_pk_add_f32 v[32:33], v[32:33], v[116:117] neg_lo:[0,1] neg_hi:[0,1]
	v_pk_mul_f32 v[66:67], v[18:19], v[18:19]
	v_pk_mul_f32 v[68:69], v[20:21], v[20:21]
	v_pk_fma_f32 v[66:67], v[22:23], v[22:23], v[66:67]
	v_pk_fma_f32 v[68:69], v[24:25], v[24:25], v[68:69]
	v_pk_fma_f32 v[66:67], v[26:27], v[26:27], v[66:67]
	v_pk_fma_f32 v[68:69], v[28:29], v[28:29], v[68:69]
	v_pk_fma_f32 v[66:67], v[30:31], v[30:31], v[66:67]
	v_pk_fma_f32 v[68:69], v[32:33], v[32:33], v[68:69]
	v_pk_add_f32 v[66:67], v[66:67], v[68:69]
	v_add_f32_e32 v66, v66, v67
	s_nop 1
	v_add_f32_dpp v66, v66, v66 row_shr:1 row_mask:0xf bank_mask:0xf bound_ctrl:1
	s_nop 1
	v_add_f32_dpp v66, v66, v66 row_shr:2 row_mask:0xf bank_mask:0xf bound_ctrl:1
	s_nop 1
	v_add_f32_dpp v66, v66, v66 row_shr:4 row_mask:0xf bank_mask:0xf bound_ctrl:1
	s_nop 1
	v_add_f32_dpp v66, v66, v66 row_shr:8 row_mask:0xf bank_mask:0xf bound_ctrl:1
	s_nop 0
	v_readlane_b32 s9, v66, 15
	v_readlane_b32 s10, v66, 31
	v_readlane_b32 s11, v66, 47
	v_readlane_b32 vcc_lo, v66, 63
	s_nop 1
	v_mov_b32_e32 v66, s9
	v_add_f32_e32 v66, s10, v66
	v_add_f32_e32 v66, s11, v66
	v_add_f32_e32 v66, vcc_lo, v66
	v_mul_f32_e32 v66, 0x3a800000, v66
	v_add_f32_e32 v66, 0x3727c5ac, v66
	v_rsq_f32_e32 v118, v66
	s_nop 0
	v_mov_b32_e32 v119, v118
	v_pk_mul_f32 v[18:19], v[18:19], v[118:119]
	v_pk_mul_f32 v[20:21], v[20:21], v[118:119]
	v_pk_mul_f32 v[22:23], v[22:23], v[118:119]
	v_pk_mul_f32 v[24:25], v[24:25], v[118:119]
	v_pk_mul_f32 v[26:27], v[26:27], v[118:119]
	v_pk_mul_f32 v[28:29], v[28:29], v[118:119]
	v_pk_mul_f32 v[30:31], v[30:31], v[118:119]
	v_pk_mul_f32 v[32:33], v[32:33], v[118:119]
	v_pk_fma_f32 v[76:77], v[18:19], v[34:35], v[50:51]
	v_pk_fma_f32 v[78:79], v[20:21], v[36:37], v[52:53]
	v_pk_fma_f32 v[80:81], v[22:23], v[38:39], v[54:55]
	v_pk_fma_f32 v[82:83], v[24:25], v[40:41], v[56:57]
	v_pk_fma_f32 v[84:85], v[26:27], v[42:43], v[58:59]
	v_pk_fma_f32 v[86:87], v[28:29], v[44:45], v[60:61]
	v_pk_fma_f32 v[88:89], v[30:31], v[46:47], v[62:63]
	v_pk_fma_f32 v[90:91], v[32:33], v[48:49], v[64:65]
	v_cvt_pk_bf16_f32 v92, v76, v77
	v_cvt_pk_bf16_f32 v93, v78, v79
	v_cvt_pk_bf16_f32 v94, v80, v81
	v_cvt_pk_bf16_f32 v95, v82, v83
	v_cvt_pk_bf16_f32 v96, v84, v85
	v_cvt_pk_bf16_f32 v97, v86, v87
	v_cvt_pk_bf16_f32 v98, v88, v89
	v_cvt_pk_bf16_f32 v99, v90, v91
	global_store_dwordx2 v115, v[92:93], s[2:3] offset:0 sc1
	global_store_dwordx2 v115, v[94:95], s[2:3] offset:512 sc1
	global_store_dwordx2 v115, v[96:97], s[2:3] offset:1024 sc1
	global_store_dwordx2 v115, v[98:99], s[2:3] offset:1536 sc1
	s_add_u32 s2, s2, 0x400000
	s_addc_u32 s3, s3, 0
	s_waitcnt vmcnt(12)
	v_pk_add_f32 v[66:67], v[122:123], v[124:125]
	v_pk_add_f32 v[68:69], v[126:127], v[128:129]
	v_pk_add_f32 v[70:71], v[130:131], v[132:133]
	v_pk_add_f32 v[72:73], v[134:135], v[136:137]
	v_pk_add_f32 v[66:67], v[66:67], v[68:69]
	v_pk_add_f32 v[70:71], v[70:71], v[72:73]
	v_pk_add_f32 v[66:67], v[66:67], v[70:71]
	v_add_f32_e32 v66, v66, v67
	s_nop 1
	v_add_f32_dpp v66, v66, v66 row_shr:1 row_mask:0xf bank_mask:0xf bound_ctrl:1
	s_nop 1
	v_add_f32_dpp v66, v66, v66 row_shr:2 row_mask:0xf bank_mask:0xf bound_ctrl:1
	s_nop 1
	v_add_f32_dpp v66, v66, v66 row_shr:4 row_mask:0xf bank_mask:0xf bound_ctrl:1
	s_nop 1
	v_add_f32_dpp v66, v66, v66 row_shr:8 row_mask:0xf bank_mask:0xf bound_ctrl:1
	s_nop 0
	v_readlane_b32 s9, v66, 15
	v_readlane_b32 s10, v66, 31
	v_readlane_b32 s11, v66, 47
	v_readlane_b32 vcc_lo, v66, 63
	s_nop 1
	v_mov_b32_e32 v66, s9
	v_add_f32_e32 v66, s10, v66
	v_add_f32_e32 v66, s11, v66
	v_add_f32_e32 v66, vcc_lo, v66
	v_mul_f32_e32 v116, 0x3a800000, v66
	v_mov_b32_e32 v117, v116
	v_pk_add_f32 v[122:123], v[122:123], v[116:117] neg_lo:[0,1] neg_hi:[0,1]
	v_pk_add_f32 v[124:125], v[124:125], v[116:117] neg_lo:[0,1] neg_hi:[0,1]
	v_pk_add_f32 v[126:127], v[126:127], v[116:117] neg_lo:[0,1] neg_hi:[0,1]
	v_pk_add_f32 v[128:129], v[128:129], v[116:117] neg_lo:[0,1] neg_hi:[0,1]
	v_pk_add_f32 v[130:131], v[130:131], v[116:117] neg_lo:[0,1] neg_hi:[0,1]
	v_pk_add_f32 v[132:133], v[132:133], v[116:117] neg_lo:[0,1] neg_hi:[0,1]
	v_pk_add_f32 v[134:135], v[134:135], v[116:117] neg_lo:[0,1] neg_hi:[0,1]
; __device__ __forceinline__ void phase_ln(float* R, const float* __restrict__ g, const float* __restrict__ b, bf16_t* xbf, float samp_scale, const float* __restrict__ part, int nsplit, bool f32_all) {
;     ...
;   for (int r = gw; r < MT; r += nw) {
;     float* row = R + (size_t)r * 1024;
;     f32x4 v[4];
; #pragma unroll
;     for (int i = 0; i < 4; ++i) v[i] = *(const f32x4*)(row + i * 256 + lane * 4);
;     if (r >= MP) {
;       for (int sp = 0; sp < nsplit; ++sp) {
;         const float* prow = part + ((size_t)sp * MS + (r - MP)) * 1024;
; #pragma unroll
;         for (int i = 0; i < 4; ++i) v[i] = v[i] + *(const f32x4*)(prow + i * 256 + lane * 4);
;       }
;     }
;     float s = 0.f;
; #pragma unroll
;     for (int i = 0; i < 4; ++i) s += v[i][0] + v[i][1] + v[i][2] + v[i][3];
; #pragma unroll
;     for (int o = 32; o >= 1; o >>= 1) s += __shfl_xor(s, o);
;     const float mean = s * (1.f / 1024.f);
;     float ss = 0.f;
; #pragma unroll
;     for (int i = 0; i < 4; ++i) { v[i] = v[i] - mean; ss += v[i][0] * v[i][0] + v[i][1] * v[i][1] + v[i][2] * v[i][2] + v[i][3] * v[i][3]; }
; #pragma unroll
;     for (int o = 32; o >= 1; o >>= 1) ss += __shfl_xor(ss, o);
;     const float rstd = rsqrtf(ss * (1.f / 1024.f) + LN_EPS);
; #pragma unroll
;     for (int i = 0; i < 4; ++i) {
;       const f32x4 y = v[i] * rstd * gv[i] + bv[i];
;       if (r >= MP) *(f32x4*)(row + i * 256 + lane * 4) = y * samp_scale;
;       else if (f32_all) *(f32x4*)(row + i * 256 + lane * 4) = y;
;       if (xbf) {
;         u32x2 wv;
;         wv[0] = cvt_pk_bf16(y[0], y[1]); wv[1] = cvt_pk_bf16(y[2], y[3]);
;         *(u32x2*)(xbf + (size_t)r * 1024 + i * 256 + lane * 4) = wv;
;       }
;     }
	v_pk_add_f32 v[136:137], v[136:137], v[116:117] neg_lo:[0,1] neg_hi:[0,1]
	v_pk_mul_f32 v[66:67], v[122:123], v[122:123]
	v_pk_mul_f32 v[68:69], v[124:125], v[124:125]
	v_pk_fma_f32 v[66:67], v[126:127], v[126:127], v[66:67]
	v_pk_fma_f32 v[68:69], v[128:129], v[128:129], v[68:69]
	v_pk_fma_f32 v[66:67], v[130:131], v[130:131], v[66:67]
	v_pk_fma_f32 v[68:69], v[132:133], v[132:133], v[68:69]
	v_pk_fma_f32 v[66:67], v[134:135], v[134:135], v[66:67]
	v_pk_fma_f32 v[68:69], v[136:137], v[136:137], v[68:69]
	v_pk_add_f32 v[66:67], v[66:67], v[68:69]
	v_add_f32_e32 v66, v66, v67
	s_nop 1
	v_add_f32_dpp v66, v66, v66 row_shr:1 row_mask:0xf bank_mask:0xf bound_ctrl:1
	s_nop 1
	v_add_f32_dpp v66, v66, v66 row_shr:2 row_mask:0xf bank_mask:0xf bound_ctrl:1
	s_nop 1
	v_add_f32_dpp v66, v66, v66 row_shr:4 row_mask:0xf bank_mask:0xf bound_ctrl:1
	s_nop 1
	v_add_f32_dpp v66, v66, v66 row_shr:8 row_mask:0xf bank_mask:0xf bound_ctrl:1
	s_nop 0
	v_readlane_b32 s9, v66, 15
	v_readlane_b32 s10, v66, 31
	v_readlane_b32 s11, v66, 47
	v_readlane_b32 vcc_lo, v66, 63
	s_nop 1
	v_mov_b32_e32 v66, s9
	v_add_f32_e32 v66, s10, v66
	v_add_f32_e32 v66, s11, v66
	v_add_f32_e32 v66, vcc_lo, v66
	v_mul_f32_e32 v66, 0x3a800000, v66
	v_add_f32_e32 v66, 0x3727c5ac, v66
	v_rsq_f32_e32 v118, v66
	s_nop 0
	v_mov_b32_e32 v119, v118
	v_pk_mul_f32 v[122:123], v[122:123], v[118:119]
	v_pk_mul_f32 v[124:125], v[124:125], v[118:119]
	v_pk_mul_f32 v[126:127], v[126:127], v[118:119]
	v_pk_mul_f32 v[128:129], v[128:129], v[118:119]
	v_pk_mul_f32 v[130:131], v[130:131], v[118:119]
	v_pk_mul_f32 v[132:133], v[132:133], v[118:119]
	v_pk_mul_f32 v[134:135], v[134:135], v[118:119]
	v_pk_mul_f32 v[136:137], v[136:137], v[118:119]
	v_pk_fma_f32 v[76:77], v[122:123], v[34:35], v[50:51]
	v_pk_fma_f32 v[78:79], v[124:125], v[36:37], v[52:53]
	v_pk_fma_f32 v[80:81], v[126:127], v[38:39], v[54:55]
	v_pk_fma_f32 v[82:83], v[128:129], v[40:41], v[56:57]
	v_pk_fma_f32 v[84:85], v[130:131], v[42:43], v[58:59]
	v_pk_fma_f32 v[86:87], v[132:133], v[44:45], v[60:61]
	v_pk_fma_f32 v[88:89], v[134:135], v[46:47], v[62:63]
	v_pk_fma_f32 v[90:91], v[136:137], v[48:49], v[64:65]
	v_cvt_pk_bf16_f32 v92, v76, v77
	v_cvt_pk_bf16_f32 v93, v78, v79
	v_cvt_pk_bf16_f32 v94, v80, v81
	v_cvt_pk_bf16_f32 v95, v82, v83
	v_cvt_pk_bf16_f32 v96, v84, v85
	v_cvt_pk_bf16_f32 v97, v86, v87
	v_cvt_pk_bf16_f32 v98, v88, v89
	v_cvt_pk_bf16_f32 v99, v90, v91
	global_store_dwordx2 v115, v[92:93], s[2:3] offset:0 sc1
	global_store_dwordx2 v115, v[94:95], s[2:3] offset:512 sc1
	global_store_dwordx2 v115, v[96:97], s[2:3] offset:1024 sc1
	global_store_dwordx2 v115, v[98:99], s[2:3] offset:1536 sc1
	s_add_u32 s2, s2, 0x400000
	s_addc_u32 s3, s3, 0
	s_waitcnt vmcnt(8)
	v_pk_add_f32 v[66:67], v[0:1], v[2:3]
	v_pk_add_f32 v[68:69], v[4:5], v[6:7]
	v_pk_add_f32 v[70:71], v[8:9], v[10:11]
	v_pk_add_f32 v[72:73], v[12:13], v[14:15]
	v_pk_add_f32 v[66:67], v[66:67], v[68:69]
	v_pk_add_f32 v[70:71], v[70:71], v[72:73]
	v_pk_add_f32 v[66:67], v[66:67], v[70:71]
	v_add_f32_e32 v66, v66, v67
	s_nop 1
	v_add_f32_dpp v66, v66, v66 row_shr:1 row_mask:0xf bank_mask:0xf bound_ctrl:1
	s_nop 1
	v_add_f32_dpp v66, v66, v66 row_shr:2 row_mask:0xf bank_mask:0xf bound_ctrl:1
	s_nop 1
	v_add_f32_dpp v66, v66, v66 row_shr:4 row_mask:0xf bank_mask:0xf bound_ctrl:1
	s_nop 1
	v_add_f32_dpp v66, v66, v66 row_shr:8 row_mask:0xf bank_mask:0xf bound_ctrl:1
	s_nop 0
	v_readlane_b32 s9, v66, 15
	v_readlane_b32 s10, v66, 31
	v_readlane_b32 s11, v66, 47
	v_readlane_b32 vcc_lo, v66, 63
	s_nop 1
	v_mov_b32_e32 v66, s9
	v_add_f32_e32 v66, s10, v66
	v_add_f32_e32 v66, s11, v66
	v_add_f32_e32 v66, vcc_lo, v66
	v_mul_f32_e32 v116, 0x3a800000, v66
	v_mov_b32_e32 v117, v116
	v_pk_add_f32 v[0:1], v[0:1], v[116:117] neg_lo:[0,1] neg_hi:[0,1]
	v_pk_add_f32 v[2:3], v[2:3], v[116:117] neg_lo:[0,1] neg_hi:[0,1]
	v_pk_add_f32 v[4:5], v[4:5], v[116:117] neg_lo:[0,1] neg_hi:[0,1]
	v_pk_add_f32 v[6:7], v[6:7], v[116:117] neg_lo:[0,1] neg_hi:[0,1]
	v_pk_add_f32 v[8:9], v[8:9], v[116:117] neg_lo:[0,1] neg_hi:[0,1]
	v_pk_add_f32 v[10:11], v[10:11], v[116:117] neg_lo:[0,1] neg_hi:[0,1]
	v_pk_add_f32 v[12:13], v[12:13], v[116:117] neg_lo:[0,1] neg_hi:[0,1]
	v_pk_add_f32 v[14:15], v[14:15], v[116:117] neg_lo:[0,1] neg_hi:[0,1]
	v_pk_mul_f32 v[66:67], v[0:1], v[0:1]
	v_pk_mul_f32 v[68:69], v[2:3], v[2:3]
	v_pk_fma_f32 v[66:67], v[4:5], v[4:5], v[66:67]
	v_pk_fma_f32 v[68:69], v[6:7], v[6:7], v[68:69]
	v_pk_fma_f32 v[66:67], v[8:9], v[8:9], v[66:67]
	v_pk_fma_f32 v[68:69], v[10:11], v[10:11], v[68:69]
	v_pk_fma_f32 v[66:67], v[12:13], v[12:13], v[66:67]
	v_pk_fma_f32 v[68:69], v[14:15], v[14:15], v[68:69]
	v_pk_add_f32 v[66:67], v[66:67], v[68:69]
	v_add_f32_e32 v66, v66, v67
	s_nop 1
	v_add_f32_dpp v66, v66, v66 row_shr:1 row_mask:0xf bank_mask:0xf bound_ctrl:1
	s_nop 1
	v_add_f32_dpp v66, v66, v66 row_shr:2 row_mask:0xf bank_mask:0xf bound_ctrl:1
	s_nop 1
	v_add_f32_dpp v66, v66, v66 row_shr:4 row_mask:0xf bank_mask:0xf bound_ctrl:1
	s_nop 1
	v_add_f32_dpp v66, v66, v66 row_shr:8 row_mask:0xf bank_mask:0xf bound_ctrl:1
	s_nop 0
	v_readlane_b32 s9, v66, 15
	v_readlane_b32 s10, v66, 31
	v_readlane_b32 s11, v66, 47
	v_readlane_b32 vcc_lo, v66, 63
	s_nop 1
	v_mov_b32_e32 v66, s9
	v_add_f32_e32 v66, s10, v66
	v_add_f32_e32 v66, s11, v66
	v_add_f32_e32 v66, vcc_lo, v66
	v_mul_f32_e32 v66, 0x3a800000, v66
	v_add_f32_e32 v66, 0x3727c5ac, v66
	v_rsq_f32_e32 v118, v66
	s_nop 0
	v_mov_b32_e32 v119, v118
	v_pk_mul_f32 v[0:1], v[0:1], v[118:119]
	v_pk_mul_f32 v[2:3], v[2:3], v[118:119]
	v_pk_mul_f32 v[4:5], v[4:5], v[118:119]
	v_pk_mul_f32 v[6:7], v[6:7], v[118:119]
	v_pk_mul_f32 v[8:9], v[8:9], v[118:119]
	v_pk_mul_f32 v[10:11], v[10:11], v[118:119]
	v_pk_mul_f32 v[12:13], v[12:13], v[118:119]
	v_pk_mul_f32 v[14:15], v[14:15], v[118:119]
	v_pk_fma_f32 v[76:77], v[0:1], v[34:35], v[50:51]
	v_pk_fma_f32 v[78:79], v[2:3], v[36:37], v[52:53]
	v_pk_fma_f32 v[80:81], v[4:5], v[38:39], v[54:55]
	v_pk_fma_f32 v[82:83], v[6:7], v[40:41], v[56:57]
	v_pk_fma_f32 v[84:85], v[8:9], v[42:43], v[58:59]
	v_pk_fma_f32 v[86:87], v[10:11], v[44:45], v[60:61]
	v_pk_fma_f32 v[88:89], v[12:13], v[46:47], v[62:63]
	v_pk_fma_f32 v[90:91], v[14:15], v[48:49], v[64:65]
	v_cvt_pk_bf16_f32 v92, v76, v77
	v_cvt_pk_bf16_f32 v93, v78, v79
	v_cvt_pk_bf16_f32 v94, v80, v81
	v_cvt_pk_bf16_f32 v95, v82, v83
	v_cvt_pk_bf16_f32 v96, v84, v85
	v_cvt_pk_bf16_f32 v97, v86, v87
	v_cvt_pk_bf16_f32 v98, v88, v89
	v_cvt_pk_bf16_f32 v99, v90, v91
	global_store_dwordx2 v115, v[92:93], s[2:3] offset:0 sc1
	global_store_dwordx2 v115, v[94:95], s[2:3] offset:512 sc1
	global_store_dwordx2 v115, v[96:97], s[2:3] offset:1024 sc1
	global_store_dwordx2 v115, v[98:99], s[2:3] offset:1536 sc1
	s_add_u32 s2, s2, 0x400000
	s_addc_u32 s3, s3, 0
	v_readfirstlane_b32 s10, v244
	v_readlane_b32 s9, v254, 6
	s_lshr_b32 s10, s10, 6
	s_cmp_ge_u32 s10, 2
	s_cbranch_scc1 .Lln1_done
; __device__ __forceinline__ void phase_ln(float* R, const float* __restrict__ g, const float* __restrict__ b, bf16_t* xbf, float samp_scale, const float* __restrict__ part, int nsplit, bool f32_all) {
;     ...
;   for (int r = gw; r < MT; r += nw) {
;     float* row = R + (size_t)r * 1024;
;     f32x4 v[4];
; #pragma unroll
;     for (int i = 0; i < 4; ++i) v[i] = *(const f32x4*)(row + i * 256 + lane * 4);
;     if (r >= MP) {
;       for (int sp = 0; sp < nsplit; ++sp) {
;         const float* prow = part + ((size_t)sp * MS + (r - MP)) * 1024;
; #pragma unroll
;         for (int i = 0; i < 4; ++i) v[i] = v[i] + *(const f32x4*)(prow + i * 256 + lane * 4);
;       }
;     }
	s_lshl_b32 s9, s9, 1
	s_add_i32 s9, s9, s10
	s_lshl_b32 s11, s9, 12
	s_add_u32 s11, s11, 0x8000000
	s_add_u32 s0, s4, s11
	s_addc_u32 s1, s5, 0
	s_lshl_b32 s11, s9, 11
	s_add_u32 s11, s11, 0x79c0000
	s_add_u32 s2, s6, s11
	s_addc_u32 s3, s7, 0
	s_lshl_b32 s11, s9, 12
	s_add_u32 s11, s11, 0x1e482000
	s_add_u32 s10, s6, s11
	s_addc_u32 s11, s7, 0
	global_load_dwordx4 v[0:3], v114, s[0:1] offset:0 nt
	global_load_dwordx4 v[4:7], v114, s[0:1] offset:1024 nt
	global_load_dwordx4 v[8:11], v114, s[0:1] offset:2048 nt
	global_load_dwordx4 v[12:15], v114, s[0:1] offset:3072 nt
	global_load_dwordx4 v[18:21], v114, s[10:11] offset:0 nt
	global_load_dwordx4 v[22:25], v114, s[10:11] offset:1024 nt
	global_load_dwordx4 v[26:29], v114, s[10:11] offset:2048 nt
	global_load_dwordx4 v[30:33], v114, s[10:11] offset:3072 nt
	s_add_u32 s10, s10, 0x200000
	s_addc_u32 s11, s11, 0
	global_load_dwordx4 v[66:69], v114, s[10:11] offset:0 nt
	global_load_dwordx4 v[70:73], v114, s[10:11] offset:1024 nt
	global_load_dwordx4 v[74:77], v114, s[10:11] offset:2048 nt
	global_load_dwordx4 v[78:81], v114, s[10:11] offset:3072 nt
	s_add_u32 s10, s10, 0x200000
	s_addc_u32 s11, s11, 0
	global_load_dwordx4 v[82:85], v114, s[10:11] offset:0 nt
	global_load_dwordx4 v[86:89], v114, s[10:11] offset:1024 nt
	global_load_dwordx4 v[90:93], v114, s[10:11] offset:2048 nt
	global_load_dwordx4 v[94:97], v114, s[10:11] offset:3072 nt
	s_add_u32 s10, s10, 0x200000
	s_addc_u32 s11, s11, 0
	global_load_dwordx4 v[98:101], v114, s[10:11] offset:0 nt
	global_load_dwordx4 v[102:105], v114, s[10:11] offset:1024 nt
	global_load_dwordx4 v[106:109], v114, s[10:11] offset:2048 nt
	global_load_dwordx4 v[110:113], v114, s[10:11] offset:3072 nt
	s_add_u32 s10, s10, 0x200000
	s_addc_u32 s11, s11, 0
	s_waitcnt vmcnt(0)
; __device__ __forceinline__ void phase_ln(float* R, const float* __restrict__ g, const float* __restrict__ b, bf16_t* xbf, float samp_scale, const float* __restrict__ part, int nsplit, bool f32_all) {
;     ...
;     if (r >= MP) {
;       for (int sp = 0; sp < nsplit; ++sp) {
;         const float* prow = part + ((size_t)sp * MS + (r - MP)) * 1024;
; #pragma unroll
;         for (int i = 0; i < 4; ++i) v[i] = v[i] + *(const f32x4*)(prow + i * 256 + lane * 4);
;       }
;     }
;     float s = 0.f;
; #pragma unroll
;     for (int i = 0; i < 4; ++i) s += v[i][0] + v[i][1] + v[i][2] + v[i][3];
; #pragma unroll
;     for (int o = 32; o >= 1; o >>= 1) s += __shfl_xor(s, o);
;     const float mean = s * (1.f / 1024.f);
;     float ss = 0.f;
; #pragma unroll
;     for (int i = 0; i < 4; ++i) { v[i] = v[i] - mean; ss += v[i][0] * v[i][0] + v[i][1] * v[i][1] + v[i][2] * v[i][2] + v[i][3] * v[i][3]; }
; #pragma unroll
;     for (int o = 32; o >= 1; o >>= 1) ss += __shfl_xor(ss, o);
;     const float rstd = rsqrtf(ss * (1.f / 1024.f) + LN_EPS);
; #pragma unroll
;     for (int i = 0; i < 4; ++i) {
;       const f32x4 y = v[i] * rstd * gv[i] + bv[i];
;       if (r >= MP) *(f32x4*)(row + i * 256 + lane * 4) = y * samp_scale;
;       else if (f32_all) *(f32x4*)(row + i * 256 + lane * 4) = y;
;       if (xbf) {
;         u32x2 wv;
;         wv[0] = cvt_pk_bf16(y[0], y[1]); wv[1] = cvt_pk_bf16(y[2], y[3]);
;         *(u32x2*)(xbf + (size_t)r * 1024 + i * 256 + lane * 4) = wv;
;       }
;     }
	v_pk_add_f32 v[0:1], v[0:1], v[18:19]
	v_pk_add_f32 v[2:3], v[2:3], v[20:21]
	v_pk_add_f32 v[4:5], v[4:5], v[22:23]
	v_pk_add_f32 v[6:7], v[6:7], v[24:25]
	v_pk_add_f32 v[8:9], v[8:9], v[26:27]
	v_pk_add_f32 v[10:11], v[10:11], v[28:29]
	v_pk_add_f32 v[12:13], v[12:13], v[30:31]
	v_pk_add_f32 v[14:15], v[14:15], v[32:33]
	v_pk_add_f32 v[0:1], v[0:1], v[66:67]
	v_pk_add_f32 v[2:3], v[2:3], v[68:69]
	v_pk_add_f32 v[4:5], v[4:5], v[70:71]
	v_pk_add_f32 v[6:7], v[6:7], v[72:73]
	v_pk_add_f32 v[8:9], v[8:9], v[74:75]
	v_pk_add_f32 v[10:11], v[10:11], v[76:77]
	v_pk_add_f32 v[12:13], v[12:13], v[78:79]
	v_pk_add_f32 v[14:15], v[14:15], v[80:81]
	v_pk_add_f32 v[0:1], v[0:1], v[82:83]
	v_pk_add_f32 v[2:3], v[2:3], v[84:85]
	v_pk_add_f32 v[4:5], v[4:5], v[86:87]
	v_pk_add_f32 v[6:7], v[6:7], v[88:89]
	v_pk_add_f32 v[8:9], v[8:9], v[90:91]
	v_pk_add_f32 v[10:11], v[10:11], v[92:93]
	v_pk_add_f32 v[12:13], v[12:13], v[94:95]
	v_pk_add_f32 v[14:15], v[14:15], v[96:97]
	v_pk_add_f32 v[0:1], v[0:1], v[98:99]
	v_pk_add_f32 v[2:3], v[2:3], v[100:101]
	v_pk_add_f32 v[4:5], v[4:5], v[102:103]
	v_pk_add_f32 v[6:7], v[6:7], v[104:105]
	v_pk_add_f32 v[8:9], v[8:9], v[106:107]
	v_pk_add_f32 v[10:11], v[10:11], v[108:109]
	v_pk_add_f32 v[12:13], v[12:13], v[110:111]
	v_pk_add_f32 v[14:15], v[14:15], v[112:113]
	v_pk_add_f32 v[66:67], v[0:1], v[2:3]
	v_pk_add_f32 v[68:69], v[4:5], v[6:7]
	v_pk_add_f32 v[70:71], v[8:9], v[10:11]
	v_pk_add_f32 v[72:73], v[12:13], v[14:15]
	v_pk_add_f32 v[66:67], v[66:67], v[68:69]
	v_pk_add_f32 v[70:71], v[70:71], v[72:73]
	v_pk_add_f32 v[66:67], v[66:67], v[70:71]
	v_add_f32_e32 v66, v66, v67
	s_nop 1
	v_add_f32_dpp v66, v66, v66 row_shr:1 row_mask:0xf bank_mask:0xf bound_ctrl:1
	s_nop 1
	v_add_f32_dpp v66, v66, v66 row_shr:2 row_mask:0xf bank_mask:0xf bound_ctrl:1
	s_nop 1
	v_add_f32_dpp v66, v66, v66 row_shr:4 row_mask:0xf bank_mask:0xf bound_ctrl:1
	s_nop 1
	v_add_f32_dpp v66, v66, v66 row_shr:8 row_mask:0xf bank_mask:0xf bound_ctrl:1
	s_nop 0
	v_readlane_b32 s9, v66, 15
	v_readlane_b32 s10, v66, 31
	v_readlane_b32 s11, v66, 47
	v_readlane_b32 vcc_lo, v66, 63
	s_nop 1
	v_mov_b32_e32 v66, s9
	v_add_f32_e32 v66, s10, v66
	v_add_f32_e32 v66, s11, v66
	v_add_f32_e32 v66, vcc_lo, v66
	v_mul_f32_e32 v116, 0x3a800000, v66
	v_mov_b32_e32 v117, v116
	v_pk_add_f32 v[0:1], v[0:1], v[116:117] neg_lo:[0,1] neg_hi:[0,1]
	v_pk_add_f32 v[2:3], v[2:3], v[116:117] neg_lo:[0,1] neg_hi:[0,1]
	v_pk_add_f32 v[4:5], v[4:5], v[116:117] neg_lo:[0,1] neg_hi:[0,1]
	v_pk_add_f32 v[6:7], v[6:7], v[116:117] neg_lo:[0,1] neg_hi:[0,1]
	v_pk_add_f32 v[8:9], v[8:9], v[116:117] neg_lo:[0,1] neg_hi:[0,1]
	v_pk_add_f32 v[10:11], v[10:11], v[116:117] neg_lo:[0,1] neg_hi:[0,1]
	v_pk_add_f32 v[12:13], v[12:13], v[116:117] neg_lo:[0,1] neg_hi:[0,1]
	v_pk_add_f32 v[14:15], v[14:15], v[116:117] neg_lo:[0,1] neg_hi:[0,1]
	v_pk_mul_f32 v[66:67], v[0:1], v[0:1]
	v_pk_mul_f32 v[68:69], v[2:3], v[2:3]
	v_pk_fma_f32 v[66:67], v[4:5], v[4:5], v[66:67]
	v_pk_fma_f32 v[68:69], v[6:7], v[6:7], v[68:69]
	v_pk_fma_f32 v[66:67], v[8:9], v[8:9], v[66:67]
	v_pk_fma_f32 v[68:69], v[10:11], v[10:11], v[68:69]
	v_pk_fma_f32 v[66:67], v[12:13], v[12:13], v[66:67]
	v_pk_fma_f32 v[68:69], v[14:15], v[14:15], v[68:69]
	v_pk_add_f32 v[66:67], v[66:67], v[68:69]
	v_add_f32_e32 v66, v66, v67
	s_nop 1
	v_add_f32_dpp v66, v66, v66 row_shr:1 row_mask:0xf bank_mask:0xf bound_ctrl:1
	s_nop 1
	v_add_f32_dpp v66, v66, v66 row_shr:2 row_mask:0xf bank_mask:0xf bound_ctrl:1
	s_nop 1
	v_add_f32_dpp v66, v66, v66 row_shr:4 row_mask:0xf bank_mask:0xf bound_ctrl:1
	s_nop 1
	v_add_f32_dpp v66, v66, v66 row_shr:8 row_mask:0xf bank_mask:0xf bound_ctrl:1
	s_nop 0
	v_readlane_b32 s9, v66, 15
	v_readlane_b32 s10, v66, 31
	v_readlane_b32 s11, v66, 47
	v_readlane_b32 vcc_lo, v66, 63
	s_nop 1
	v_mov_b32_e32 v66, s9
	v_add_f32_e32 v66, s10, v66
	v_add_f32_e32 v66, s11, v66
	v_add_f32_e32 v66, vcc_lo, v66
	v_mul_f32_e32 v66, 0x3a800000, v66
	v_add_f32_e32 v66, 0x3727c5ac, v66
	v_rsq_f32_e32 v118, v66
	s_nop 0
	v_mov_b32_e32 v119, v118
	v_pk_mul_f32 v[0:1], v[0:1], v[118:119]
	v_pk_mul_f32 v[2:3], v[2:3], v[118:119]
	v_pk_mul_f32 v[4:5], v[4:5], v[118:119]
	v_pk_mul_f32 v[6:7], v[6:7], v[118:119]
	v_pk_mul_f32 v[8:9], v[8:9], v[118:119]
	v_pk_mul_f32 v[10:11], v[10:11], v[118:119]
	v_pk_mul_f32 v[12:13], v[12:13], v[118:119]
	v_pk_mul_f32 v[14:15], v[14:15], v[118:119]
	v_pk_fma_f32 v[76:77], v[0:1], v[34:35], v[50:51]
	v_pk_fma_f32 v[78:79], v[2:3], v[36:37], v[52:53]
	v_pk_fma_f32 v[80:81], v[4:5], v[38:39], v[54:55]
	v_pk_fma_f32 v[82:83], v[6:7], v[40:41], v[56:57]
	v_pk_fma_f32 v[84:85], v[8:9], v[42:43], v[58:59]
	v_pk_fma_f32 v[86:87], v[10:11], v[44:45], v[60:61]
	v_pk_fma_f32 v[88:89], v[12:13], v[46:47], v[62:63]
	v_pk_fma_f32 v[90:91], v[14:15], v[48:49], v[64:65]
	s_mov_b32 s9, 0x3fb504f3
	v_mov_b32_e32 v120, s9
	v_mov_b32_e32 v121, s9
	v_pk_mul_f32 v[0:1], v[76:77], v[120:121]
	v_pk_mul_f32 v[2:3], v[78:79], v[120:121]
	v_pk_mul_f32 v[4:5], v[80:81], v[120:121]
	v_pk_mul_f32 v[6:7], v[82:83], v[120:121]
	v_pk_mul_f32 v[8:9], v[84:85], v[120:121]
	v_pk_mul_f32 v[10:11], v[86:87], v[120:121]
	v_pk_mul_f32 v[12:13], v[88:89], v[120:121]
	v_pk_mul_f32 v[14:15], v[90:91], v[120:121]
	global_store_dwordx4 v114, v[0:3], s[0:1] offset:0 sc1
	global_store_dwordx4 v114, v[4:7], s[0:1] offset:1024 sc1
	global_store_dwordx4 v114, v[8:11], s[0:1] offset:2048 sc1
	global_store_dwordx4 v114, v[12:15], s[0:1] offset:3072 sc1
	v_cvt_pk_bf16_f32 v92, v76, v77
	v_cvt_pk_bf16_f32 v93, v78, v79
	v_cvt_pk_bf16_f32 v94, v80, v81
	v_cvt_pk_bf16_f32 v95, v82, v83
	v_cvt_pk_bf16_f32 v96, v84, v85
	v_cvt_pk_bf16_f32 v97, v86, v87
	v_cvt_pk_bf16_f32 v98, v88, v89
	v_cvt_pk_bf16_f32 v99, v90, v91
	global_store_dwordx2 v115, v[92:93], s[2:3] offset:0 sc1
	global_store_dwordx2 v115, v[94:95], s[2:3] offset:512 sc1
	global_store_dwordx2 v115, v[96:97], s[2:3] offset:1024 sc1
	global_store_dwordx2 v115, v[98:99], s[2:3] offset:1536 sc1

; __device__ __forceinline__ int otid() { int t = threadIdx.x; asm volatile("" : "+v"(t)); return t; }
; __device__ __forceinline__ void phase_ln(float* R, const float* __restrict__ g, const float* __restrict__ b, bf16_t* xbf, float samp_scale, const float* __restrict__ part, int nsplit, bool f32_all) {
;   const int tid = otid(), lane = tid & 63, gw = blockIdx.x * 8 + (tid >> 6), nw = gridDim.x * 8;
;   f32x4 gv[4], bv[4];
; #pragma unroll
;   for (int i = 0; i < 4; ++i) { gv[i] = *(const f32x4*)(g + i * 256 + lane * 4); bv[i] = *(const f32x4*)(b + i * 256 + lane * 4); }
;   for (int r = gw; r < MT; r += nw) {
;     float* row = R + (size_t)r * 1024;
;     f32x4 v[4];
; #pragma unroll
;     for (int i = 0; i < 4; ++i) v[i] = *(const f32x4*)(row + i * 256 + lane * 4);
;     if (r >= MP) {
;       for (int sp = 0; sp < nsplit; ++sp) {
;         const float* prow = part + ((size_t)sp * MS + (r - MP)) * 1024;
; #pragma unroll
;         for (int i = 0; i < 4; ++i) v[i] = v[i] + *(const f32x4*)(prow + i * 256 + lane * 4);
;       }
;     }
;     float s = 0.f;
; #pragma unroll
;     for (int i = 0; i < 4; ++i) s += v[i][0] + v[i][1] + v[i][2] + v[i][3];
; #pragma unroll
;     for (int o = 32; o >= 1; o >>= 1) s += __shfl_xor(s, o);
;     const float mean = s * (1.f / 1024.f);
;     float ss = 0.f;
; #pragma unroll
;     for (int i = 0; i < 4; ++i) { v[i] = v[i] - mean; ss += v[i][0] * v[i][0] + v[i][1] * v[i][1] + v[i][2] * v[i][2] + v[i][3] * v[i][3]; }
; #pragma unroll
;     for (int o = 32; o >= 1; o >>= 1) ss += __shfl_xor(ss, o);
;     const float rstd = rsqrtf(ss * (1.f / 1024.f) + LN_EPS);
; #pragma unroll
;     for (int i = 0; i < 4; ++i) {
;       const f32x4 y = v[i] * rstd * gv[i] + bv[i];
;       if (r >= MP) *(f32x4*)(row + i * 256 + lane * 4) = y * samp_scale;
;       else if (f32_all) *(f32x4*)(row + i * 256 + lane * 4) = y;
;       if (xbf) {
;         u32x2 wv;
;         wv[0] = cvt_pk_bf16(y[0], y[1]); wv[1] = cvt_pk_bf16(y[2], y[3]);
;         *(u32x2*)(xbf + (size_t)r * 1024 + i * 256 + lane * 4) = wv;
;       }
;     }
.LBB0_3944:
	s_or_b64 exec, exec, s[0:1]
	v_readlane_b32 s0, v254, 51
	s_nop 0
	s_cmp_lg_u32 s0, 0
	s_cbranch_scc1 .Lln2_orig
	v_readlane_b32 s6, v254, 2
	v_readlane_b32 s7, v254, 3
	v_readlane_b32 s8, v255, 22
	s_waitcnt lgkmcnt(0)
	s_barrier
	s_load_dwordx4 s[0:3], s[6:7], 0x98
	s_load_dwordx4 s[4:7], s[6:7], 0xa8
	v_readlane_b32 s9, v254, 15
	v_readfirstlane_b32 s10, v244
	v_lshlrev_b32_e32 v114, 4, v252
	v_lshlrev_b32_e32 v115, 3, v252
	s_lshr_b32 s10, s10, 6
	s_add_i32 s9, s9, s10
	s_lshl_b32 s11, s8, 12
	s_waitcnt lgkmcnt(0)
	s_add_u32 s0, s0, s11
	s_addc_u32 s1, s1, 0
	s_add_u32 s2, s2, s11
	s_addc_u32 s3, s3, 0
	global_load_dwordx4 v[34:37], v114, s[0:1] offset:0 nt
	global_load_dwordx4 v[38:41], v114, s[0:1] offset:1024 nt
	global_load_dwordx4 v[42:45], v114, s[0:1] offset:2048 nt
	global_load_dwordx4 v[46:49], v114, s[0:1] offset:3072 nt
	global_load_dwordx4 v[50:53], v114, s[2:3] offset:0
	global_load_dwordx4 v[54:57], v114, s[2:3] offset:1024
	global_load_dwordx4 v[58:61], v114, s[2:3] offset:2048
	global_load_dwordx4 v[62:65], v114, s[2:3] offset:3072
	s_lshl_b32 s11, s9, 12
	s_add_u32 s0, s4, s11
	s_addc_u32 s1, s5, 0
	s_lshl_b32 s11, s9, 11
	s_add_u32 s11, s11, 0x39c0000
	s_add_u32 s2, s6, s11
	s_addc_u32 s3, s7, 0
	global_load_dwordx4 v[0:3], v114, s[0:1] offset:0 nt
	global_load_dwordx4 v[4:7], v114, s[0:1] offset:1024 nt
	global_load_dwordx4 v[8:11], v114, s[0:1] offset:2048 nt
	global_load_dwordx4 v[12:15], v114, s[0:1] offset:3072 nt
	s_add_u32 s0, s0, 0x800000
	s_addc_u32 s1, s1, 0
	global_load_dwordx4 v[18:21], v114, s[0:1] offset:0 nt
	global_load_dwordx4 v[22:25], v114, s[0:1] offset:1024 nt
	global_load_dwordx4 v[26:29], v114, s[0:1] offset:2048 nt
	global_load_dwordx4 v[30:33], v114, s[0:1] offset:3072 nt
	s_add_u32 s0, s0, 0x800000
	s_addc_u32 s1, s1, 0
	global_load_dwordx4 v[122:125], v114, s[0:1] offset:0 nt
	global_load_dwordx4 v[126:129], v114, s[0:1] offset:1024 nt
	global_load_dwordx4 v[130:133], v114, s[0:1] offset:2048 nt
	global_load_dwordx4 v[134:137], v114, s[0:1] offset:3072 nt
	s_waitcnt vmcnt(8)
	v_pk_add_f32 v[66:67], v[0:1], v[2:3]
	v_pk_add_f32 v[68:69], v[4:5], v[6:7]
	v_pk_add_f32 v[70:71], v[8:9], v[10:11]
	v_pk_add_f32 v[72:73], v[12:13], v[14:15]
	v_pk_add_f32 v[66:67], v[66:67], v[68:69]
	v_pk_add_f32 v[70:71], v[70:71], v[72:73]
	v_pk_add_f32 v[66:67], v[66:67], v[70:71]
	v_add_f32_e32 v66, v66, v67
	s_nop 1
	v_add_f32_dpp v66, v66, v66 row_shr:1 row_mask:0xf bank_mask:0xf bound_ctrl:1
	s_nop 1
	v_add_f32_dpp v66, v66, v66 row_shr:2 row_mask:0xf bank_mask:0xf bound_ctrl:1
	s_nop 1
	v_add_f32_dpp v66, v66, v66 row_shr:4 row_mask:0xf bank_mask:0xf bound_ctrl:1
	s_nop 1
	v_add_f32_dpp v66, v66, v66 row_shr:8 row_mask:0xf bank_mask:0xf bound_ctrl:1
	s_nop 0
	v_readlane_b32 s9, v66, 15
	v_readlane_b32 s10, v66, 31
	v_readlane_b32 s11, v66, 47
	v_readlane_b32 vcc_lo, v66, 63
	s_nop 1
	v_mov_b32_e32 v66, s9
	v_add_f32_e32 v66, s10, v66
	v_add_f32_e32 v66, s11, v66
	v_add_f32_e32 v66, vcc_lo, v66
	v_mul_f32_e32 v116, 0x3a800000, v66
	v_mov_b32_e32 v117, v116
	v_pk_add_f32 v[0:1], v[0:1], v[116:117] neg_lo:[0,1] neg_hi:[0,1]
	v_pk_add_f32 v[2:3], v[2:3], v[116:117] neg_lo:[0,1] neg_hi:[0,1]
	v_pk_add_f32 v[4:5], v[4:5], v[116:117] neg_lo:[0,1] neg_hi:[0,1]
	v_pk_add_f32 v[6:7], v[6:7], v[116:117] neg_lo:[0,1] neg_hi:[0,1]
	v_pk_add_f32 v[8:9], v[8:9], v[116:117] neg_lo:[0,1] neg_hi:[0,1]
	v_pk_add_f32 v[10:11], v[10:11], v[116:117] neg_lo:[0,1] neg_hi:[0,1]
	v_pk_add_f32 v[12:13], v[12:13], v[116:117] neg_lo:[0,1] neg_hi:[0,1]
	v_pk_add_f32 v[14:15], v[14:15], v[116:117] neg_lo:[0,1] neg_hi:[0,1]
	v_pk_mul_f32 v[66:67], v[0:1], v[0:1]
	v_pk_mul_f32 v[68:69], v[2:3], v[2:3]
	v_pk_fma_f32 v[66:67], v[4:5], v[4:5], v[66:67]
	v_pk_fma_f32 v[68:69], v[6:7], v[6:7], v[68:69]
	v_pk_fma_f32 v[66:67], v[8:9], v[8:9], v[66:67]
	v_pk_fma_f32 v[68:69], v[10:11], v[10:11], v[68:69]
	v_pk_fma_f32 v[66:67], v[12:13], v[12:13], v[66:67]
	v_pk_fma_f32 v[68:69], v[14:15], v[14:15], v[68:69]
	v_pk_add_f32 v[66:67], v[66:67], v[68:69]
	v_add_f32_e32 v66, v66, v67
	s_nop 1
	v_add_f32_dpp v66, v66, v66 row_shr:1 row_mask:0xf bank_mask:0xf bound_ctrl:1
	s_nop 1
	v_add_f32_dpp v66, v66, v66 row_shr:2 row_mask:0xf bank_mask:0xf bound_ctrl:1
	s_nop 1
	v_add_f32_dpp v66, v66, v66 row_shr:4 row_mask:0xf bank_mask:0xf bound_ctrl:1
	s_nop 1
	v_add_f32_dpp v66, v66, v66 row_shr:8 row_mask:0xf bank_mask:0xf bound_ctrl:1
	s_nop 0
	v_readlane_b32 s9, v66, 15
	v_readlane_b32 s10, v66, 31
	v_readlane_b32 s11, v66, 47
	v_readlane_b32 vcc_lo, v66, 63
	s_nop 1
	v_mov_b32_e32 v66, s9
	v_add_f32_e32 v66, s10, v66
	v_add_f32_e32 v66, s11, v66
	v_add_f32_e32 v66, vcc_lo, v66
	v_mul_f32_e32 v66, 0x3a800000, v66
	v_add_f32_e32 v66, 0x3727c5ac, v66
	v_rsq_f32_e32 v118, v66
	s_nop 0
	v_mov_b32_e32 v119, v118
	v_pk_mul_f32 v[0:1], v[0:1], v[118:119]
	v_pk_mul_f32 v[2:3], v[2:3], v[118:119]
	v_pk_mul_f32 v[4:5], v[4:5], v[118:119]
	v_pk_mul_f32 v[6:7], v[6:7], v[118:119]
	v_pk_mul_f32 v[8:9], v[8:9], v[118:119]
	v_pk_mul_f32 v[10:11], v[10:11], v[118:119]
	v_pk_mul_f32 v[12:13], v[12:13], v[118:119]
	v_pk_mul_f32 v[14:15], v[14:15], v[118:119]
	v_pk_fma_f32 v[76:77], v[0:1], v[34:35], v[50:51]
	v_pk_fma_f32 v[78:79], v[2:3], v[36:37], v[52:53]
	v_pk_fma_f32 v[80:81], v[4:5], v[38:39], v[54:55]
	v_pk_fma_f32 v[82:83], v[6:7], v[40:41], v[56:57]
	v_pk_fma_f32 v[84:85], v[8:9], v[42:43], v[58:59]
	v_pk_fma_f32 v[86:87], v[10:11], v[44:45], v[60:61]
	v_pk_fma_f32 v[88:89], v[12:13], v[46:47], v[62:63]
	v_pk_fma_f32 v[90:91], v[14:15], v[48:49], v[64:65]
	s_cmp_lg_u32 s8, 0
	s_cbranch_scc1 .Lln2_f32_0
	v_cvt_pk_bf16_f32 v92, v76, v77
	v_cvt_pk_bf16_f32 v93, v78, v79
	v_cvt_pk_bf16_f32 v94, v80, v81
	v_cvt_pk_bf16_f32 v95, v82, v83
	v_cvt_pk_bf16_f32 v96, v84, v85
	v_cvt_pk_bf16_f32 v97, v86, v87
	v_cvt_pk_bf16_f32 v98, v88, v89
	v_cvt_pk_bf16_f32 v99, v90, v91
	global_store_dwordx2 v115, v[92:93], s[2:3] offset:0 sc1
	global_store_dwordx2 v115, v[94:95], s[2:3] offset:512 sc1
	global_store_dwordx2 v115, v[96:97], s[2:3] offset:1024 sc1
	global_store_dwordx2 v115, v[98:99], s[2:3] offset:1536 sc1
	s_branch .Lln2_st_0
; __device__ __forceinline__ void phase_ln(float* R, const float* __restrict__ g, const float* __restrict__ b, bf16_t* xbf, float samp_scale, const float* __restrict__ part, int nsplit, bool f32_all) {
;     ...
;   for (int r = gw; r < MT; r += nw) {
;     float* row = R + (size_t)r * 1024;
;     f32x4 v[4];
; #pragma unroll
;     for (int i = 0; i < 4; ++i) v[i] = *(const f32x4*)(row + i * 256 + lane * 4);
;     if (r >= MP) {
;       for (int sp = 0; sp < nsplit; ++sp) {
;         const float* prow = part + ((size_t)sp * MS + (r - MP)) * 1024;
; #pragma unroll
;         for (int i = 0; i < 4; ++i) v[i] = v[i] + *(const f32x4*)(prow + i * 256 + lane * 4);
;       }
;     }
;     float s = 0.f;
; #pragma unroll
;     for (int i = 0; i < 4; ++i) s += v[i][0] + v[i][1] + v[i][2] + v[i][3];
; #pragma unroll
;     for (int o = 32; o >= 1; o >>= 1) s += __shfl_xor(s, o);
;     const float mean = s * (1.f / 1024.f);
;     float ss = 0.f;
; #pragma unroll
;     for (int i = 0; i < 4; ++i) { v[i] = v[i] - mean; ss += v[i][0] * v[i][0] + v[i][1] * v[i][1] + v[i][2] * v[i][2] + v[i][3] * v[i][3]; }
; #pragma unroll
;     for (int o = 32; o >= 1; o >>= 1) ss += __shfl_xor(ss, o);
;     const float rstd = rsqrtf(ss * (1.f / 1024.f) + LN_EPS);
; #pragma unroll
;     for (int i = 0; i < 4; ++i) {
;       const f32x4 y = v[i] * rstd * gv[i] + bv[i];
;       if (r >= MP) *(f32x4*)(row + i * 256 + lane * 4) = y * samp_scale;
;       else if (f32_all) *(f32x4*)(row + i * 256 + lane * 4) = y;
;       if (xbf) {
;         u32x2 wv;
;         wv[0] = cvt_pk_bf16(y[0], y[1]); wv[1] = cvt_pk_bf16(y[2], y[3]);
;         *(u32x2*)(xbf + (size_t)r * 1024 + i * 256 + lane * 4) = wv;
;       }
;     }
.Lln2_f32_0:
	s_sub_u32 s10, s0, 0x1000000
	s_subb_u32 s11, s1, 0
	global_store_dwordx4 v114, v[76:79], s[10:11] offset:0 sc1
	global_store_dwordx4 v114, v[80:83], s[10:11] offset:1024 sc1
	global_store_dwordx4 v114, v[84:87], s[10:11] offset:2048 sc1
	global_store_dwordx4 v114, v[88:91], s[10:11] offset:3072 sc1
.Lln2_st_0:
	s_add_u32 s2, s2, 0x400000
	s_addc_u32 s3, s3, 0
	s_add_u32 s0, s0, 0x800000
	s_addc_u32 s1, s1, 0
	global_load_dwordx4 v[0:3], v114, s[0:1] offset:0 nt
	global_load_dwordx4 v[4:7], v114, s[0:1] offset:1024 nt
	global_load_dwordx4 v[8:11], v114, s[0:1] offset:2048 nt
	global_load_dwordx4 v[12:15], v114, s[0:1] offset:3072 nt
	s_waitcnt vmcnt(12)
	v_pk_add_f32 v[66:67], v[18:19], v[20:21]
	v_pk_add_f32 v[68:69], v[22:23], v[24:25]
	v_pk_add_f32 v[70:71], v[26:27], v[28:29]
	v_pk_add_f32 v[72:73], v[30:31], v[32:33]
	v_pk_add_f32 v[66:67], v[66:67], v[68:69]
	v_pk_add_f32 v[70:71], v[70:71], v[72:73]
	v_pk_add_f32 v[66:67], v[66:67], v[70:71]
	v_add_f32_e32 v66, v66, v67
	s_nop 1
	v_add_f32_dpp v66, v66, v66 row_shr:1 row_mask:0xf bank_mask:0xf bound_ctrl:1
	s_nop 1
	v_add_f32_dpp v66, v66, v66 row_shr:2 row_mask:0xf bank_mask:0xf bound_ctrl:1
	s_nop 1
	v_add_f32_dpp v66, v66, v66 row_shr:4 row_mask:0xf bank_mask:0xf bound_ctrl:1
	s_nop 1
	v_add_f32_dpp v66, v66, v66 row_shr:8 row_mask:0xf bank_mask:0xf bound_ctrl:1
	s_nop 0
	v_readlane_b32 s9, v66, 15
	v_readlane_b32 s10, v66, 31
	v_readlane_b32 s11, v66, 47
	v_readlane_b32 vcc_lo, v66, 63
	s_nop 1
	v_mov_b32_e32 v66, s9
	v_add_f32_e32 v66, s10, v66
	v_add_f32_e32 v66, s11, v66
	v_add_f32_e32 v66, vcc_lo, v66
	v_mul_f32_e32 v116, 0x3a800000, v66
	v_mov_b32_e32 v117, v116
	v_pk_add_f32 v[18:19], v[18:19], v[116:117] neg_lo:[0,1] neg_hi:[0,1]
	v_pk_add_f32 v[20:21], v[20:21], v[116:117] neg_lo:[0,1] neg_hi:[0,1]
	v_pk_add_f32 v[22:23], v[22:23], v[116:117] neg_lo:[0,1] neg_hi:[0,1]
	v_pk_add_f32 v[24:25], v[24:25], v[116:117] neg_lo:[0,1] neg_hi:[0,1]
	v_pk_add_f32 v[26:27], v[26:27], v[116:117] neg_lo:[0,1] neg_hi:[0,1]
	v_pk_add_f32 v[28:29], v[28:29], v[116:117] neg_lo:[0,1] neg_hi:[0,1]
	v_pk_add_f32 v[30:31], v[30:31], v[116:117] neg_lo:[0,1] neg_hi:[0,1]
	v_pk_add_f32 v[32:33], v[32:33], v[116:117] neg_lo:[0,1] neg_hi:[0,1]
	v_pk_mul_f32 v[66:67], v[18:19], v[18:19]
	v_pk_mul_f32 v[68:69], v[20:21], v[20:21]
	v_pk_fma_f32 v[66:67], v[22:23], v[22:23], v[66:67]
	v_pk_fma_f32 v[68:69], v[24:25], v[24:25], v[68:69]
	v_pk_fma_f32 v[66:67], v[26:27], v[26:27], v[66:67]
	v_pk_fma_f32 v[68:69], v[28:29], v[28:29], v[68:69]
	v_pk_fma_f32 v[66:67], v[30:31], v[30:31], v[66:67]
	v_pk_fma_f32 v[68:69], v[32:33], v[32:33], v[68:69]
	v_pk_add_f32 v[66:67], v[66:67], v[68:69]
	v_add_f32_e32 v66, v66, v67
	s_nop 1
	v_add_f32_dpp v66, v66, v66 row_shr:1 row_mask:0xf bank_mask:0xf bound_ctrl:1
	s_nop 1
	v_add_f32_dpp v66, v66, v66 row_shr:2 row_mask:0xf bank_mask:0xf bound_ctrl:1
	s_nop 1
	v_add_f32_dpp v66, v66, v66 row_shr:4 row_mask:0xf bank_mask:0xf bound_ctrl:1
	s_nop 1
	v_add_f32_dpp v66, v66, v66 row_shr:8 row_mask:0xf bank_mask:0xf bound_ctrl:1
	s_nop 0
	v_readlane_b32 s9, v66, 15
	v_readlane_b32 s10, v66, 31
	v_readlane_b32 s11, v66, 47
	v_readlane_b32 vcc_lo, v66, 63
	s_nop 1
	v_mov_b32_e32 v66, s9
	v_add_f32_e32 v66, s10, v66
	v_add_f32_e32 v66, s11, v66
	v_add_f32_e32 v66, vcc_lo, v66
	v_mul_f32_e32 v66, 0x3a800000, v66
	v_add_f32_e32 v66, 0x3727c5ac, v66
	v_rsq_f32_e32 v118, v66
	s_nop 0
	v_mov_b32_e32 v119, v118
	v_pk_mul_f32 v[18:19], v[18:19], v[118:119]
	v_pk_mul_f32 v[20:21], v[20:21], v[118:119]
	v_pk_mul_f32 v[22:23], v[22:23], v[118:119]
	v_pk_mul_f32 v[24:25], v[24:25], v[118:119]
	v_pk_mul_f32 v[26:27], v[26:27], v[118:119]
	v_pk_mul_f32 v[28:29], v[28:29], v[118:119]
	v_pk_mul_f32 v[30:31], v[30:31], v[118:119]
	v_pk_mul_f32 v[32:33], v[32:33], v[118:119]
	v_pk_fma_f32 v[76:77], v[18:19], v[34:35], v[50:51]
	v_pk_fma_f32 v[78:79], v[20:21], v[36:37], v[52:53]
	v_pk_fma_f32 v[80:81], v[22:23], v[38:39], v[54:55]
	v_pk_fma_f32 v[82:83], v[24:25], v[40:41], v[56:57]
	v_pk_fma_f32 v[84:85], v[26:27], v[42:43], v[58:59]
	v_pk_fma_f32 v[86:87], v[28:29], v[44:45], v[60:61]
	v_pk_fma_f32 v[88:89], v[30:31], v[46:47], v[62:63]
	v_pk_fma_f32 v[90:91], v[32:33], v[48:49], v[64:65]
	s_cmp_lg_u32 s8, 0
	s_cbranch_scc1 .Lln2_f32_1
	v_cvt_pk_bf16_f32 v92, v76, v77
	v_cvt_pk_bf16_f32 v93, v78, v79
	v_cvt_pk_bf16_f32 v94, v80, v81
	v_cvt_pk_bf16_f32 v95, v82, v83
	v_cvt_pk_bf16_f32 v96, v84, v85
	v_cvt_pk_bf16_f32 v97, v86, v87
	v_cvt_pk_bf16_f32 v98, v88, v89
	v_cvt_pk_bf16_f32 v99, v90, v91
	global_store_dwordx2 v115, v[92:93], s[2:3] offset:0 sc1
	global_store_dwordx2 v115, v[94:95], s[2:3] offset:512 sc1
	global_store_dwordx2 v115, v[96:97], s[2:3] offset:1024 sc1
	global_store_dwordx2 v115, v[98:99], s[2:3] offset:1536 sc1
	s_branch .Lln2_st_1

; __device__ __forceinline__ void phase_ln(float* R, const float* __restrict__ g, const float* __restrict__ b, bf16_t* xbf, float samp_scale, const float* __restrict__ part, int nsplit, bool f32_all) {
;     ...
;   for (int r = gw; r < MT; r += nw) {
;     float* row = R + (size_t)r * 1024;
;     f32x4 v[4];
; #pragma unroll
;     for (int i = 0; i < 4; ++i) v[i] = *(const f32x4*)(row + i * 256 + lane * 4);
;     if (r >= MP) {
;       for (int sp = 0; sp < nsplit; ++sp) {
;         const float* prow = part + ((size_t)sp * MS + (r - MP)) * 1024;
; #pragma unroll
;         for (int i = 0; i < 4; ++i) v[i] = v[i] + *(const f32x4*)(prow + i * 256 + lane * 4);
;       }
;     }
;     float s = 0.f;
; #pragma unroll
;     for (int i = 0; i < 4; ++i) s += v[i][0] + v[i][1] + v[i][2] + v[i][3];
; #pragma unroll
;     for (int o = 32; o >= 1; o >>= 1) s += __shfl_xor(s, o);
;     const float mean = s * (1.f / 1024.f);
;     float ss = 0.f;
; #pragma unroll
;     for (int i = 0; i < 4; ++i) { v[i] = v[i] - mean; ss += v[i][0] * v[i][0] + v[i][1] * v[i][1] + v[i][2] * v[i][2] + v[i][3] * v[i][3]; }
; #pragma unroll
;     for (int o = 32; o >= 1; o >>= 1) ss += __shfl_xor(ss, o);
;     const float rstd = rsqrtf(ss * (1.f / 1024.f) + LN_EPS);
; #pragma unroll
;     for (int i = 0; i < 4; ++i) {
;       const f32x4 y = v[i] * rstd * gv[i] + bv[i];
;       if (r >= MP) *(f32x4*)(row + i * 256 + lane * 4) = y * samp_scale;
;       else if (f32_all) *(f32x4*)(row + i * 256 + lane * 4) = y;
;       if (xbf) {
;         u32x2 wv;
;         wv[0] = cvt_pk_bf16(y[0], y[1]); wv[1] = cvt_pk_bf16(y[2], y[3]);
;         *(u32x2*)(xbf + (size_t)r * 1024 + i * 256 + lane * 4) = wv;
;       }
;     }
.Lln2_st_1:
	s_add_u32 s2, s2, 0x400000
	s_addc_u32 s3, s3, 0
	s_add_u32 s0, s0, 0x800000
	s_addc_u32 s1, s1, 0
	global_load_dwordx4 v[18:21], v114, s[0:1] offset:0 nt
	global_load_dwordx4 v[22:25], v114, s[0:1] offset:1024 nt
	global_load_dwordx4 v[26:29], v114, s[0:1] offset:2048 nt
	global_load_dwordx4 v[30:33], v114, s[0:1] offset:3072 nt
	s_waitcnt vmcnt(16)
	v_pk_add_f32 v[66:67], v[122:123], v[124:125]
	v_pk_add_f32 v[68:69], v[126:127], v[128:129]
	v_pk_add_f32 v[70:71], v[130:131], v[132:133]
	v_pk_add_f32 v[72:73], v[134:135], v[136:137]
	v_pk_add_f32 v[66:67], v[66:67], v[68:69]
	v_pk_add_f32 v[70:71], v[70:71], v[72:73]
	v_pk_add_f32 v[66:67], v[66:67], v[70:71]
	v_add_f32_e32 v66, v66, v67
	s_nop 1
	v_add_f32_dpp v66, v66, v66 row_shr:1 row_mask:0xf bank_mask:0xf bound_ctrl:1
	s_nop 1
	v_add_f32_dpp v66, v66, v66 row_shr:2 row_mask:0xf bank_mask:0xf bound_ctrl:1
	s_nop 1
	v_add_f32_dpp v66, v66, v66 row_shr:4 row_mask:0xf bank_mask:0xf bound_ctrl:1
	s_nop 1
	v_add_f32_dpp v66, v66, v66 row_shr:8 row_mask:0xf bank_mask:0xf bound_ctrl:1
	s_nop 0
	v_readlane_b32 s9, v66, 15
	v_readlane_b32 s10, v66, 31
	v_readlane_b32 s11, v66, 47
	v_readlane_b32 vcc_lo, v66, 63
	s_nop 1
	v_mov_b32_e32 v66, s9
	v_add_f32_e32 v66, s10, v66
	v_add_f32_e32 v66, s11, v66
	v_add_f32_e32 v66, vcc_lo, v66
	v_mul_f32_e32 v116, 0x3a800000, v66
	v_mov_b32_e32 v117, v116
	v_pk_add_f32 v[122:123], v[122:123], v[116:117] neg_lo:[0,1] neg_hi:[0,1]
	v_pk_add_f32 v[124:125], v[124:125], v[116:117] neg_lo:[0,1] neg_hi:[0,1]
	v_pk_add_f32 v[126:127], v[126:127], v[116:117] neg_lo:[0,1] neg_hi:[0,1]
	v_pk_add_f32 v[128:129], v[128:129], v[116:117] neg_lo:[0,1] neg_hi:[0,1]
	v_pk_add_f32 v[130:131], v[130:131], v[116:117] neg_lo:[0,1] neg_hi:[0,1]
	v_pk_add_f32 v[132:133], v[132:133], v[116:117] neg_lo:[0,1] neg_hi:[0,1]
	v_pk_add_f32 v[134:135], v[134:135], v[116:117] neg_lo:[0,1] neg_hi:[0,1]
	v_pk_add_f32 v[136:137], v[136:137], v[116:117] neg_lo:[0,1] neg_hi:[0,1]
	v_pk_mul_f32 v[66:67], v[122:123], v[122:123]
	v_pk_mul_f32 v[68:69], v[124:125], v[124:125]
	v_pk_fma_f32 v[66:67], v[126:127], v[126:127], v[66:67]
	v_pk_fma_f32 v[68:69], v[128:129], v[128:129], v[68:69]
	v_pk_fma_f32 v[66:67], v[130:131], v[130:131], v[66:67]
	v_pk_fma_f32 v[68:69], v[132:133], v[132:133], v[68:69]
	v_pk_fma_f32 v[66:67], v[134:135], v[134:135], v[66:67]
	v_pk_fma_f32 v[68:69], v[136:137], v[136:137], v[68:69]
	v_pk_add_f32 v[66:67], v[66:67], v[68:69]
	v_add_f32_e32 v66, v66, v67
	s_nop 1
	v_add_f32_dpp v66, v66, v66 row_shr:1 row_mask:0xf bank_mask:0xf bound_ctrl:1
	s_nop 1
	v_add_f32_dpp v66, v66, v66 row_shr:2 row_mask:0xf bank_mask:0xf bound_ctrl:1
	s_nop 1
	v_add_f32_dpp v66, v66, v66 row_shr:4 row_mask:0xf bank_mask:0xf bound_ctrl:1
	s_nop 1
	v_add_f32_dpp v66, v66, v66 row_shr:8 row_mask:0xf bank_mask:0xf bound_ctrl:1
	s_nop 0
	v_readlane_b32 s9, v66, 15
	v_readlane_b32 s10, v66, 31
	v_readlane_b32 s11, v66, 47
	v_readlane_b32 vcc_lo, v66, 63
	s_nop 1
	v_mov_b32_e32 v66, s9
	v_add_f32_e32 v66, s10, v66
	v_add_f32_e32 v66, s11, v66
	v_add_f32_e32 v66, vcc_lo, v66
	v_mul_f32_e32 v66, 0x3a800000, v66
	v_add_f32_e32 v66, 0x3727c5ac, v66
	v_rsq_f32_e32 v118, v66
	s_nop 0
	v_mov_b32_e32 v119, v118
	v_pk_mul_f32 v[122:123], v[122:123], v[118:119]
	v_pk_mul_f32 v[124:125], v[124:125], v[118:119]
	v_pk_mul_f32 v[126:127], v[126:127], v[118:119]
	v_pk_mul_f32 v[128:129], v[128:129], v[118:119]
	v_pk_mul_f32 v[130:131], v[130:131], v[118:119]
	v_pk_mul_f32 v[132:133], v[132:133], v[118:119]
	v_pk_mul_f32 v[134:135], v[134:135], v[118:119]
	v_pk_mul_f32 v[136:137], v[136:137], v[118:119]
	v_pk_fma_f32 v[76:77], v[122:123], v[34:35], v[50:51]
	v_pk_fma_f32 v[78:79], v[124:125], v[36:37], v[52:53]
	v_pk_fma_f32 v[80:81], v[126:127], v[38:39], v[54:55]
	v_pk_fma_f32 v[82:83], v[128:129], v[40:41], v[56:57]
	v_pk_fma_f32 v[84:85], v[130:131], v[42:43], v[58:59]
	v_pk_fma_f32 v[86:87], v[132:133], v[44:45], v[60:61]
	v_pk_fma_f32 v[88:89], v[134:135], v[46:47], v[62:63]
	v_pk_fma_f32 v[90:91], v[136:137], v[48:49], v[64:65]
	s_cmp_lg_u32 s8, 0
	s_cbranch_scc1 .Lln2_f32_2
	v_cvt_pk_bf16_f32 v92, v76, v77
	v_cvt_pk_bf16_f32 v93, v78, v79
	v_cvt_pk_bf16_f32 v94, v80, v81
	v_cvt_pk_bf16_f32 v95, v82, v83
	v_cvt_pk_bf16_f32 v96, v84, v85
	v_cvt_pk_bf16_f32 v97, v86, v87
	v_cvt_pk_bf16_f32 v98, v88, v89
	v_cvt_pk_bf16_f32 v99, v90, v91
	global_store_dwordx2 v115, v[92:93], s[2:3] offset:0 sc1
	global_store_dwordx2 v115, v[94:95], s[2:3] offset:512 sc1
	global_store_dwordx2 v115, v[96:97], s[2:3] offset:1024 sc1
	global_store_dwordx2 v115, v[98:99], s[2:3] offset:1536 sc1
	s_branch .Lln2_st_2

; __device__ __forceinline__ void phase_ln(float* R, const float* __restrict__ g, const float* __restrict__ b, bf16_t* xbf, float samp_scale, const float* __restrict__ part, int nsplit, bool f32_all) {
;     ...
;   for (int r = gw; r < MT; r += nw) {
;     float* row = R + (size_t)r * 1024;
;     f32x4 v[4];
; #pragma unroll
;     for (int i = 0; i < 4; ++i) v[i] = *(const f32x4*)(row + i * 256 + lane * 4);
;     if (r >= MP) {
;       for (int sp = 0; sp < nsplit; ++sp) {
;         const float* prow = part + ((size_t)sp * MS + (r - MP)) * 1024;
; #pragma unroll
;         for (int i = 0; i < 4; ++i) v[i] = v[i] + *(const f32x4*)(prow + i * 256 + lane * 4);
;       }
;     }
;     float s = 0.f;
; #pragma unroll
;     for (int i = 0; i < 4; ++i) s += v[i][0] + v[i][1] + v[i][2] + v[i][3];
; #pragma unroll
;     for (int o = 32; o >= 1; o >>= 1) s += __shfl_xor(s, o);
;     const float mean = s * (1.f / 1024.f);
;     float ss = 0.f;
; #pragma unroll
;     for (int i = 0; i < 4; ++i) { v[i] = v[i] - mean; ss += v[i][0] * v[i][0] + v[i][1] * v[i][1] + v[i][2] * v[i][2] + v[i][3] * v[i][3]; }
; #pragma unroll
;     for (int o = 32; o >= 1; o >>= 1) ss += __shfl_xor(ss, o);
;     const float rstd = rsqrtf(ss * (1.f / 1024.f) + LN_EPS);
; #pragma unroll
;     for (int i = 0; i < 4; ++i) {
;       const f32x4 y = v[i] * rstd * gv[i] + bv[i];
;       if (r >= MP) *(f32x4*)(row + i * 256 + lane * 4) = y * samp_scale;
;       else if (f32_all) *(f32x4*)(row + i * 256 + lane * 4) = y;
;       if (xbf) {
;         u32x2 wv;
;         wv[0] = cvt_pk_bf16(y[0], y[1]); wv[1] = cvt_pk_bf16(y[2], y[3]);
;         *(u32x2*)(xbf + (size_t)r * 1024 + i * 256 + lane * 4) = wv;
;       }
;     }
.Lln2_st_2:
	s_add_u32 s2, s2, 0x400000
	s_addc_u32 s3, s3, 0
	s_add_u32 s0, s0, 0x800000
	s_addc_u32 s1, s1, 0
	global_load_dwordx4 v[122:125], v114, s[0:1] offset:0 nt
	global_load_dwordx4 v[126:129], v114, s[0:1] offset:1024 nt
	global_load_dwordx4 v[130:133], v114, s[0:1] offset:2048 nt
	global_load_dwordx4 v[134:137], v114, s[0:1] offset:3072 nt
	s_waitcnt vmcnt(16)
	v_pk_add_f32 v[66:67], v[0:1], v[2:3]
	v_pk_add_f32 v[68:69], v[4:5], v[6:7]
	v_pk_add_f32 v[70:71], v[8:9], v[10:11]
	v_pk_add_f32 v[72:73], v[12:13], v[14:15]
	v_pk_add_f32 v[66:67], v[66:67], v[68:69]
	v_pk_add_f32 v[70:71], v[70:71], v[72:73]
	v_pk_add_f32 v[66:67], v[66:67], v[70:71]
	v_add_f32_e32 v66, v66, v67
	s_nop 1
	v_add_f32_dpp v66, v66, v66 row_shr:1 row_mask:0xf bank_mask:0xf bound_ctrl:1
	s_nop 1
	v_add_f32_dpp v66, v66, v66 row_shr:2 row_mask:0xf bank_mask:0xf bound_ctrl:1
	s_nop 1
	v_add_f32_dpp v66, v66, v66 row_shr:4 row_mask:0xf bank_mask:0xf bound_ctrl:1
	s_nop 1
	v_add_f32_dpp v66, v66, v66 row_shr:8 row_mask:0xf bank_mask:0xf bound_ctrl:1
	s_nop 0
	v_readlane_b32 s9, v66, 15
	v_readlane_b32 s10, v66, 31
	v_readlane_b32 s11, v66, 47
	v_readlane_b32 vcc_lo, v66, 63
	s_nop 1
	v_mov_b32_e32 v66, s9
	v_add_f32_e32 v66, s10, v66
	v_add_f32_e32 v66, s11, v66
	v_add_f32_e32 v66, vcc_lo, v66
	v_mul_f32_e32 v116, 0x3a800000, v66
	v_mov_b32_e32 v117, v116
	v_pk_add_f32 v[0:1], v[0:1], v[116:117] neg_lo:[0,1] neg_hi:[0,1]
	v_pk_add_f32 v[2:3], v[2:3], v[116:117] neg_lo:[0,1] neg_hi:[0,1]
	v_pk_add_f32 v[4:5], v[4:5], v[116:117] neg_lo:[0,1] neg_hi:[0,1]
	v_pk_add_f32 v[6:7], v[6:7], v[116:117] neg_lo:[0,1] neg_hi:[0,1]
	v_pk_add_f32 v[8:9], v[8:9], v[116:117] neg_lo:[0,1] neg_hi:[0,1]
	v_pk_add_f32 v[10:11], v[10:11], v[116:117] neg_lo:[0,1] neg_hi:[0,1]
	v_pk_add_f32 v[12:13], v[12:13], v[116:117] neg_lo:[0,1] neg_hi:[0,1]
	v_pk_add_f32 v[14:15], v[14:15], v[116:117] neg_lo:[0,1] neg_hi:[0,1]
	v_pk_mul_f32 v[66:67], v[0:1], v[0:1]
	v_pk_mul_f32 v[68:69], v[2:3], v[2:3]
	v_pk_fma_f32 v[66:67], v[4:5], v[4:5], v[66:67]
	v_pk_fma_f32 v[68:69], v[6:7], v[6:7], v[68:69]
	v_pk_fma_f32 v[66:67], v[8:9], v[8:9], v[66:67]
	v_pk_fma_f32 v[68:69], v[10:11], v[10:11], v[68:69]
	v_pk_fma_f32 v[66:67], v[12:13], v[12:13], v[66:67]
	v_pk_fma_f32 v[68:69], v[14:15], v[14:15], v[68:69]
	v_pk_add_f32 v[66:67], v[66:67], v[68:69]
	v_add_f32_e32 v66, v66, v67
	s_nop 1
	v_add_f32_dpp v66, v66, v66 row_shr:1 row_mask:0xf bank_mask:0xf bound_ctrl:1
	s_nop 1
	v_add_f32_dpp v66, v66, v66 row_shr:2 row_mask:0xf bank_mask:0xf bound_ctrl:1
	s_nop 1
	v_add_f32_dpp v66, v66, v66 row_shr:4 row_mask:0xf bank_mask:0xf bound_ctrl:1
	s_nop 1
	v_add_f32_dpp v66, v66, v66 row_shr:8 row_mask:0xf bank_mask:0xf bound_ctrl:1
	s_nop 0
	v_readlane_b32 s9, v66, 15
	v_readlane_b32 s10, v66, 31
	v_readlane_b32 s11, v66, 47
	v_readlane_b32 vcc_lo, v66, 63
	s_nop 1
	v_mov_b32_e32 v66, s9
	v_add_f32_e32 v66, s10, v66
	v_add_f32_e32 v66, s11, v66
	v_add_f32_e32 v66, vcc_lo, v66
	v_mul_f32_e32 v66, 0x3a800000, v66
	v_add_f32_e32 v66, 0x3727c5ac, v66
	v_rsq_f32_e32 v118, v66
	s_nop 0
	v_mov_b32_e32 v119, v118
	v_pk_mul_f32 v[0:1], v[0:1], v[118:119]
	v_pk_mul_f32 v[2:3], v[2:3], v[118:119]
	v_pk_mul_f32 v[4:5], v[4:5], v[118:119]
	v_pk_mul_f32 v[6:7], v[6:7], v[118:119]
	v_pk_mul_f32 v[8:9], v[8:9], v[118:119]
	v_pk_mul_f32 v[10:11], v[10:11], v[118:119]
	v_pk_mul_f32 v[12:13], v[12:13], v[118:119]
	v_pk_mul_f32 v[14:15], v[14:15], v[118:119]
	v_pk_fma_f32 v[76:77], v[0:1], v[34:35], v[50:51]
	v_pk_fma_f32 v[78:79], v[2:3], v[36:37], v[52:53]
	v_pk_fma_f32 v[80:81], v[4:5], v[38:39], v[54:55]
	v_pk_fma_f32 v[82:83], v[6:7], v[40:41], v[56:57]
	v_pk_fma_f32 v[84:85], v[8:9], v[42:43], v[58:59]
	v_pk_fma_f32 v[86:87], v[10:11], v[44:45], v[60:61]
	v_pk_fma_f32 v[88:89], v[12:13], v[46:47], v[62:63]
	v_pk_fma_f32 v[90:91], v[14:15], v[48:49], v[64:65]
	s_cmp_lg_u32 s8, 0
	s_cbranch_scc1 .Lln2_f32_3
	v_cvt_pk_bf16_f32 v92, v76, v77
	v_cvt_pk_bf16_f32 v93, v78, v79
	v_cvt_pk_bf16_f32 v94, v80, v81
	v_cvt_pk_bf16_f32 v95, v82, v83
	v_cvt_pk_bf16_f32 v96, v84, v85
	v_cvt_pk_bf16_f32 v97, v86, v87
	v_cvt_pk_bf16_f32 v98, v88, v89
	v_cvt_pk_bf16_f32 v99, v90, v91
	global_store_dwordx2 v115, v[92:93], s[2:3] offset:0 sc1
	global_store_dwordx2 v115, v[94:95], s[2:3] offset:512 sc1
	global_store_dwordx2 v115, v[96:97], s[2:3] offset:1024 sc1
	global_store_dwordx2 v115, v[98:99], s[2:3] offset:1536 sc1
	s_branch .Lln2_st_3

; __device__ __forceinline__ void phase_ln(float* R, const float* __restrict__ g, const float* __restrict__ b, bf16_t* xbf, float samp_scale, const float* __restrict__ part, int nsplit, bool f32_all) {
;     ...
;   for (int r = gw; r < MT; r += nw) {
;     float* row = R + (size_t)r * 1024;
;     f32x4 v[4];
; #pragma unroll
;     for (int i = 0; i < 4; ++i) v[i] = *(const f32x4*)(row + i * 256 + lane * 4);
;     if (r >= MP) {
;       for (int sp = 0; sp < nsplit; ++sp) {
;         const float* prow = part + ((size_t)sp * MS + (r - MP)) * 1024;
; #pragma unroll
;         for (int i = 0; i < 4; ++i) v[i] = v[i] + *(const f32x4*)(prow + i * 256 + lane * 4);
;       }
;     }
;     float s = 0.f;
; #pragma unroll
;     for (int i = 0; i < 4; ++i) s += v[i][0] + v[i][1] + v[i][2] + v[i][3];
; #pragma unroll
;     for (int o = 32; o >= 1; o >>= 1) s += __shfl_xor(s, o);
;     const float mean = s * (1.f / 1024.f);
;     float ss = 0.f;
; #pragma unroll
;     for (int i = 0; i < 4; ++i) { v[i] = v[i] - mean; ss += v[i][0] * v[i][0] + v[i][1] * v[i][1] + v[i][2] * v[i][2] + v[i][3] * v[i][3]; }
; #pragma unroll
;     for (int o = 32; o >= 1; o >>= 1) ss += __shfl_xor(ss, o);
;     const float rstd = rsqrtf(ss * (1.f / 1024.f) + LN_EPS);
; #pragma unroll
;     for (int i = 0; i < 4; ++i) {
;       const f32x4 y = v[i] * rstd * gv[i] + bv[i];
;       if (r >= MP) *(f32x4*)(row + i * 256 + lane * 4) = y * samp_scale;
;       else if (f32_all) *(f32x4*)(row + i * 256 + lane * 4) = y;
;       if (xbf) {
;         u32x2 wv;
;         wv[0] = cvt_pk_bf16(y[0], y[1]); wv[1] = cvt_pk_bf16(y[2], y[3]);
;         *(u32x2*)(xbf + (size_t)r * 1024 + i * 256 + lane * 4) = wv;
;       }
;     }
.Lln2_st_3:
	s_add_u32 s2, s2, 0x400000
	s_addc_u32 s3, s3, 0
	s_add_u32 s0, s0, 0x800000
	s_addc_u32 s1, s1, 0
	global_load_dwordx4 v[0:3], v114, s[0:1] offset:0 nt
	global_load_dwordx4 v[4:7], v114, s[0:1] offset:1024 nt
	global_load_dwordx4 v[8:11], v114, s[0:1] offset:2048 nt
	global_load_dwordx4 v[12:15], v114, s[0:1] offset:3072 nt
	s_waitcnt vmcnt(16)
	v_pk_add_f32 v[66:67], v[18:19], v[20:21]
	v_pk_add_f32 v[68:69], v[22:23], v[24:25]
	v_pk_add_f32 v[70:71], v[26:27], v[28:29]
	v_pk_add_f32 v[72:73], v[30:31], v[32:33]
	v_pk_add_f32 v[66:67], v[66:67], v[68:69]
	v_pk_add_f32 v[70:71], v[70:71], v[72:73]
	v_pk_add_f32 v[66:67], v[66:67], v[70:71]
	v_add_f32_e32 v66, v66, v67
	s_nop 1
	v_add_f32_dpp v66, v66, v66 row_shr:1 row_mask:0xf bank_mask:0xf bound_ctrl:1
	s_nop 1
	v_add_f32_dpp v66, v66, v66 row_shr:2 row_mask:0xf bank_mask:0xf bound_ctrl:1
	s_nop 1
	v_add_f32_dpp v66, v66, v66 row_shr:4 row_mask:0xf bank_mask:0xf bound_ctrl:1
	s_nop 1
	v_add_f32_dpp v66, v66, v66 row_shr:8 row_mask:0xf bank_mask:0xf bound_ctrl:1
	s_nop 0
	v_readlane_b32 s9, v66, 15
	v_readlane_b32 s10, v66, 31
	v_readlane_b32 s11, v66, 47
	v_readlane_b32 vcc_lo, v66, 63
	s_nop 1
	v_mov_b32_e32 v66, s9
	v_add_f32_e32 v66, s10, v66
	v_add_f32_e32 v66, s11, v66
	v_add_f32_e32 v66, vcc_lo, v66
	v_mul_f32_e32 v116, 0x3a800000, v66
	v_mov_b32_e32 v117, v116
	v_pk_add_f32 v[18:19], v[18:19], v[116:117] neg_lo:[0,1] neg_hi:[0,1]
	v_pk_add_f32 v[20:21], v[20:21], v[116:117] neg_lo:[0,1] neg_hi:[0,1]
	v_pk_add_f32 v[22:23], v[22:23], v[116:117] neg_lo:[0,1] neg_hi:[0,1]
	v_pk_add_f32 v[24:25], v[24:25], v[116:117] neg_lo:[0,1] neg_hi:[0,1]
	v_pk_add_f32 v[26:27], v[26:27], v[116:117] neg_lo:[0,1] neg_hi:[0,1]
	v_pk_add_f32 v[28:29], v[28:29], v[116:117] neg_lo:[0,1] neg_hi:[0,1]
	v_pk_add_f32 v[30:31], v[30:31], v[116:117] neg_lo:[0,1] neg_hi:[0,1]
	v_pk_add_f32 v[32:33], v[32:33], v[116:117] neg_lo:[0,1] neg_hi:[0,1]
	v_pk_mul_f32 v[66:67], v[18:19], v[18:19]
	v_pk_mul_f32 v[68:69], v[20:21], v[20:21]
	v_pk_fma_f32 v[66:67], v[22:23], v[22:23], v[66:67]
	v_pk_fma_f32 v[68:69], v[24:25], v[24:25], v[68:69]
	v_pk_fma_f32 v[66:67], v[26:27], v[26:27], v[66:67]
	v_pk_fma_f32 v[68:69], v[28:29], v[28:29], v[68:69]
	v_pk_fma_f32 v[66:67], v[30:31], v[30:31], v[66:67]
	v_pk_fma_f32 v[68:69], v[32:33], v[32:33], v[68:69]
	v_pk_add_f32 v[66:67], v[66:67], v[68:69]
	v_add_f32_e32 v66, v66, v67
	s_nop 1
	v_add_f32_dpp v66, v66, v66 row_shr:1 row_mask:0xf bank_mask:0xf bound_ctrl:1
	s_nop 1
	v_add_f32_dpp v66, v66, v66 row_shr:2 row_mask:0xf bank_mask:0xf bound_ctrl:1
	s_nop 1
	v_add_f32_dpp v66, v66, v66 row_shr:4 row_mask:0xf bank_mask:0xf bound_ctrl:1
	s_nop 1
	v_add_f32_dpp v66, v66, v66 row_shr:8 row_mask:0xf bank_mask:0xf bound_ctrl:1
	s_nop 0
	v_readlane_b32 s9, v66, 15
	v_readlane_b32 s10, v66, 31
	v_readlane_b32 s11, v66, 47
	v_readlane_b32 vcc_lo, v66, 63
	s_nop 1
	v_mov_b32_e32 v66, s9
	v_add_f32_e32 v66, s10, v66
	v_add_f32_e32 v66, s11, v66
	v_add_f32_e32 v66, vcc_lo, v66
	v_mul_f32_e32 v66, 0x3a800000, v66
	v_add_f32_e32 v66, 0x3727c5ac, v66
	v_rsq_f32_e32 v118, v66
	s_nop 0
	v_mov_b32_e32 v119, v118
	v_pk_mul_f32 v[18:19], v[18:19], v[118:119]
	v_pk_mul_f32 v[20:21], v[20:21], v[118:119]
	v_pk_mul_f32 v[22:23], v[22:23], v[118:119]
	v_pk_mul_f32 v[24:25], v[24:25], v[118:119]
	v_pk_mul_f32 v[26:27], v[26:27], v[118:119]
	v_pk_mul_f32 v[28:29], v[28:29], v[118:119]
	v_pk_mul_f32 v[30:31], v[30:31], v[118:119]
	v_pk_mul_f32 v[32:33], v[32:33], v[118:119]
	v_pk_fma_f32 v[76:77], v[18:19], v[34:35], v[50:51]
	v_pk_fma_f32 v[78:79], v[20:21], v[36:37], v[52:53]
	v_pk_fma_f32 v[80:81], v[22:23], v[38:39], v[54:55]
	v_pk_fma_f32 v[82:83], v[24:25], v[40:41], v[56:57]
	v_pk_fma_f32 v[84:85], v[26:27], v[42:43], v[58:59]
	v_pk_fma_f32 v[86:87], v[28:29], v[44:45], v[60:61]
	v_pk_fma_f32 v[88:89], v[30:31], v[46:47], v[62:63]
	v_pk_fma_f32 v[90:91], v[32:33], v[48:49], v[64:65]
	s_cmp_lg_u32 s8, 0
	s_cbranch_scc1 .Lln2_f32_4
	v_cvt_pk_bf16_f32 v92, v76, v77
	v_cvt_pk_bf16_f32 v93, v78, v79
	v_cvt_pk_bf16_f32 v94, v80, v81
	v_cvt_pk_bf16_f32 v95, v82, v83
	v_cvt_pk_bf16_f32 v96, v84, v85
	v_cvt_pk_bf16_f32 v97, v86, v87
	v_cvt_pk_bf16_f32 v98, v88, v89
	v_cvt_pk_bf16_f32 v99, v90, v91
	global_store_dwordx2 v115, v[92:93], s[2:3] offset:0 sc1
	global_store_dwordx2 v115, v[94:95], s[2:3] offset:512 sc1
	global_store_dwordx2 v115, v[96:97], s[2:3] offset:1024 sc1
	global_store_dwordx2 v115, v[98:99], s[2:3] offset:1536 sc1
	s_branch .Lln2_st_4

; __device__ __forceinline__ void phase_ln(float* R, const float* __restrict__ g, const float* __restrict__ b, bf16_t* xbf, float samp_scale, const float* __restrict__ part, int nsplit, bool f32_all) {
;     ...
;   for (int r = gw; r < MT; r += nw) {
;     float* row = R + (size_t)r * 1024;
;     f32x4 v[4];
; #pragma unroll
;     for (int i = 0; i < 4; ++i) v[i] = *(const f32x4*)(row + i * 256 + lane * 4);
;     if (r >= MP) {
;       for (int sp = 0; sp < nsplit; ++sp) {
;         const float* prow = part + ((size_t)sp * MS + (r - MP)) * 1024;
; #pragma unroll
;         for (int i = 0; i < 4; ++i) v[i] = v[i] + *(const f32x4*)(prow + i * 256 + lane * 4);
;       }
;     }
;     float s = 0.f;
; #pragma unroll
;     for (int i = 0; i < 4; ++i) s += v[i][0] + v[i][1] + v[i][2] + v[i][3];
; #pragma unroll
;     for (int o = 32; o >= 1; o >>= 1) s += __shfl_xor(s, o);
;     const float mean = s * (1.f / 1024.f);
;     float ss = 0.f;
; #pragma unroll
;     for (int i = 0; i < 4; ++i) { v[i] = v[i] - mean; ss += v[i][0] * v[i][0] + v[i][1] * v[i][1] + v[i][2] * v[i][2] + v[i][3] * v[i][3]; }
; #pragma unroll
;     for (int o = 32; o >= 1; o >>= 1) ss += __shfl_xor(ss, o);
;     const float rstd = rsqrtf(ss * (1.f / 1024.f) + LN_EPS);
; #pragma unroll
;     for (int i = 0; i < 4; ++i) {
;       const f32x4 y = v[i] * rstd * gv[i] + bv[i];
;       if (r >= MP) *(f32x4*)(row + i * 256 + lane * 4) = y * samp_scale;
;       else if (f32_all) *(f32x4*)(row + i * 256 + lane * 4) = y;
;       if (xbf) {
;         u32x2 wv;
;         wv[0] = cvt_pk_bf16(y[0], y[1]); wv[1] = cvt_pk_bf16(y[2], y[3]);
;         *(u32x2*)(xbf + (size_t)r * 1024 + i * 256 + lane * 4) = wv;
;       }
;     }
.Lln2_st_13:
	s_add_u32 s2, s2, 0x400000
	s_addc_u32 s3, s3, 0
	s_waitcnt vmcnt(12)
	v_pk_add_f32 v[66:67], v[122:123], v[124:125]
	v_pk_add_f32 v[68:69], v[126:127], v[128:129]
	v_pk_add_f32 v[70:71], v[130:131], v[132:133]
	v_pk_add_f32 v[72:73], v[134:135], v[136:137]
	v_pk_add_f32 v[66:67], v[66:67], v[68:69]
	v_pk_add_f32 v[70:71], v[70:71], v[72:73]
	v_pk_add_f32 v[66:67], v[66:67], v[70:71]
	v_add_f32_e32 v66, v66, v67
	s_nop 1
	v_add_f32_dpp v66, v66, v66 row_shr:1 row_mask:0xf bank_mask:0xf bound_ctrl:1
	s_nop 1
	v_add_f32_dpp v66, v66, v66 row_shr:2 row_mask:0xf bank_mask:0xf bound_ctrl:1
	s_nop 1
	v_add_f32_dpp v66, v66, v66 row_shr:4 row_mask:0xf bank_mask:0xf bound_ctrl:1
	s_nop 1
	v_add_f32_dpp v66, v66, v66 row_shr:8 row_mask:0xf bank_mask:0xf bound_ctrl:1
	s_nop 0
	v_readlane_b32 s9, v66, 15
	v_readlane_b32 s10, v66, 31
	v_readlane_b32 s11, v66, 47
	v_readlane_b32 vcc_lo, v66, 63
	s_nop 1
	v_mov_b32_e32 v66, s9
	v_add_f32_e32 v66, s10, v66
	v_add_f32_e32 v66, s11, v66
	v_add_f32_e32 v66, vcc_lo, v66
	v_mul_f32_e32 v116, 0x3a800000, v66
	v_mov_b32_e32 v117, v116
	v_pk_add_f32 v[122:123], v[122:123], v[116:117] neg_lo:[0,1] neg_hi:[0,1]
	v_pk_add_f32 v[124:125], v[124:125], v[116:117] neg_lo:[0,1] neg_hi:[0,1]
	v_pk_add_f32 v[126:127], v[126:127], v[116:117] neg_lo:[0,1] neg_hi:[0,1]
	v_pk_add_f32 v[128:129], v[128:129], v[116:117] neg_lo:[0,1] neg_hi:[0,1]
	v_pk_add_f32 v[130:131], v[130:131], v[116:117] neg_lo:[0,1] neg_hi:[0,1]
	v_pk_add_f32 v[132:133], v[132:133], v[116:117] neg_lo:[0,1] neg_hi:[0,1]
	v_pk_add_f32 v[134:135], v[134:135], v[116:117] neg_lo:[0,1] neg_hi:[0,1]
	v_pk_add_f32 v[136:137], v[136:137], v[116:117] neg_lo:[0,1] neg_hi:[0,1]
	v_pk_mul_f32 v[66:67], v[122:123], v[122:123]
	v_pk_mul_f32 v[68:69], v[124:125], v[124:125]
	v_pk_fma_f32 v[66:67], v[126:127], v[126:127], v[66:67]
	v_pk_fma_f32 v[68:69], v[128:129], v[128:129], v[68:69]
	v_pk_fma_f32 v[66:67], v[130:131], v[130:131], v[66:67]
	v_pk_fma_f32 v[68:69], v[132:133], v[132:133], v[68:69]
	v_pk_fma_f32 v[66:67], v[134:135], v[134:135], v[66:67]
	v_pk_fma_f32 v[68:69], v[136:137], v[136:137], v[68:69]
	v_pk_add_f32 v[66:67], v[66:67], v[68:69]
	v_add_f32_e32 v66, v66, v67
	s_nop 1
	v_add_f32_dpp v66, v66, v66 row_shr:1 row_mask:0xf bank_mask:0xf bound_ctrl:1
	s_nop 1
	v_add_f32_dpp v66, v66, v66 row_shr:2 row_mask:0xf bank_mask:0xf bound_ctrl:1
	s_nop 1
	v_add_f32_dpp v66, v66, v66 row_shr:4 row_mask:0xf bank_mask:0xf bound_ctrl:1
	s_nop 1
	v_add_f32_dpp v66, v66, v66 row_shr:8 row_mask:0xf bank_mask:0xf bound_ctrl:1
	s_nop 0
	v_readlane_b32 s9, v66, 15
	v_readlane_b32 s10, v66, 31
	v_readlane_b32 s11, v66, 47
	v_readlane_b32 vcc_lo, v66, 63
	s_nop 1
	v_mov_b32_e32 v66, s9
	v_add_f32_e32 v66, s10, v66
	v_add_f32_e32 v66, s11, v66
	v_add_f32_e32 v66, vcc_lo, v66
	v_mul_f32_e32 v66, 0x3a800000, v66
	v_add_f32_e32 v66, 0x3727c5ac, v66
	v_rsq_f32_e32 v118, v66
	s_nop 0
	v_mov_b32_e32 v119, v118
	v_pk_mul_f32 v[122:123], v[122:123], v[118:119]
	v_pk_mul_f32 v[124:125], v[124:125], v[118:119]
	v_pk_mul_f32 v[126:127], v[126:127], v[118:119]
	v_pk_mul_f32 v[128:129], v[128:129], v[118:119]
	v_pk_mul_f32 v[130:131], v[130:131], v[118:119]
	v_pk_mul_f32 v[132:133], v[132:133], v[118:119]
	v_pk_mul_f32 v[134:135], v[134:135], v[118:119]
	v_pk_mul_f32 v[136:137], v[136:137], v[118:119]
	v_pk_fma_f32 v[76:77], v[122:123], v[34:35], v[50:51]
	v_pk_fma_f32 v[78:79], v[124:125], v[36:37], v[52:53]
	v_pk_fma_f32 v[80:81], v[126:127], v[38:39], v[54:55]
	v_pk_fma_f32 v[82:83], v[128:129], v[40:41], v[56:57]
	v_pk_fma_f32 v[84:85], v[130:131], v[42:43], v[58:59]
	v_pk_fma_f32 v[86:87], v[132:133], v[44:45], v[60:61]
	v_pk_fma_f32 v[88:89], v[134:135], v[46:47], v[62:63]
	v_pk_fma_f32 v[90:91], v[136:137], v[48:49], v[64:65]
	s_cmp_lg_u32 s8, 0
	s_cbranch_scc1 .Lln2_f32_14
	v_cvt_pk_bf16_f32 v92, v76, v77
	v_cvt_pk_bf16_f32 v93, v78, v79
	v_cvt_pk_bf16_f32 v94, v80, v81
	v_cvt_pk_bf16_f32 v95, v82, v83
	v_cvt_pk_bf16_f32 v96, v84, v85
	v_cvt_pk_bf16_f32 v97, v86, v87
	v_cvt_pk_bf16_f32 v98, v88, v89
	v_cvt_pk_bf16_f32 v99, v90, v91
	global_store_dwordx2 v115, v[92:93], s[2:3] offset:0 sc1
	global_store_dwordx2 v115, v[94:95], s[2:3] offset:512 sc1
	global_store_dwordx2 v115, v[96:97], s[2:3] offset:1024 sc1
	global_store_dwordx2 v115, v[98:99], s[2:3] offset:1536 sc1
	s_branch .Lln2_st_14

; __device__ __forceinline__ void phase_ln(float* R, const float* __restrict__ g, const float* __restrict__ b, bf16_t* xbf, float samp_scale, const float* __restrict__ part, int nsplit, bool f32_all) {
;     ...
;   for (int r = gw; r < MT; r += nw) {
;     float* row = R + (size_t)r * 1024;
;     f32x4 v[4];
; #pragma unroll
;     for (int i = 0; i < 4; ++i) v[i] = *(const f32x4*)(row + i * 256 + lane * 4);
;     if (r >= MP) {
;       for (int sp = 0; sp < nsplit; ++sp) {
;         const float* prow = part + ((size_t)sp * MS + (r - MP)) * 1024;
; #pragma unroll
;         for (int i = 0; i < 4; ++i) v[i] = v[i] + *(const f32x4*)(prow + i * 256 + lane * 4);
;       }
;     }
;     float s = 0.f;
; #pragma unroll
;     for (int i = 0; i < 4; ++i) s += v[i][0] + v[i][1] + v[i][2] + v[i][3];
; #pragma unroll
;     for (int o = 32; o >= 1; o >>= 1) s += __shfl_xor(s, o);
;     const float mean = s * (1.f / 1024.f);
;     float ss = 0.f;
; #pragma unroll
;     for (int i = 0; i < 4; ++i) { v[i] = v[i] - mean; ss += v[i][0] * v[i][0] + v[i][1] * v[i][1] + v[i][2] * v[i][2] + v[i][3] * v[i][3]; }
; #pragma unroll
;     for (int o = 32; o >= 1; o >>= 1) ss += __shfl_xor(ss, o);
;     const float rstd = rsqrtf(ss * (1.f / 1024.f) + LN_EPS);
; #pragma unroll
;     for (int i = 0; i < 4; ++i) {
;       const f32x4 y = v[i] * rstd * gv[i] + bv[i];
;       if (r >= MP) *(f32x4*)(row + i * 256 + lane * 4) = y * samp_scale;
;       else if (f32_all) *(f32x4*)(row + i * 256 + lane * 4) = y;
;       if (xbf) {
;         u32x2 wv;
;         wv[0] = cvt_pk_bf16(y[0], y[1]); wv[1] = cvt_pk_bf16(y[2], y[3]);
;         *(u32x2*)(xbf + (size_t)r * 1024 + i * 256 + lane * 4) = wv;
;       }
;     }
.Lln2_st_14:
	s_add_u32 s2, s2, 0x400000
	s_addc_u32 s3, s3, 0
	s_waitcnt vmcnt(8)
	v_pk_add_f32 v[66:67], v[0:1], v[2:3]
	v_pk_add_f32 v[68:69], v[4:5], v[6:7]
	v_pk_add_f32 v[70:71], v[8:9], v[10:11]
	v_pk_add_f32 v[72:73], v[12:13], v[14:15]
	v_pk_add_f32 v[66:67], v[66:67], v[68:69]
	v_pk_add_f32 v[70:71], v[70:71], v[72:73]
	v_pk_add_f32 v[66:67], v[66:67], v[70:71]
	v_add_f32_e32 v66, v66, v67
	s_nop 1
	v_add_f32_dpp v66, v66, v66 row_shr:1 row_mask:0xf bank_mask:0xf bound_ctrl:1
	s_nop 1
	v_add_f32_dpp v66, v66, v66 row_shr:2 row_mask:0xf bank_mask:0xf bound_ctrl:1
	s_nop 1
	v_add_f32_dpp v66, v66, v66 row_shr:4 row_mask:0xf bank_mask:0xf bound_ctrl:1
	s_nop 1
	v_add_f32_dpp v66, v66, v66 row_shr:8 row_mask:0xf bank_mask:0xf bound_ctrl:1
	s_nop 0
	v_readlane_b32 s9, v66, 15
	v_readlane_b32 s10, v66, 31
	v_readlane_b32 s11, v66, 47
	v_readlane_b32 vcc_lo, v66, 63
	s_nop 1
	v_mov_b32_e32 v66, s9
	v_add_f32_e32 v66, s10, v66
	v_add_f32_e32 v66, s11, v66
	v_add_f32_e32 v66, vcc_lo, v66
	v_mul_f32_e32 v116, 0x3a800000, v66
	v_mov_b32_e32 v117, v116
	v_pk_add_f32 v[0:1], v[0:1], v[116:117] neg_lo:[0,1] neg_hi:[0,1]
	v_pk_add_f32 v[2:3], v[2:3], v[116:117] neg_lo:[0,1] neg_hi:[0,1]
	v_pk_add_f32 v[4:5], v[4:5], v[116:117] neg_lo:[0,1] neg_hi:[0,1]
	v_pk_add_f32 v[6:7], v[6:7], v[116:117] neg_lo:[0,1] neg_hi:[0,1]
	v_pk_add_f32 v[8:9], v[8:9], v[116:117] neg_lo:[0,1] neg_hi:[0,1]
	v_pk_add_f32 v[10:11], v[10:11], v[116:117] neg_lo:[0,1] neg_hi:[0,1]
	v_pk_add_f32 v[12:13], v[12:13], v[116:117] neg_lo:[0,1] neg_hi:[0,1]
	v_pk_add_f32 v[14:15], v[14:15], v[116:117] neg_lo:[0,1] neg_hi:[0,1]
	v_pk_mul_f32 v[66:67], v[0:1], v[0:1]
	v_pk_mul_f32 v[68:69], v[2:3], v[2:3]
	v_pk_fma_f32 v[66:67], v[4:5], v[4:5], v[66:67]
	v_pk_fma_f32 v[68:69], v[6:7], v[6:7], v[68:69]
	v_pk_fma_f32 v[66:67], v[8:9], v[8:9], v[66:67]
	v_pk_fma_f32 v[68:69], v[10:11], v[10:11], v[68:69]
	v_pk_fma_f32 v[66:67], v[12:13], v[12:13], v[66:67]
	v_pk_fma_f32 v[68:69], v[14:15], v[14:15], v[68:69]
	v_pk_add_f32 v[66:67], v[66:67], v[68:69]
	v_add_f32_e32 v66, v66, v67
	s_nop 1
	v_add_f32_dpp v66, v66, v66 row_shr:1 row_mask:0xf bank_mask:0xf bound_ctrl:1
	s_nop 1
	v_add_f32_dpp v66, v66, v66 row_shr:2 row_mask:0xf bank_mask:0xf bound_ctrl:1
	s_nop 1
	v_add_f32_dpp v66, v66, v66 row_shr:4 row_mask:0xf bank_mask:0xf bound_ctrl:1
	s_nop 1
	v_add_f32_dpp v66, v66, v66 row_shr:8 row_mask:0xf bank_mask:0xf bound_ctrl:1
	s_nop 0
	v_readlane_b32 s9, v66, 15
	v_readlane_b32 s10, v66, 31
	v_readlane_b32 s11, v66, 47
	v_readlane_b32 vcc_lo, v66, 63
	s_nop 1
	v_mov_b32_e32 v66, s9
	v_add_f32_e32 v66, s10, v66
	v_add_f32_e32 v66, s11, v66
	v_add_f32_e32 v66, vcc_lo, v66
	v_mul_f32_e32 v66, 0x3a800000, v66
	v_add_f32_e32 v66, 0x3727c5ac, v66
	v_rsq_f32_e32 v118, v66
	s_nop 0
	v_mov_b32_e32 v119, v118
	v_pk_mul_f32 v[0:1], v[0:1], v[118:119]
	v_pk_mul_f32 v[2:3], v[2:3], v[118:119]
	v_pk_mul_f32 v[4:5], v[4:5], v[118:119]
	v_pk_mul_f32 v[6:7], v[6:7], v[118:119]
	v_pk_mul_f32 v[8:9], v[8:9], v[118:119]
	v_pk_mul_f32 v[10:11], v[10:11], v[118:119]
	v_pk_mul_f32 v[12:13], v[12:13], v[118:119]
	v_pk_mul_f32 v[14:15], v[14:15], v[118:119]
	v_pk_fma_f32 v[76:77], v[0:1], v[34:35], v[50:51]
	v_pk_fma_f32 v[78:79], v[2:3], v[36:37], v[52:53]
	v_pk_fma_f32 v[80:81], v[4:5], v[38:39], v[54:55]
	v_pk_fma_f32 v[82:83], v[6:7], v[40:41], v[56:57]
	v_pk_fma_f32 v[84:85], v[8:9], v[42:43], v[58:59]
	v_pk_fma_f32 v[86:87], v[10:11], v[44:45], v[60:61]
	v_pk_fma_f32 v[88:89], v[12:13], v[46:47], v[62:63]
	v_pk_fma_f32 v[90:91], v[14:15], v[48:49], v[64:65]
	s_cmp_lg_u32 s8, 0
	s_cbranch_scc1 .Lln2_f32_15
	v_cvt_pk_bf16_f32 v92, v76, v77
	v_cvt_pk_bf16_f32 v93, v78, v79
	v_cvt_pk_bf16_f32 v94, v80, v81
	v_cvt_pk_bf16_f32 v95, v82, v83
	v_cvt_pk_bf16_f32 v96, v84, v85
	v_cvt_pk_bf16_f32 v97, v86, v87
	v_cvt_pk_bf16_f32 v98, v88, v89
	v_cvt_pk_bf16_f32 v99, v90, v91
	global_store_dwordx2 v115, v[92:93], s[2:3] offset:0 sc1
	global_store_dwordx2 v115, v[94:95], s[2:3] offset:512 sc1
	global_store_dwordx2 v115, v[96:97], s[2:3] offset:1024 sc1
	global_store_dwordx2 v115, v[98:99], s[2:3] offset:1536 sc1
	s_branch .Lln2_st_15
